# GEMM K-loops (12 of 13): the last two LDS-DMA loads of each SP2 load segment are issued at the start of the next load segment (4+4 instead of 6+2), SP2 wait vmcnt(6)
# speedup vs baseline: 1.0086x; 1.0084x over previous
; #define PG8_STAGE(bufoff, gbase, voff) do { _Pragma("unroll") for (int _i = 0; _i < 2; ++_i) \
;         __builtin_amdgcn_global_load_lds((const unsigned*)((const char*)(gbase) + (voff)[_i]), (PG8_LAS unsigned*)(lds + (bufoff) + ldsw + _i * 8192), 16, 0, 0); } while (0)
; #define PG8_LDA(dst, b, h) do { _Pragma("unroll") for (int m = 0; m < 4; ++m) _Pragma("unroll") for (int k = 0; k < 2; ++k) dst[m][k] = *(const PG8_LAS bf16x8*)(lds + PG8_SA(b, h) + aoff + m * 2048 + k * 1024); } while (0)
; #define PG8_LDB(dst, b, h) do { _Pragma("unroll") for (int n = 0; n < 2; ++n) _Pragma("unroll") for (int k = 0; k < 2; ++k) dst[n][k] = *(const PG8_LAS bf16x8*)(lds + PG8_SB(b, h) + boff + n * 2048 + k * 1024); } while (0)
; #define PG8_MMA(ai, bj, At, Bt) do { __builtin_amdgcn_s_setprio(1); _Pragma("unroll") for (int m = 0; m < 4; ++m) _Pragma("unroll") for (int n = 0; n < 2; ++n) _Pragma("unroll") for (int k = 0; k < 2; ++k) \
;         acc[ai][bj][m][n] = __builtin_amdgcn_mfma_f32_16x16x32_bf16(Bt[n][k], At[m][k], acc[ai][bj][m][n], 0, 0, 0); __builtin_amdgcn_s_setprio(0); } while (0)
; #define PG8_WAIT_V(n) asm volatile("s_waitcnt vmcnt(" #n ")" ::: "memory")
; #define PG8_WAIT_L(n) asm volatile("s_waitcnt lgkmcnt(" #n ")" ::: "memory")
; #define PG8_BAR __builtin_amdgcn_s_barrier()
; #define PG8_SCHED __builtin_amdgcn_sched_barrier(0)
; template <class Epi, class Sched, bool ALIGN_EPI = false, bool SP2 = false>
; __device__ __forceinline__ void gemm_phase(PG8_LAS unsigned char* lds, const Gemm g, const Sched& S, const Epi& E) {
;     ...
;         for (int t = 0; t < nt; t += 2) {
;             const bool last = (t == nt - 2);
;             const char* a1 = cA + (size_t)(t + 1) * kstep;
;             const char* a2 = last ? nA : cA + (size_t)(t + 2) * kstep; const char* b2 = last ? nB : cB + (size_t)(t + 2) * kstep;
;             const char* a3 = a2 + kstep; const char* b3 = b2 + kstep;
;             if (last && has_next) S.a_ready(nxt);
;             if constexpr (SP2) {
;             PG8_LDB(B0, 0, 0); PG8_LDB(B1, 0, 1); PG8_SCHED; PG8_LDA(At, 0, 0); PG8_STAGE(PG8_SA(1, 1), a1 + hstepA, voffA);
;             PG8_WAIT_V(8); PG8_WAIT_L(0); PG8_BAR; PG8_MMA(0, 0, At, B0); PG8_MMA(0, 1, At, B1); PG8_BAR; PG8_SCHED;
;             PG8_LDA(At, 0, 1); PG8_STAGE(PG8_SB(0, 0), b2, voffB); PG8_STAGE(PG8_SB(0, 1), b2 + hstepB, voffB); PG8_STAGE(PG8_SA(0, 0), a2, voffA);
.LBB0_210:
	ds_read_b128 v[146:149], v155
	ds_read_b128 v[158:161], v155 offset:1024
	ds_read_b128 v[162:165], v155 offset:2048
	ds_read_b128 v[166:169], v155 offset:3072
	ds_read_b128 v[170:173], v156
	ds_read_b128 v[174:177], v156 offset:1024
	ds_read_b128 v[178:181], v156 offset:2048
	ds_read_b128 v[182:185], v156 offset:3072
	s_add_u32 s26, s24, 0xfff00080
	s_addc_u32 s27, s25, -1
	s_cmp_eq_u32 s53, 60
	s_cselect_b32 s29, s17, s27
	s_cselect_b32 s28, s49, s26
	s_cselect_b32 s27, s15, s52
	s_cselect_b32 s26, s50, s51
	v_lshl_add_u64 v[214:215], s[24:25], 0, v[138:139]
	s_add_i32 m0, s23, 0xc000
	ds_read_b128 v[186:189], v157
	ds_read_b128 v[190:193], v157 offset:1024
	ds_read_b128 v[194:197], v157 offset:2048
	ds_read_b128 v[198:201], v157 offset:3072
	ds_read_b128 v[202:205], v157 offset:4096
	ds_read_b128 v[206:209], v157 offset:5120
	ds_read_b128 v[210:213], v157 offset:6144
	ds_read_b128 v[218:221], v157 offset:7168
	global_load_lds_dwordx4 v[214:215], off
	v_lshl_add_u64 v[214:215], s[24:25], 0, v[140:141]
	s_add_i32 m0, s23, 0xe000
	s_nop 0
	global_load_lds_dwordx4 v[214:215], off
	s_waitcnt vmcnt(8)
	s_waitcnt lgkmcnt(0)
	s_barrier
	s_setprio 1
	s_waitcnt lgkmcnt(0)
	v_mfma_f32_16x16x32_bf16 v[126:129], v[146:149], v[186:189], v[126:129]
	v_mfma_f32_16x16x32_bf16 v[122:125], v[162:165], v[186:189], v[122:125]
	v_mfma_f32_16x16x32_bf16 v[118:121], v[146:149], v[194:197], v[118:121]
	v_mfma_f32_16x16x32_bf16 v[114:117], v[162:165], v[194:197], v[114:117]
	v_mfma_f32_16x16x32_bf16 v[106:109], v[146:149], v[202:205], v[106:109]
	v_mfma_f32_16x16x32_bf16 v[98:101], v[162:165], v[202:205], v[98:101]
	v_mfma_f32_16x16x32_bf16 v[78:81], v[146:149], v[210:213], v[78:81]
	v_mfma_f32_16x16x32_bf16 v[74:77], v[162:165], v[210:213], v[74:77]
	v_mfma_f32_16x16x32_bf16 v[126:129], v[158:161], v[190:193], v[126:129]
	v_mfma_f32_16x16x32_bf16 v[122:125], v[166:169], v[190:193], v[122:125]
	v_mfma_f32_16x16x32_bf16 v[118:121], v[158:161], v[198:201], v[118:121]
	v_mfma_f32_16x16x32_bf16 v[114:117], v[166:169], v[198:201], v[114:117]
	v_mfma_f32_16x16x32_bf16 v[106:109], v[158:161], v[206:209], v[106:109]
	v_mfma_f32_16x16x32_bf16 v[98:101], v[166:169], v[206:209], v[98:101]
	v_mfma_f32_16x16x32_bf16 v[78:81], v[158:161], v[218:221], v[78:81]
	v_mfma_f32_16x16x32_bf16 v[74:77], v[166:169], v[218:221], v[74:77]
	s_setprio 0
	s_setprio 1
	v_mfma_f32_16x16x32_bf16 v[110:113], v[170:173], v[186:189], v[110:113]
	v_mfma_f32_16x16x32_bf16 v[102:105], v[178:181], v[186:189], v[102:105]
	v_mfma_f32_16x16x32_bf16 v[94:97], v[170:173], v[194:197], v[94:97]
	v_mfma_f32_16x16x32_bf16 v[90:93], v[178:181], v[194:197], v[90:93]
	v_mfma_f32_16x16x32_bf16 v[86:89], v[170:173], v[202:205], v[86:89]
	v_mfma_f32_16x16x32_bf16 v[82:85], v[178:181], v[202:205], v[82:85]
	v_mfma_f32_16x16x32_bf16 v[70:73], v[170:173], v[210:213], v[70:73]
	v_mfma_f32_16x16x32_bf16 v[66:69], v[178:181], v[210:213], v[66:69]
	v_mfma_f32_16x16x32_bf16 v[110:113], v[174:177], v[190:193], v[110:113]
	v_mfma_f32_16x16x32_bf16 v[102:105], v[182:185], v[190:193], v[102:105]
	v_mfma_f32_16x16x32_bf16 v[94:97], v[174:177], v[198:201], v[94:97]
	v_mfma_f32_16x16x32_bf16 v[90:93], v[182:185], v[198:201], v[90:93]
	v_mfma_f32_16x16x32_bf16 v[86:89], v[174:177], v[206:209], v[86:89]
	v_mfma_f32_16x16x32_bf16 v[82:85], v[182:185], v[206:209], v[82:85]
	v_mfma_f32_16x16x32_bf16 v[70:73], v[174:177], v[218:221], v[70:73]
	v_mfma_f32_16x16x32_bf16 v[66:69], v[182:185], v[218:221], v[66:69]
	s_setprio 0
	s_barrier
	s_add_i32 s54, s45, s35
	v_lshl_add_u64 v[214:215], s[26:27], 0, v[134:135]
	s_mov_b32 m0, s54
	ds_read_b128 v[186:189], v157 offset:16384
	ds_read_b128 v[190:193], v157 offset:17408
	ds_read_b128 v[194:197], v157 offset:18432
	ds_read_b128 v[198:201], v157 offset:19456
	ds_read_b128 v[202:205], v157 offset:20480
	ds_read_b128 v[206:209], v157 offset:21504
	ds_read_b128 v[210:213], v157 offset:22528
	ds_read_b128 v[218:221], v157 offset:23552
	global_load_lds_dwordx4 v[214:215], off
	s_add_i32 m0, s54, 0x2000
	s_add_u32 s54, s26, 0x100000
	v_lshl_add_u64 v[222:223], s[26:27], 0, v[130:131]
	s_addc_u32 s55, s27, 0
	s_add_i32 s56, s46, s35
	global_load_lds_dwordx4 v[222:223], off
	v_lshl_add_u64 v[224:225], s[54:55], 0, v[134:135]
	s_mov_b32 m0, s56
	v_lshl_add_u64 v[226:227], s[28:29], 0, v[132:133]
	global_load_lds_dwordx4 v[224:225], off
	v_lshl_add_u64 v[224:225], s[54:55], 0, v[130:131]
	s_add_i32 m0, s56, 0x2000
	s_nop 0
	global_load_lds_dwordx4 v[224:225], off
	v_lshl_add_u64 v[224:225], s[28:29], 0, v[136:137]
	s_waitcnt vmcnt(6)
	s_waitcnt lgkmcnt(0)
	s_barrier
; #define PG8_STAGE(bufoff, gbase, voff) do { _Pragma("unroll") for (int _i = 0; _i < 2; ++_i) \
;         __builtin_amdgcn_global_load_lds((const unsigned*)((const char*)(gbase) + (voff)[_i]), (PG8_LAS unsigned*)(lds + (bufoff) + ldsw + _i * 8192), 16, 0, 0); } while (0)
; #define PG8_LDA(dst, b, h) do { _Pragma("unroll") for (int m = 0; m < 4; ++m) _Pragma("unroll") for (int k = 0; k < 2; ++k) dst[m][k] = *(const PG8_LAS bf16x8*)(lds + PG8_SA(b, h) + aoff + m * 2048 + k * 1024); } while (0)
; #define PG8_LDB(dst, b, h) do { _Pragma("unroll") for (int n = 0; n < 2; ++n) _Pragma("unroll") for (int k = 0; k < 2; ++k) dst[n][k] = *(const PG8_LAS bf16x8*)(lds + PG8_SB(b, h) + boff + n * 2048 + k * 1024); } while (0)
; #define PG8_MMA(ai, bj, At, Bt) do { __builtin_amdgcn_s_setprio(1); _Pragma("unroll") for (int m = 0; m < 4; ++m) _Pragma("unroll") for (int n = 0; n < 2; ++n) _Pragma("unroll") for (int k = 0; k < 2; ++k) \
;         acc[ai][bj][m][n] = __builtin_amdgcn_mfma_f32_16x16x32_bf16(Bt[n][k], At[m][k], acc[ai][bj][m][n], 0, 0, 0); __builtin_amdgcn_s_setprio(0); } while (0)
; #define PG8_WAIT_V(n) asm volatile("s_waitcnt vmcnt(" #n ")" ::: "memory")
; #define PG8_WAIT_L(n) asm volatile("s_waitcnt lgkmcnt(" #n ")" ::: "memory")
; #define PG8_BAR __builtin_amdgcn_s_barrier()
; #define PG8_SCHED __builtin_amdgcn_sched_barrier(0)
; template <class Epi, class Sched, bool ALIGN_EPI = false, bool SP2 = false>
; __device__ __forceinline__ void gemm_phase(PG8_LAS unsigned char* lds, const Gemm g, const Sched& S, const Epi& E) {
;     ...
;             PG8_WAIT_V(8); PG8_WAIT_L(0); PG8_BAR; PG8_MMA(1, 0, At, B0); PG8_MMA(1, 1, At, B1); PG8_BAR; PG8_SCHED;
;             PG8_LDB(B0, 1, 0); PG8_LDB(B1, 1, 1); PG8_SCHED; PG8_LDA(At, 1, 0); PG8_STAGE(PG8_SA(0, 1), a2 + hstepA, voffA);
;             PG8_WAIT_V(8); PG8_WAIT_L(0); PG8_BAR; PG8_MMA(0, 0, At, B0); PG8_MMA(0, 1, At, B1); PG8_BAR; PG8_SCHED;
;             PG8_LDA(At, 1, 1); PG8_STAGE(PG8_SB(1, 0), b3, voffB); PG8_STAGE(PG8_SB(1, 1), b3 + hstepB, voffB); PG8_STAGE(PG8_SA(1, 0), a3, voffA);
	s_setprio 1
	s_waitcnt lgkmcnt(0)
	v_mfma_f32_16x16x32_bf16 v[62:65], v[146:149], v[186:189], v[62:65]
	v_mfma_f32_16x16x32_bf16 v[58:61], v[162:165], v[186:189], v[58:61]
	v_mfma_f32_16x16x32_bf16 v[50:53], v[146:149], v[194:197], v[50:53]
	v_mfma_f32_16x16x32_bf16 v[42:45], v[162:165], v[194:197], v[42:45]
	v_mfma_f32_16x16x32_bf16 v[34:37], v[146:149], v[202:205], v[34:37]
	v_mfma_f32_16x16x32_bf16 v[26:29], v[162:165], v[202:205], v[26:29]
	v_mfma_f32_16x16x32_bf16 v[18:21], v[146:149], v[210:213], v[18:21]
	v_mfma_f32_16x16x32_bf16 v[10:13], v[162:165], v[210:213], v[10:13]
	v_mfma_f32_16x16x32_bf16 v[62:65], v[158:161], v[190:193], v[62:65]
	v_mfma_f32_16x16x32_bf16 v[58:61], v[166:169], v[190:193], v[58:61]
	v_mfma_f32_16x16x32_bf16 v[50:53], v[158:161], v[198:201], v[50:53]
	v_mfma_f32_16x16x32_bf16 v[42:45], v[166:169], v[198:201], v[42:45]
	v_mfma_f32_16x16x32_bf16 v[34:37], v[158:161], v[206:209], v[34:37]
	v_mfma_f32_16x16x32_bf16 v[26:29], v[166:169], v[206:209], v[26:29]
	v_mfma_f32_16x16x32_bf16 v[18:21], v[158:161], v[218:221], v[18:21]
	v_mfma_f32_16x16x32_bf16 v[10:13], v[166:169], v[218:221], v[10:13]
	s_setprio 0
	s_setprio 1
	v_mfma_f32_16x16x32_bf16 v[54:57], v[170:173], v[186:189], v[54:57]
	v_mfma_f32_16x16x32_bf16 v[46:49], v[178:181], v[186:189], v[46:49]
	v_mfma_f32_16x16x32_bf16 v[38:41], v[170:173], v[194:197], v[38:41]
	v_mfma_f32_16x16x32_bf16 v[30:33], v[178:181], v[194:197], v[30:33]
	v_mfma_f32_16x16x32_bf16 v[22:25], v[170:173], v[202:205], v[22:25]
	v_mfma_f32_16x16x32_bf16 v[14:17], v[178:181], v[202:205], v[14:17]
	v_mfma_f32_16x16x32_bf16 v[6:9], v[170:173], v[210:213], v[6:9]
	v_mfma_f32_16x16x32_bf16 v[2:5], v[178:181], v[210:213], v[2:5]
	v_mfma_f32_16x16x32_bf16 v[54:57], v[174:177], v[190:193], v[54:57]
	v_mfma_f32_16x16x32_bf16 v[46:49], v[182:185], v[190:193], v[46:49]
	v_mfma_f32_16x16x32_bf16 v[38:41], v[174:177], v[198:201], v[38:41]
	v_mfma_f32_16x16x32_bf16 v[30:33], v[182:185], v[198:201], v[30:33]
	v_mfma_f32_16x16x32_bf16 v[22:25], v[174:177], v[206:209], v[22:25]
	v_mfma_f32_16x16x32_bf16 v[14:17], v[182:185], v[206:209], v[14:17]
	v_mfma_f32_16x16x32_bf16 v[6:9], v[174:177], v[218:221], v[6:9]
	v_mfma_f32_16x16x32_bf16 v[2:5], v[182:185], v[218:221], v[2:5]
	s_setprio 0
	s_barrier
	s_mov_b32 m0, s23
	s_nop 0
	global_load_lds_dwordx4 v[224:225], off
	s_mov_b32 m0, s38
	s_nop 0
	global_load_lds_dwordx4 v[226:227], off
	s_add_i32 s54, 0, 0x18000
	v_add_u32_e32 v150, s54, v151
	s_add_i32 s55, 0, 0x1c000
	ds_read_b128 v[146:149], v150
	ds_read_b128 v[158:161], v150 offset:1024
	ds_read_b128 v[162:165], v150 offset:2048
	ds_read_b128 v[166:169], v150 offset:3072
	v_add_u32_e32 v150, s55, v151
	ds_read_b128 v[170:173], v150
	ds_read_b128 v[174:177], v150 offset:1024
	ds_read_b128 v[178:181], v150 offset:2048
	ds_read_b128 v[182:185], v150 offset:3072
	s_add_u32 s28, s28, 0x100000
	s_addc_u32 s29, s29, 0
	s_mov_b32 m0, s39
	v_lshl_add_u64 v[228:229], s[28:29], 0, v[136:137]
	ds_read_b128 v[186:189], v157 offset:32768
	ds_read_b128 v[190:193], v157 offset:33792
	ds_read_b128 v[194:197], v157 offset:34816
	ds_read_b128 v[198:201], v157 offset:35840
	ds_read_b128 v[202:205], v157 offset:36864
	ds_read_b128 v[206:209], v157 offset:37888
	ds_read_b128 v[210:213], v157 offset:38912
	ds_read_b128 v[218:221], v157 offset:39936
	global_load_lds_dwordx4 v[228:229], off
	v_lshl_add_u64 v[228:229], s[28:29], 0, v[132:133]
	s_mov_b32 m0, s40
	s_nop 0
	global_load_lds_dwordx4 v[228:229], off
	s_waitcnt vmcnt(8)
	s_waitcnt lgkmcnt(0)
	s_barrier
	s_setprio 1
	s_waitcnt lgkmcnt(0)
	v_mfma_f32_16x16x32_bf16 v[126:129], v[146:149], v[186:189], v[126:129]
	v_mfma_f32_16x16x32_bf16 v[122:125], v[162:165], v[186:189], v[122:125]
	v_mfma_f32_16x16x32_bf16 v[118:121], v[146:149], v[194:197], v[118:121]
	v_mfma_f32_16x16x32_bf16 v[114:117], v[162:165], v[194:197], v[114:117]
	v_mfma_f32_16x16x32_bf16 v[106:109], v[146:149], v[202:205], v[106:109]
	v_mfma_f32_16x16x32_bf16 v[98:101], v[162:165], v[202:205], v[98:101]
	v_mfma_f32_16x16x32_bf16 v[78:81], v[146:149], v[210:213], v[78:81]
	v_mfma_f32_16x16x32_bf16 v[74:77], v[162:165], v[210:213], v[74:77]
	v_mfma_f32_16x16x32_bf16 v[126:129], v[158:161], v[190:193], v[126:129]
	v_mfma_f32_16x16x32_bf16 v[122:125], v[166:169], v[190:193], v[122:125]
	v_mfma_f32_16x16x32_bf16 v[118:121], v[158:161], v[198:201], v[118:121]
	v_mfma_f32_16x16x32_bf16 v[114:117], v[166:169], v[198:201], v[114:117]
	v_mfma_f32_16x16x32_bf16 v[106:109], v[158:161], v[206:209], v[106:109]
	v_mfma_f32_16x16x32_bf16 v[98:101], v[166:169], v[206:209], v[98:101]
	v_mfma_f32_16x16x32_bf16 v[78:81], v[158:161], v[218:221], v[78:81]
	v_mfma_f32_16x16x32_bf16 v[74:77], v[166:169], v[218:221], v[74:77]
	s_setprio 0
	s_setprio 1
	v_mfma_f32_16x16x32_bf16 v[110:113], v[170:173], v[186:189], v[110:113]
	v_mfma_f32_16x16x32_bf16 v[102:105], v[178:181], v[186:189], v[102:105]
	v_mfma_f32_16x16x32_bf16 v[94:97], v[170:173], v[194:197], v[94:97]
	v_mfma_f32_16x16x32_bf16 v[90:93], v[178:181], v[194:197], v[90:93]
	v_mfma_f32_16x16x32_bf16 v[86:89], v[170:173], v[202:205], v[86:89]
	v_mfma_f32_16x16x32_bf16 v[82:85], v[178:181], v[202:205], v[82:85]
	v_mfma_f32_16x16x32_bf16 v[70:73], v[170:173], v[210:213], v[70:73]
	v_mfma_f32_16x16x32_bf16 v[66:69], v[178:181], v[210:213], v[66:69]
	v_mfma_f32_16x16x32_bf16 v[110:113], v[174:177], v[190:193], v[110:113]
	v_mfma_f32_16x16x32_bf16 v[102:105], v[182:185], v[190:193], v[102:105]
	v_mfma_f32_16x16x32_bf16 v[94:97], v[174:177], v[198:201], v[94:97]
	v_mfma_f32_16x16x32_bf16 v[90:93], v[182:185], v[198:201], v[90:93]
	v_mfma_f32_16x16x32_bf16 v[86:89], v[174:177], v[206:209], v[86:89]
	v_mfma_f32_16x16x32_bf16 v[82:85], v[182:185], v[206:209], v[82:85]
	v_mfma_f32_16x16x32_bf16 v[70:73], v[174:177], v[218:221], v[70:73]
	v_mfma_f32_16x16x32_bf16 v[66:69], v[182:185], v[218:221], v[66:69]
	s_setprio 0
	s_barrier
; #define PG8_STAGE(bufoff, gbase, voff) do { _Pragma("unroll") for (int _i = 0; _i < 2; ++_i) \
;         __builtin_amdgcn_global_load_lds((const unsigned*)((const char*)(gbase) + (voff)[_i]), (PG8_LAS unsigned*)(lds + (bufoff) + ldsw + _i * 8192), 16, 0, 0); } while (0)
; #define PG8_LDA(dst, b, h) do { _Pragma("unroll") for (int m = 0; m < 4; ++m) _Pragma("unroll") for (int k = 0; k < 2; ++k) dst[m][k] = *(const PG8_LAS bf16x8*)(lds + PG8_SA(b, h) + aoff + m * 2048 + k * 1024); } while (0)
; #define PG8_MMA(ai, bj, At, Bt) do { __builtin_amdgcn_s_setprio(1); _Pragma("unroll") for (int m = 0; m < 4; ++m) _Pragma("unroll") for (int n = 0; n < 2; ++n) _Pragma("unroll") for (int k = 0; k < 2; ++k) \
;         acc[ai][bj][m][n] = __builtin_amdgcn_mfma_f32_16x16x32_bf16(Bt[n][k], At[m][k], acc[ai][bj][m][n], 0, 0, 0); __builtin_amdgcn_s_setprio(0); } while (0)
; #define PG8_WAIT_V(n) asm volatile("s_waitcnt vmcnt(" #n ")" ::: "memory")
; #define PG8_WAIT_L(n) asm volatile("s_waitcnt lgkmcnt(" #n ")" ::: "memory")
; #define PG8_BAR __builtin_amdgcn_s_barrier()
; #define PG8_SCHED __builtin_amdgcn_sched_barrier(0)
; template <class Epi, class Sched, bool ALIGN_EPI = false, bool SP2 = false>
; __device__ __forceinline__ void gemm_phase(PG8_LAS unsigned char* lds, const Gemm g, const Sched& S, const Epi& E) {
;     ...
;             PG8_LDA(At, 1, 1); PG8_STAGE(PG8_SB(1, 0), b3, voffB); PG8_STAGE(PG8_SB(1, 1), b3 + hstepB, voffB); PG8_STAGE(PG8_SA(1, 0), a3, voffA);
;             PG8_WAIT_V(8); PG8_WAIT_L(0); PG8_BAR; PG8_MMA(1, 0, At, B0); PG8_MMA(1, 1, At, B1); PG8_BAR; PG8_SCHED;
	s_add_i32 s28, s54, s35
	v_lshl_add_u64 v[214:215], v[214:215], 0, s[10:11]
	s_mov_b32 m0, s28
	ds_read_b128 v[186:189], v157 offset:49152
	ds_read_b128 v[190:193], v157 offset:50176
	ds_read_b128 v[194:197], v157 offset:51200
	ds_read_b128 v[198:201], v157 offset:52224
	ds_read_b128 v[202:205], v157 offset:53248
	ds_read_b128 v[206:209], v157 offset:54272
	ds_read_b128 v[210:213], v157 offset:55296
	ds_read_b128 v[218:221], v157 offset:56320
	global_load_lds_dwordx4 v[214:215], off
	s_add_i32 m0, s28, 0x2000
	s_add_u32 s26, s26, 0x100080
	v_lshl_add_u64 v[214:215], v[222:223], 0, s[10:11]
	s_addc_u32 s27, s27, 0
	s_add_i32 s28, s55, s35
	global_load_lds_dwordx4 v[214:215], off
	v_lshl_add_u64 v[214:215], s[26:27], 0, v[134:135]
	s_mov_b32 m0, s28
	s_nop 0
	global_load_lds_dwordx4 v[214:215], off
	v_lshl_add_u64 v[214:215], s[26:27], 0, v[130:131]
	s_add_i32 m0, s28, 0x2000
	s_nop 0
	global_load_lds_dwordx4 v[214:215], off
	s_waitcnt vmcnt(6)
	s_waitcnt lgkmcnt(0)
	s_barrier
	s_setprio 1
	s_waitcnt lgkmcnt(0)
	v_mfma_f32_16x16x32_bf16 v[62:65], v[146:149], v[186:189], v[62:65]
	v_mfma_f32_16x16x32_bf16 v[58:61], v[162:165], v[186:189], v[58:61]
	v_mfma_f32_16x16x32_bf16 v[50:53], v[146:149], v[194:197], v[50:53]
	v_mfma_f32_16x16x32_bf16 v[42:45], v[162:165], v[194:197], v[42:45]
	v_mfma_f32_16x16x32_bf16 v[34:37], v[146:149], v[202:205], v[34:37]
	v_mfma_f32_16x16x32_bf16 v[26:29], v[162:165], v[202:205], v[26:29]
	v_mfma_f32_16x16x32_bf16 v[18:21], v[146:149], v[210:213], v[18:21]
	v_mfma_f32_16x16x32_bf16 v[10:13], v[162:165], v[210:213], v[10:13]
	v_mfma_f32_16x16x32_bf16 v[62:65], v[158:161], v[190:193], v[62:65]
	v_mfma_f32_16x16x32_bf16 v[58:61], v[166:169], v[190:193], v[58:61]
	v_mfma_f32_16x16x32_bf16 v[50:53], v[158:161], v[198:201], v[50:53]
	v_mfma_f32_16x16x32_bf16 v[42:45], v[166:169], v[198:201], v[42:45]
	v_mfma_f32_16x16x32_bf16 v[34:37], v[158:161], v[206:209], v[34:37]
	v_mfma_f32_16x16x32_bf16 v[26:29], v[166:169], v[206:209], v[26:29]
	v_mfma_f32_16x16x32_bf16 v[18:21], v[158:161], v[218:221], v[18:21]
	v_mfma_f32_16x16x32_bf16 v[10:13], v[166:169], v[218:221], v[10:13]
	s_setprio 0
	s_setprio 1
	v_mfma_f32_16x16x32_bf16 v[54:57], v[170:173], v[186:189], v[54:57]
	v_mfma_f32_16x16x32_bf16 v[46:49], v[178:181], v[186:189], v[46:49]
	v_mfma_f32_16x16x32_bf16 v[38:41], v[170:173], v[194:197], v[38:41]
	v_mfma_f32_16x16x32_bf16 v[30:33], v[178:181], v[194:197], v[30:33]
	v_mfma_f32_16x16x32_bf16 v[22:25], v[170:173], v[202:205], v[22:25]
	v_mfma_f32_16x16x32_bf16 v[14:17], v[178:181], v[202:205], v[14:17]
	v_mfma_f32_16x16x32_bf16 v[6:9], v[170:173], v[210:213], v[6:9]
	v_mfma_f32_16x16x32_bf16 v[2:5], v[178:181], v[210:213], v[2:5]
	v_mfma_f32_16x16x32_bf16 v[54:57], v[174:177], v[190:193], v[54:57]
	v_mfma_f32_16x16x32_bf16 v[46:49], v[182:185], v[190:193], v[46:49]
	v_mfma_f32_16x16x32_bf16 v[38:41], v[174:177], v[198:201], v[38:41]
	v_mfma_f32_16x16x32_bf16 v[30:33], v[182:185], v[198:201], v[30:33]
	v_mfma_f32_16x16x32_bf16 v[22:25], v[174:177], v[206:209], v[22:25]
	v_mfma_f32_16x16x32_bf16 v[14:17], v[182:185], v[206:209], v[14:17]
	v_mfma_f32_16x16x32_bf16 v[6:9], v[174:177], v[218:221], v[6:9]
	v_mfma_f32_16x16x32_bf16 v[2:5], v[182:185], v[218:221], v[2:5]
	s_setprio 0
	s_barrier
	v_lshl_add_u64 v[214:215], v[224:225], 0, s[10:11]
	s_mov_b32 m0, s42
	s_nop 0
	global_load_lds_dwordx4 v[214:215], off
	v_lshl_add_u64 v[214:215], v[226:227], 0, s[10:11]
	s_mov_b32 m0, s43
	s_nop 0
	global_load_lds_dwordx4 v[214:215], off
	s_add_i32 s53, s53, 2
	s_add_u32 s24, s24, 0x100
	s_addc_u32 s25, s25, 0
	s_add_u32 s51, s51, 0x100
	s_addc_u32 s52, s52, 0
	s_cmp_gt_u32 s53, 61
	s_cbranch_scc0 .LBB0_210
	s_and_b64 vcc, exec, s[12:13]
	s_cbranch_vccz .LBB0_213
	s_barrier

; #define PG8_STAGE(bufoff, gbase, voff) do { _Pragma("unroll") for (int _i = 0; _i < 2; ++_i) \
;         __builtin_amdgcn_global_load_lds((const unsigned*)((const char*)(gbase) + (voff)[_i]), (PG8_LAS unsigned*)(lds + (bufoff) + ldsw + _i * 8192), 16, 0, 0); } while (0)
; #define PG8_LDA(dst, b, h) do { _Pragma("unroll") for (int m = 0; m < 4; ++m) _Pragma("unroll") for (int k = 0; k < 2; ++k) dst[m][k] = *(const PG8_LAS bf16x8*)(lds + PG8_SA(b, h) + aoff + m * 2048 + k * 1024); } while (0)
; #define PG8_LDB(dst, b, h) do { _Pragma("unroll") for (int n = 0; n < 2; ++n) _Pragma("unroll") for (int k = 0; k < 2; ++k) dst[n][k] = *(const PG8_LAS bf16x8*)(lds + PG8_SB(b, h) + boff + n * 2048 + k * 1024); } while (0)
; #define PG8_MMA(ai, bj, At, Bt) do { __builtin_amdgcn_s_setprio(1); _Pragma("unroll") for (int m = 0; m < 4; ++m) _Pragma("unroll") for (int n = 0; n < 2; ++n) _Pragma("unroll") for (int k = 0; k < 2; ++k) \
;         acc[ai][bj][m][n] = __builtin_amdgcn_mfma_f32_16x16x32_bf16(Bt[n][k], At[m][k], acc[ai][bj][m][n], 0, 0, 0); __builtin_amdgcn_s_setprio(0); } while (0)
; #define PG8_WAIT_V(n) asm volatile("s_waitcnt vmcnt(" #n ")" ::: "memory")
; #define PG8_WAIT_L(n) asm volatile("s_waitcnt lgkmcnt(" #n ")" ::: "memory")
; #define PG8_BAR __builtin_amdgcn_s_barrier()
; #define PG8_SCHED __builtin_amdgcn_sched_barrier(0)
; template <class Epi, class Sched, bool ALIGN_EPI = false, bool SP2 = false>
; __device__ __forceinline__ void gemm_phase(PG8_LAS unsigned char* lds, const Gemm g, const Sched& S, const Epi& E) {
;     ...
;         for (int t = 0; t < nt; t += 2) {
;             const bool last = (t == nt - 2);
;             const char* a1 = cA + (size_t)(t + 1) * kstep;
;             const char* a2 = last ? nA : cA + (size_t)(t + 2) * kstep; const char* b2 = last ? nB : cB + (size_t)(t + 2) * kstep;
;             const char* a3 = a2 + kstep; const char* b3 = b2 + kstep;
;             if (last && has_next) S.a_ready(nxt);
;             if constexpr (SP2) {
;             PG8_LDB(B0, 0, 0); PG8_LDB(B1, 0, 1); PG8_SCHED; PG8_LDA(At, 0, 0); PG8_STAGE(PG8_SA(1, 1), a1 + hstepA, voffA);
;             PG8_WAIT_V(8); PG8_WAIT_L(0); PG8_BAR; PG8_MMA(0, 0, At, B0); PG8_MMA(0, 1, At, B1); PG8_BAR; PG8_SCHED;
;             PG8_LDA(At, 0, 1); PG8_STAGE(PG8_SB(0, 0), b2, voffB); PG8_STAGE(PG8_SB(0, 1), b2 + hstepB, voffB); PG8_STAGE(PG8_SA(0, 0), a2, voffA);
.LBB0_241:
	s_lshl_b32 s26, s54, 7
	s_add_u32 s27, s16, s26
	s_addc_u32 s28, s17, 0
	v_add_u32_e32 v170, s46, v1
	s_add_u32 s29, s27, 0x100
	ds_read_b128 v[178:181], v170
	ds_read_b128 v[182:185], v170 offset:1024
	ds_read_b128 v[186:189], v170 offset:2048
	ds_read_b128 v[190:193], v170 offset:3072
	v_add_u32_e32 v170, s47, v1
	s_addc_u32 s55, s28, 0
	ds_read_b128 v[194:197], v170
	ds_read_b128 v[198:201], v170 offset:1024
	ds_read_b128 v[202:205], v170 offset:2048
	ds_read_b128 v[206:209], v170 offset:3072
	s_and_b64 s[24:25], s[22:23], exec
	s_cselect_b32 s25, s50, s55
	s_cselect_b32 s24, s51, s29
	s_add_u32 s26, s18, s26
	s_addc_u32 s29, s19, 0
	s_add_u32 s26, s26, 0x100
	s_addc_u32 s29, s29, 0
	s_and_b64 s[22:23], s[22:23], exec
	s_cselect_b32 s23, s52, s29
	s_cselect_b32 s22, s53, s26
	s_add_u32 s26, s27, 0x100080
	s_addc_u32 s27, s28, 0
	v_lshl_add_u64 v[214:215], s[26:27], 0, v[132:133]
	s_add_i32 m0, s1, 0xc000
	ds_read_b128 v[210:213], v175
	ds_read_b128 v[218:221], v175 offset:1024
	ds_read_b128 v[222:225], v175 offset:2048
	ds_read_b128 v[226:229], v175 offset:3072
	ds_read_b128 v[230:233], v175 offset:4096
	ds_read_b128 v[234:237], v175 offset:5120
	ds_read_b128 v[238:241], v175 offset:6144
	ds_read_b128 v[242:245], v175 offset:7168
	global_load_lds_dwordx4 v[214:215], off
	v_lshl_add_u64 v[214:215], s[26:27], 0, v[134:135]
	s_add_i32 m0, s1, 0xe000
	s_nop 0
	global_load_lds_dwordx4 v[214:215], off
	s_waitcnt vmcnt(8)
	s_waitcnt lgkmcnt(0)
	s_barrier
	s_setprio 1
	s_waitcnt lgkmcnt(0)
	v_mfma_f32_16x16x32_bf16 v[126:129], v[178:181], v[210:213], v[126:129]
	v_mfma_f32_16x16x32_bf16 v[122:125], v[186:189], v[210:213], v[122:125]
	v_mfma_f32_16x16x32_bf16 v[118:121], v[178:181], v[222:225], v[118:121]
	v_mfma_f32_16x16x32_bf16 v[114:117], v[186:189], v[222:225], v[114:117]
	v_mfma_f32_16x16x32_bf16 v[110:113], v[178:181], v[230:233], v[110:113]
	v_mfma_f32_16x16x32_bf16 v[102:105], v[186:189], v[230:233], v[102:105]
	v_mfma_f32_16x16x32_bf16 v[94:97], v[178:181], v[238:241], v[94:97]
	v_mfma_f32_16x16x32_bf16 v[86:89], v[186:189], v[238:241], v[86:89]
	v_mfma_f32_16x16x32_bf16 v[126:129], v[182:185], v[218:221], v[126:129]
	v_mfma_f32_16x16x32_bf16 v[122:125], v[190:193], v[218:221], v[122:125]
	v_mfma_f32_16x16x32_bf16 v[118:121], v[182:185], v[226:229], v[118:121]
	v_mfma_f32_16x16x32_bf16 v[114:117], v[190:193], v[226:229], v[114:117]
	v_mfma_f32_16x16x32_bf16 v[110:113], v[182:185], v[234:237], v[110:113]
	v_mfma_f32_16x16x32_bf16 v[102:105], v[190:193], v[234:237], v[102:105]
	v_mfma_f32_16x16x32_bf16 v[94:97], v[182:185], v[242:245], v[94:97]
	v_mfma_f32_16x16x32_bf16 v[86:89], v[190:193], v[242:245], v[86:89]
	s_setprio 0
	s_setprio 1
	v_mfma_f32_16x16x32_bf16 v[106:109], v[194:197], v[210:213], v[106:109]
	v_mfma_f32_16x16x32_bf16 v[98:101], v[202:205], v[210:213], v[98:101]
	v_mfma_f32_16x16x32_bf16 v[90:93], v[194:197], v[222:225], v[90:93]
	v_mfma_f32_16x16x32_bf16 v[82:85], v[202:205], v[222:225], v[82:85]
	v_mfma_f32_16x16x32_bf16 v[78:81], v[194:197], v[230:233], v[78:81]
	v_mfma_f32_16x16x32_bf16 v[74:77], v[202:205], v[230:233], v[74:77]
	v_mfma_f32_16x16x32_bf16 v[70:73], v[194:197], v[238:241], v[70:73]
	v_mfma_f32_16x16x32_bf16 v[66:69], v[202:205], v[238:241], v[66:69]
	v_mfma_f32_16x16x32_bf16 v[106:109], v[198:201], v[218:221], v[106:109]
	v_mfma_f32_16x16x32_bf16 v[98:101], v[206:209], v[218:221], v[98:101]
	v_mfma_f32_16x16x32_bf16 v[90:93], v[198:201], v[226:229], v[90:93]
	v_mfma_f32_16x16x32_bf16 v[82:85], v[206:209], v[226:229], v[82:85]
	v_mfma_f32_16x16x32_bf16 v[78:81], v[198:201], v[234:237], v[78:81]
	v_mfma_f32_16x16x32_bf16 v[74:77], v[206:209], v[234:237], v[74:77]
	v_mfma_f32_16x16x32_bf16 v[70:73], v[198:201], v[242:245], v[70:73]
	v_mfma_f32_16x16x32_bf16 v[66:69], v[206:209], v[242:245], v[66:69]
	s_setprio 0
	s_barrier
	s_add_i32 s26, s46, s39
	v_lshl_add_u64 v[214:215], s[22:23], 0, v[130:131]
	s_mov_b32 m0, s26
	ds_read_b128 v[210:213], v175 offset:16384
	ds_read_b128 v[218:221], v175 offset:17408
	ds_read_b128 v[222:225], v175 offset:18432
	ds_read_b128 v[226:229], v175 offset:19456
	ds_read_b128 v[230:233], v175 offset:20480
	ds_read_b128 v[234:237], v175 offset:21504
	ds_read_b128 v[238:241], v175 offset:22528
	ds_read_b128 v[242:245], v175 offset:23552
	global_load_lds_dwordx4 v[214:215], off
	s_add_i32 m0, s26, 0x2000
	s_add_u32 s26, s22, 0x100000
	v_lshl_add_u64 v[246:247], s[22:23], 0, v[136:137]
	s_addc_u32 s27, s23, 0
	s_add_i32 s28, s47, s39
	global_load_lds_dwordx4 v[246:247], off
	v_lshl_add_u64 v[248:249], s[26:27], 0, v[130:131]
	s_mov_b32 m0, s28
	v_lshl_add_u64 v[250:251], s[24:25], 0, v[134:135]
	global_load_lds_dwordx4 v[248:249], off
	v_lshl_add_u64 v[248:249], s[26:27], 0, v[136:137]
	s_add_i32 m0, s28, 0x2000
	s_nop 0
	global_load_lds_dwordx4 v[248:249], off
	v_lshl_add_u64 v[248:249], s[24:25], 0, v[132:133]
	s_waitcnt vmcnt(6)
	s_waitcnt lgkmcnt(0)
	s_barrier
; #define PG8_STAGE(bufoff, gbase, voff) do { _Pragma("unroll") for (int _i = 0; _i < 2; ++_i) \
;         __builtin_amdgcn_global_load_lds((const unsigned*)((const char*)(gbase) + (voff)[_i]), (PG8_LAS unsigned*)(lds + (bufoff) + ldsw + _i * 8192), 16, 0, 0); } while (0)
; #define PG8_LDA(dst, b, h) do { _Pragma("unroll") for (int m = 0; m < 4; ++m) _Pragma("unroll") for (int k = 0; k < 2; ++k) dst[m][k] = *(const PG8_LAS bf16x8*)(lds + PG8_SA(b, h) + aoff + m * 2048 + k * 1024); } while (0)
; #define PG8_LDB(dst, b, h) do { _Pragma("unroll") for (int n = 0; n < 2; ++n) _Pragma("unroll") for (int k = 0; k < 2; ++k) dst[n][k] = *(const PG8_LAS bf16x8*)(lds + PG8_SB(b, h) + boff + n * 2048 + k * 1024); } while (0)
; #define PG8_MMA(ai, bj, At, Bt) do { __builtin_amdgcn_s_setprio(1); _Pragma("unroll") for (int m = 0; m < 4; ++m) _Pragma("unroll") for (int n = 0; n < 2; ++n) _Pragma("unroll") for (int k = 0; k < 2; ++k) \
;         acc[ai][bj][m][n] = __builtin_amdgcn_mfma_f32_16x16x32_bf16(Bt[n][k], At[m][k], acc[ai][bj][m][n], 0, 0, 0); __builtin_amdgcn_s_setprio(0); } while (0)
; #define PG8_WAIT_V(n) asm volatile("s_waitcnt vmcnt(" #n ")" ::: "memory")
; #define PG8_WAIT_L(n) asm volatile("s_waitcnt lgkmcnt(" #n ")" ::: "memory")
; #define PG8_BAR __builtin_amdgcn_s_barrier()
; #define PG8_SCHED __builtin_amdgcn_sched_barrier(0)
; template <class Epi, class Sched, bool ALIGN_EPI = false, bool SP2 = false>
; __device__ __forceinline__ void gemm_phase(PG8_LAS unsigned char* lds, const Gemm g, const Sched& S, const Epi& E) {
;     ...
;             PG8_WAIT_V(8); PG8_WAIT_L(0); PG8_BAR; PG8_MMA(1, 0, At, B0); PG8_MMA(1, 1, At, B1); PG8_BAR; PG8_SCHED;
;             PG8_LDB(B0, 1, 0); PG8_LDB(B1, 1, 1); PG8_SCHED; PG8_LDA(At, 1, 0); PG8_STAGE(PG8_SA(0, 1), a2 + hstepA, voffA);
;             PG8_WAIT_V(8); PG8_WAIT_L(0); PG8_BAR; PG8_MMA(0, 0, At, B0); PG8_MMA(0, 1, At, B1); PG8_BAR; PG8_SCHED;
;             PG8_LDA(At, 1, 1); PG8_STAGE(PG8_SB(1, 0), b3, voffB); PG8_STAGE(PG8_SB(1, 1), b3 + hstepB, voffB); PG8_STAGE(PG8_SA(1, 0), a3, voffA);
	s_setprio 1
	s_waitcnt lgkmcnt(0)
	v_mfma_f32_16x16x32_bf16 v[62:65], v[178:181], v[210:213], v[62:65]
	v_mfma_f32_16x16x32_bf16 v[58:61], v[186:189], v[210:213], v[58:61]
	v_mfma_f32_16x16x32_bf16 v[50:53], v[178:181], v[222:225], v[50:53]
	v_mfma_f32_16x16x32_bf16 v[42:45], v[186:189], v[222:225], v[42:45]
	v_mfma_f32_16x16x32_bf16 v[34:37], v[178:181], v[230:233], v[34:37]
	v_mfma_f32_16x16x32_bf16 v[26:29], v[186:189], v[230:233], v[26:29]
	v_mfma_f32_16x16x32_bf16 v[18:21], v[178:181], v[238:241], v[18:21]
	v_mfma_f32_16x16x32_bf16 v[10:13], v[186:189], v[238:241], v[10:13]
	v_mfma_f32_16x16x32_bf16 v[62:65], v[182:185], v[218:221], v[62:65]
	v_mfma_f32_16x16x32_bf16 v[58:61], v[190:193], v[218:221], v[58:61]
	v_mfma_f32_16x16x32_bf16 v[50:53], v[182:185], v[226:229], v[50:53]
	v_mfma_f32_16x16x32_bf16 v[42:45], v[190:193], v[226:229], v[42:45]
	v_mfma_f32_16x16x32_bf16 v[34:37], v[182:185], v[234:237], v[34:37]
	v_mfma_f32_16x16x32_bf16 v[26:29], v[190:193], v[234:237], v[26:29]
	v_mfma_f32_16x16x32_bf16 v[18:21], v[182:185], v[242:245], v[18:21]
	v_mfma_f32_16x16x32_bf16 v[10:13], v[190:193], v[242:245], v[10:13]
	s_setprio 0
	s_setprio 1
	v_mfma_f32_16x16x32_bf16 v[54:57], v[194:197], v[210:213], v[54:57]
	v_mfma_f32_16x16x32_bf16 v[46:49], v[202:205], v[210:213], v[46:49]
	v_mfma_f32_16x16x32_bf16 v[38:41], v[194:197], v[222:225], v[38:41]
	v_mfma_f32_16x16x32_bf16 v[30:33], v[202:205], v[222:225], v[30:33]
	v_mfma_f32_16x16x32_bf16 v[22:25], v[194:197], v[230:233], v[22:25]
	v_mfma_f32_16x16x32_bf16 v[14:17], v[202:205], v[230:233], v[14:17]
	v_mfma_f32_16x16x32_bf16 v[6:9], v[194:197], v[238:241], v[6:9]
	v_mfma_f32_16x16x32_bf16 v[2:5], v[202:205], v[238:241], v[2:5]
	v_mfma_f32_16x16x32_bf16 v[54:57], v[198:201], v[218:221], v[54:57]
	v_mfma_f32_16x16x32_bf16 v[46:49], v[206:209], v[218:221], v[46:49]
	v_mfma_f32_16x16x32_bf16 v[38:41], v[198:201], v[226:229], v[38:41]
	v_mfma_f32_16x16x32_bf16 v[30:33], v[206:209], v[226:229], v[30:33]
	v_mfma_f32_16x16x32_bf16 v[22:25], v[198:201], v[234:237], v[22:25]
	v_mfma_f32_16x16x32_bf16 v[14:17], v[206:209], v[234:237], v[14:17]
	v_mfma_f32_16x16x32_bf16 v[6:9], v[198:201], v[242:245], v[6:9]
	v_mfma_f32_16x16x32_bf16 v[2:5], v[206:209], v[242:245], v[2:5]
	s_setprio 0
	s_barrier
	s_mov_b32 m0, s1
	s_nop 0
	global_load_lds_dwordx4 v[248:249], off
	s_mov_b32 m0, s40
	s_nop 0
	global_load_lds_dwordx4 v[250:251], off
	s_add_i32 s26, 0, 0x18000
	v_add_u32_e32 v170, s26, v1
	s_add_i32 s27, 0, 0x1c000
	ds_read_b128 v[178:181], v170
	ds_read_b128 v[182:185], v170 offset:1024
	ds_read_b128 v[186:189], v170 offset:2048
	ds_read_b128 v[190:193], v170 offset:3072
	v_add_u32_e32 v170, s27, v1
	ds_read_b128 v[194:197], v170
	ds_read_b128 v[198:201], v170 offset:1024
	ds_read_b128 v[202:205], v170 offset:2048
	ds_read_b128 v[206:209], v170 offset:3072
	s_add_u32 s24, s24, 0x100000
	s_addc_u32 s25, s25, 0
	s_mov_b32 m0, s41
	v_lshl_add_u64 v[252:253], s[24:25], 0, v[132:133]
	ds_read_b128 v[210:213], v175 offset:32768
	ds_read_b128 v[218:221], v175 offset:33792
	ds_read_b128 v[222:225], v175 offset:34816
	ds_read_b128 v[226:229], v175 offset:35840
	ds_read_b128 v[230:233], v175 offset:36864
	ds_read_b128 v[234:237], v175 offset:37888
	ds_read_b128 v[238:241], v175 offset:38912
	ds_read_b128 v[242:245], v175 offset:39936
	global_load_lds_dwordx4 v[252:253], off
	v_lshl_add_u64 v[252:253], s[24:25], 0, v[134:135]
	s_mov_b32 m0, s42
	s_nop 0
	global_load_lds_dwordx4 v[252:253], off
	s_waitcnt vmcnt(8)
	s_waitcnt lgkmcnt(0)
	s_barrier
	s_setprio 1
	s_waitcnt lgkmcnt(0)
	v_mfma_f32_16x16x32_bf16 v[126:129], v[178:181], v[210:213], v[126:129]
	v_mfma_f32_16x16x32_bf16 v[122:125], v[186:189], v[210:213], v[122:125]
	v_mfma_f32_16x16x32_bf16 v[118:121], v[178:181], v[222:225], v[118:121]
	v_mfma_f32_16x16x32_bf16 v[114:117], v[186:189], v[222:225], v[114:117]
	v_mfma_f32_16x16x32_bf16 v[110:113], v[178:181], v[230:233], v[110:113]
	v_mfma_f32_16x16x32_bf16 v[102:105], v[186:189], v[230:233], v[102:105]
	v_mfma_f32_16x16x32_bf16 v[94:97], v[178:181], v[238:241], v[94:97]
	v_mfma_f32_16x16x32_bf16 v[86:89], v[186:189], v[238:241], v[86:89]
	v_mfma_f32_16x16x32_bf16 v[126:129], v[182:185], v[218:221], v[126:129]
	v_mfma_f32_16x16x32_bf16 v[122:125], v[190:193], v[218:221], v[122:125]
	v_mfma_f32_16x16x32_bf16 v[118:121], v[182:185], v[226:229], v[118:121]
	v_mfma_f32_16x16x32_bf16 v[114:117], v[190:193], v[226:229], v[114:117]
	v_mfma_f32_16x16x32_bf16 v[110:113], v[182:185], v[234:237], v[110:113]
	v_mfma_f32_16x16x32_bf16 v[102:105], v[190:193], v[234:237], v[102:105]
	v_mfma_f32_16x16x32_bf16 v[94:97], v[182:185], v[242:245], v[94:97]
	v_mfma_f32_16x16x32_bf16 v[86:89], v[190:193], v[242:245], v[86:89]
	s_setprio 0
	s_setprio 1
	v_mfma_f32_16x16x32_bf16 v[106:109], v[194:197], v[210:213], v[106:109]
	v_mfma_f32_16x16x32_bf16 v[98:101], v[202:205], v[210:213], v[98:101]
	v_mfma_f32_16x16x32_bf16 v[90:93], v[194:197], v[222:225], v[90:93]
	v_mfma_f32_16x16x32_bf16 v[82:85], v[202:205], v[222:225], v[82:85]
	v_mfma_f32_16x16x32_bf16 v[78:81], v[194:197], v[230:233], v[78:81]
	v_mfma_f32_16x16x32_bf16 v[74:77], v[202:205], v[230:233], v[74:77]
	v_mfma_f32_16x16x32_bf16 v[70:73], v[194:197], v[238:241], v[70:73]
	v_mfma_f32_16x16x32_bf16 v[66:69], v[202:205], v[238:241], v[66:69]
	v_mfma_f32_16x16x32_bf16 v[106:109], v[198:201], v[218:221], v[106:109]
	v_mfma_f32_16x16x32_bf16 v[98:101], v[206:209], v[218:221], v[98:101]
	v_mfma_f32_16x16x32_bf16 v[90:93], v[198:201], v[226:229], v[90:93]
	v_mfma_f32_16x16x32_bf16 v[82:85], v[206:209], v[226:229], v[82:85]
	v_mfma_f32_16x16x32_bf16 v[78:81], v[198:201], v[234:237], v[78:81]
	v_mfma_f32_16x16x32_bf16 v[74:77], v[206:209], v[234:237], v[74:77]
	v_mfma_f32_16x16x32_bf16 v[70:73], v[198:201], v[242:245], v[70:73]
	v_mfma_f32_16x16x32_bf16 v[66:69], v[206:209], v[242:245], v[66:69]
	s_setprio 0
	s_barrier
; #define PG8_STAGE(bufoff, gbase, voff) do { _Pragma("unroll") for (int _i = 0; _i < 2; ++_i) \
;         __builtin_amdgcn_global_load_lds((const unsigned*)((const char*)(gbase) + (voff)[_i]), (PG8_LAS unsigned*)(lds + (bufoff) + ldsw + _i * 8192), 16, 0, 0); } while (0)
; #define PG8_LDA(dst, b, h) do { _Pragma("unroll") for (int m = 0; m < 4; ++m) _Pragma("unroll") for (int k = 0; k < 2; ++k) dst[m][k] = *(const PG8_LAS bf16x8*)(lds + PG8_SA(b, h) + aoff + m * 2048 + k * 1024); } while (0)
; #define PG8_MMA(ai, bj, At, Bt) do { __builtin_amdgcn_s_setprio(1); _Pragma("unroll") for (int m = 0; m < 4; ++m) _Pragma("unroll") for (int n = 0; n < 2; ++n) _Pragma("unroll") for (int k = 0; k < 2; ++k) \
;         acc[ai][bj][m][n] = __builtin_amdgcn_mfma_f32_16x16x32_bf16(Bt[n][k], At[m][k], acc[ai][bj][m][n], 0, 0, 0); __builtin_amdgcn_s_setprio(0); } while (0)
; #define PG8_WAIT_V(n) asm volatile("s_waitcnt vmcnt(" #n ")" ::: "memory")
; #define PG8_WAIT_L(n) asm volatile("s_waitcnt lgkmcnt(" #n ")" ::: "memory")
; #define PG8_BAR __builtin_amdgcn_s_barrier()
; #define PG8_SCHED __builtin_amdgcn_sched_barrier(0)
; template <class Epi, class Sched, bool ALIGN_EPI = false, bool SP2 = false>
; __device__ __forceinline__ void gemm_phase(PG8_LAS unsigned char* lds, const Gemm g, const Sched& S, const Epi& E) {
;     ...
;             PG8_LDA(At, 1, 1); PG8_STAGE(PG8_SB(1, 0), b3, voffB); PG8_STAGE(PG8_SB(1, 1), b3 + hstepB, voffB); PG8_STAGE(PG8_SA(1, 0), a3, voffA);
;             PG8_WAIT_V(8); PG8_WAIT_L(0); PG8_BAR; PG8_MMA(1, 0, At, B0); PG8_MMA(1, 1, At, B1); PG8_BAR; PG8_SCHED;
	s_add_i32 s24, s26, s39
	v_lshl_add_u64 v[214:215], v[214:215], 0, s[10:11]
	s_mov_b32 m0, s24
	ds_read_b128 v[210:213], v175 offset:49152
	ds_read_b128 v[218:221], v175 offset:50176
	ds_read_b128 v[222:225], v175 offset:51200
	ds_read_b128 v[226:229], v175 offset:52224
	ds_read_b128 v[230:233], v175 offset:53248
	ds_read_b128 v[234:237], v175 offset:54272
	ds_read_b128 v[238:241], v175 offset:55296
	ds_read_b128 v[242:245], v175 offset:56320
	global_load_lds_dwordx4 v[214:215], off
	s_add_i32 m0, s24, 0x2000
	s_add_u32 s22, s22, 0x100080
	v_lshl_add_u64 v[214:215], v[246:247], 0, s[10:11]
	s_addc_u32 s23, s23, 0
	s_add_i32 s24, s27, s39
	global_load_lds_dwordx4 v[214:215], off
	v_lshl_add_u64 v[214:215], s[22:23], 0, v[130:131]
	s_mov_b32 m0, s24
	s_nop 0
	global_load_lds_dwordx4 v[214:215], off
	v_lshl_add_u64 v[214:215], s[22:23], 0, v[136:137]
	s_add_i32 m0, s24, 0x2000
	s_nop 0
	global_load_lds_dwordx4 v[214:215], off
	s_waitcnt vmcnt(6)
	s_waitcnt lgkmcnt(0)
	s_barrier
	s_setprio 1
	s_waitcnt lgkmcnt(0)
	v_mfma_f32_16x16x32_bf16 v[62:65], v[178:181], v[210:213], v[62:65]
	v_mfma_f32_16x16x32_bf16 v[58:61], v[186:189], v[210:213], v[58:61]
	v_mfma_f32_16x16x32_bf16 v[50:53], v[178:181], v[222:225], v[50:53]
	v_mfma_f32_16x16x32_bf16 v[42:45], v[186:189], v[222:225], v[42:45]
	v_mfma_f32_16x16x32_bf16 v[34:37], v[178:181], v[230:233], v[34:37]
	v_mfma_f32_16x16x32_bf16 v[26:29], v[186:189], v[230:233], v[26:29]
	v_mfma_f32_16x16x32_bf16 v[18:21], v[178:181], v[238:241], v[18:21]
	v_mfma_f32_16x16x32_bf16 v[10:13], v[186:189], v[238:241], v[10:13]
	v_mfma_f32_16x16x32_bf16 v[62:65], v[182:185], v[218:221], v[62:65]
	v_mfma_f32_16x16x32_bf16 v[58:61], v[190:193], v[218:221], v[58:61]
	v_mfma_f32_16x16x32_bf16 v[50:53], v[182:185], v[226:229], v[50:53]
	v_mfma_f32_16x16x32_bf16 v[42:45], v[190:193], v[226:229], v[42:45]
	v_mfma_f32_16x16x32_bf16 v[34:37], v[182:185], v[234:237], v[34:37]
	v_mfma_f32_16x16x32_bf16 v[26:29], v[190:193], v[234:237], v[26:29]
	v_mfma_f32_16x16x32_bf16 v[18:21], v[182:185], v[242:245], v[18:21]
	v_mfma_f32_16x16x32_bf16 v[10:13], v[190:193], v[242:245], v[10:13]
	s_setprio 0
	s_setprio 1
	v_mfma_f32_16x16x32_bf16 v[54:57], v[194:197], v[210:213], v[54:57]
	v_mfma_f32_16x16x32_bf16 v[46:49], v[202:205], v[210:213], v[46:49]
	v_mfma_f32_16x16x32_bf16 v[38:41], v[194:197], v[222:225], v[38:41]
	v_mfma_f32_16x16x32_bf16 v[30:33], v[202:205], v[222:225], v[30:33]
	v_mfma_f32_16x16x32_bf16 v[22:25], v[194:197], v[230:233], v[22:25]
	v_mfma_f32_16x16x32_bf16 v[14:17], v[202:205], v[230:233], v[14:17]
	v_mfma_f32_16x16x32_bf16 v[6:9], v[194:197], v[238:241], v[6:9]
	v_mfma_f32_16x16x32_bf16 v[2:5], v[202:205], v[238:241], v[2:5]
	v_mfma_f32_16x16x32_bf16 v[54:57], v[198:201], v[218:221], v[54:57]
	v_mfma_f32_16x16x32_bf16 v[46:49], v[206:209], v[218:221], v[46:49]
	v_mfma_f32_16x16x32_bf16 v[38:41], v[198:201], v[226:229], v[38:41]
	v_mfma_f32_16x16x32_bf16 v[30:33], v[206:209], v[226:229], v[30:33]
	v_mfma_f32_16x16x32_bf16 v[22:25], v[198:201], v[234:237], v[22:25]
	v_mfma_f32_16x16x32_bf16 v[14:17], v[206:209], v[234:237], v[14:17]
	v_mfma_f32_16x16x32_bf16 v[6:9], v[198:201], v[242:245], v[6:9]
	v_mfma_f32_16x16x32_bf16 v[2:5], v[206:209], v[242:245], v[2:5]
	s_setprio 0
	s_barrier
	v_lshl_add_u64 v[214:215], v[248:249], 0, s[10:11]
	s_mov_b32 m0, s43
	s_nop 0
	global_load_lds_dwordx4 v[214:215], off
	v_lshl_add_u64 v[214:215], v[250:251], 0, s[10:11]
	s_mov_b32 m0, s44
	s_nop 0
	global_load_lds_dwordx4 v[214:215], off
	s_add_i32 s22, s54, 2
	s_cmp_gt_u32 s54, 61
	s_mov_b32 s54, s22
	s_cbranch_scc1 .LBB0_255

; #define PG8_STAGE(bufoff, gbase, voff) do { _Pragma("unroll") for (int _i = 0; _i < 2; ++_i) \
;         __builtin_amdgcn_global_load_lds((const unsigned*)((const char*)(gbase) + (voff)[_i]), (PG8_LAS unsigned*)(lds + (bufoff) + ldsw + _i * 8192), 16, 0, 0); } while (0)
; #define PG8_LDA(dst, b, h) do { _Pragma("unroll") for (int m = 0; m < 4; ++m) _Pragma("unroll") for (int k = 0; k < 2; ++k) dst[m][k] = *(const PG8_LAS bf16x8*)(lds + PG8_SA(b, h) + aoff + m * 2048 + k * 1024); } while (0)
; #define PG8_LDB(dst, b, h) do { _Pragma("unroll") for (int n = 0; n < 2; ++n) _Pragma("unroll") for (int k = 0; k < 2; ++k) dst[n][k] = *(const PG8_LAS bf16x8*)(lds + PG8_SB(b, h) + boff + n * 2048 + k * 1024); } while (0)
; #define PG8_MMA(ai, bj, At, Bt) do { __builtin_amdgcn_s_setprio(1); _Pragma("unroll") for (int m = 0; m < 4; ++m) _Pragma("unroll") for (int n = 0; n < 2; ++n) _Pragma("unroll") for (int k = 0; k < 2; ++k) \
;         acc[ai][bj][m][n] = __builtin_amdgcn_mfma_f32_16x16x32_bf16(Bt[n][k], At[m][k], acc[ai][bj][m][n], 0, 0, 0); __builtin_amdgcn_s_setprio(0); } while (0)
; #define PG8_WAIT_V(n) asm volatile("s_waitcnt vmcnt(" #n ")" ::: "memory")
; #define PG8_WAIT_L(n) asm volatile("s_waitcnt lgkmcnt(" #n ")" ::: "memory")
; #define PG8_BAR __builtin_amdgcn_s_barrier()
; #define PG8_SCHED __builtin_amdgcn_sched_barrier(0)
; template <class Epi, class Sched, bool ALIGN_EPI = false, bool SP2 = false>
; __device__ __forceinline__ void gemm_phase(PG8_LAS unsigned char* lds, const Gemm g, const Sched& S, const Epi& E) {
;     ...
;         for (int t = 0; t < nt; t += 2) {
;             const bool last = (t == nt - 2);
;             const char* a1 = cA + (size_t)(t + 1) * kstep;
;             const char* a2 = last ? nA : cA + (size_t)(t + 2) * kstep; const char* b2 = last ? nB : cB + (size_t)(t + 2) * kstep;
;             const char* a3 = a2 + kstep; const char* b3 = b2 + kstep;
;             if (last && has_next) S.a_ready(nxt);
;             if constexpr (SP2) {
;             PG8_LDB(B0, 0, 0); PG8_LDB(B1, 0, 1); PG8_SCHED; PG8_LDA(At, 0, 0); PG8_STAGE(PG8_SA(1, 1), a1 + hstepA, voffA);
;             PG8_WAIT_V(8); PG8_WAIT_L(0); PG8_BAR; PG8_MMA(0, 0, At, B0); PG8_MMA(0, 1, At, B1); PG8_BAR; PG8_SCHED;
;             PG8_LDA(At, 0, 1); PG8_STAGE(PG8_SB(0, 0), b2, voffB); PG8_STAGE(PG8_SB(0, 1), b2 + hstepB, voffB); PG8_STAGE(PG8_SA(0, 0), a2, voffA);
.LBB0_443:
	ds_read_b128 v[146:149], v155
	ds_read_b128 v[158:161], v155 offset:1024
	ds_read_b128 v[162:165], v155 offset:2048
	ds_read_b128 v[166:169], v155 offset:3072
	ds_read_b128 v[174:177], v156
	ds_read_b128 v[178:181], v156 offset:1024
	ds_read_b128 v[182:185], v156 offset:2048
	ds_read_b128 v[186:189], v156 offset:3072
	s_add_u32 s28, s26, 0xfff00080
	s_addc_u32 s29, s27, -1
	s_cmp_eq_u32 s53, 60
	s_cselect_b32 s31, s17, s29
	s_cselect_b32 s30, s49, s28
	s_cselect_b32 s29, s19, s52
	s_cselect_b32 s28, s50, s51
	v_lshl_add_u64 v[170:171], s[26:27], 0, v[138:139]
	s_add_i32 m0, s25, 0xc000
	ds_read_b128 v[190:193], v157
	ds_read_b128 v[194:197], v157 offset:1024
	ds_read_b128 v[198:201], v157 offset:2048
	ds_read_b128 v[202:205], v157 offset:3072
	ds_read_b128 v[206:209], v157 offset:4096
	ds_read_b128 v[210:213], v157 offset:5120
	ds_read_b128 v[218:221], v157 offset:6144
	ds_read_b128 v[222:225], v157 offset:7168
	global_load_lds_dwordx4 v[170:171], off
	v_lshl_add_u64 v[170:171], s[26:27], 0, v[140:141]
	s_add_i32 m0, s25, 0xe000
	s_nop 0
	global_load_lds_dwordx4 v[170:171], off
	s_waitcnt vmcnt(8)
	s_waitcnt lgkmcnt(0)
	s_barrier
	s_setprio 1
	s_waitcnt lgkmcnt(0)
	v_mfma_f32_16x16x32_bf16 v[126:129], v[146:149], v[190:193], v[126:129]
	v_mfma_f32_16x16x32_bf16 v[122:125], v[162:165], v[190:193], v[122:125]
	v_mfma_f32_16x16x32_bf16 v[118:121], v[146:149], v[198:201], v[118:121]
	v_mfma_f32_16x16x32_bf16 v[114:117], v[162:165], v[198:201], v[114:117]
	v_mfma_f32_16x16x32_bf16 v[106:109], v[146:149], v[206:209], v[106:109]
	v_mfma_f32_16x16x32_bf16 v[98:101], v[162:165], v[206:209], v[98:101]
	v_mfma_f32_16x16x32_bf16 v[78:81], v[146:149], v[218:221], v[78:81]
	v_mfma_f32_16x16x32_bf16 v[74:77], v[162:165], v[218:221], v[74:77]
	v_mfma_f32_16x16x32_bf16 v[126:129], v[158:161], v[194:197], v[126:129]
	v_mfma_f32_16x16x32_bf16 v[122:125], v[166:169], v[194:197], v[122:125]
	v_mfma_f32_16x16x32_bf16 v[118:121], v[158:161], v[202:205], v[118:121]
	v_mfma_f32_16x16x32_bf16 v[114:117], v[166:169], v[202:205], v[114:117]
	v_mfma_f32_16x16x32_bf16 v[106:109], v[158:161], v[210:213], v[106:109]
	v_mfma_f32_16x16x32_bf16 v[98:101], v[166:169], v[210:213], v[98:101]
	v_mfma_f32_16x16x32_bf16 v[78:81], v[158:161], v[222:225], v[78:81]
	v_mfma_f32_16x16x32_bf16 v[74:77], v[166:169], v[222:225], v[74:77]
	s_setprio 0
	s_setprio 1
	v_mfma_f32_16x16x32_bf16 v[110:113], v[174:177], v[190:193], v[110:113]
	v_mfma_f32_16x16x32_bf16 v[102:105], v[182:185], v[190:193], v[102:105]
	v_mfma_f32_16x16x32_bf16 v[94:97], v[174:177], v[198:201], v[94:97]
	v_mfma_f32_16x16x32_bf16 v[90:93], v[182:185], v[198:201], v[90:93]
	v_mfma_f32_16x16x32_bf16 v[86:89], v[174:177], v[206:209], v[86:89]
	v_mfma_f32_16x16x32_bf16 v[82:85], v[182:185], v[206:209], v[82:85]
	v_mfma_f32_16x16x32_bf16 v[70:73], v[174:177], v[218:221], v[70:73]
	v_mfma_f32_16x16x32_bf16 v[66:69], v[182:185], v[218:221], v[66:69]
	v_mfma_f32_16x16x32_bf16 v[110:113], v[178:181], v[194:197], v[110:113]
	v_mfma_f32_16x16x32_bf16 v[102:105], v[186:189], v[194:197], v[102:105]
	v_mfma_f32_16x16x32_bf16 v[94:97], v[178:181], v[202:205], v[94:97]
	v_mfma_f32_16x16x32_bf16 v[90:93], v[186:189], v[202:205], v[90:93]
	v_mfma_f32_16x16x32_bf16 v[86:89], v[178:181], v[210:213], v[86:89]
	v_mfma_f32_16x16x32_bf16 v[82:85], v[186:189], v[210:213], v[82:85]
	v_mfma_f32_16x16x32_bf16 v[70:73], v[178:181], v[222:225], v[70:73]
	v_mfma_f32_16x16x32_bf16 v[66:69], v[186:189], v[222:225], v[66:69]
	s_setprio 0
	s_barrier
	s_add_i32 s54, s45, s37
	v_lshl_add_u64 v[170:171], s[28:29], 0, v[134:135]
	s_mov_b32 m0, s54
	ds_read_b128 v[190:193], v157 offset:16384
	ds_read_b128 v[194:197], v157 offset:17408
	ds_read_b128 v[198:201], v157 offset:18432
	ds_read_b128 v[202:205], v157 offset:19456
	ds_read_b128 v[206:209], v157 offset:20480
	ds_read_b128 v[210:213], v157 offset:21504
	ds_read_b128 v[218:221], v157 offset:22528
	ds_read_b128 v[222:225], v157 offset:23552
	global_load_lds_dwordx4 v[170:171], off
	s_add_i32 m0, s54, 0x2000
	s_add_u32 s54, s28, 0x100000
	v_lshl_add_u64 v[214:215], s[28:29], 0, v[130:131]
	s_addc_u32 s55, s29, 0
	s_add_i32 s56, s46, s37
	global_load_lds_dwordx4 v[214:215], off
	v_lshl_add_u64 v[226:227], s[54:55], 0, v[134:135]
	s_mov_b32 m0, s56
	v_lshl_add_u64 v[228:229], s[30:31], 0, v[132:133]
	global_load_lds_dwordx4 v[226:227], off
	v_lshl_add_u64 v[226:227], s[54:55], 0, v[130:131]
	s_add_i32 m0, s56, 0x2000
	s_nop 0
	global_load_lds_dwordx4 v[226:227], off
	v_lshl_add_u64 v[226:227], s[30:31], 0, v[136:137]
	s_waitcnt vmcnt(6)
	s_waitcnt lgkmcnt(0)
	s_barrier
; #define PG8_STAGE(bufoff, gbase, voff) do { _Pragma("unroll") for (int _i = 0; _i < 2; ++_i) \
;         __builtin_amdgcn_global_load_lds((const unsigned*)((const char*)(gbase) + (voff)[_i]), (PG8_LAS unsigned*)(lds + (bufoff) + ldsw + _i * 8192), 16, 0, 0); } while (0)
; #define PG8_LDA(dst, b, h) do { _Pragma("unroll") for (int m = 0; m < 4; ++m) _Pragma("unroll") for (int k = 0; k < 2; ++k) dst[m][k] = *(const PG8_LAS bf16x8*)(lds + PG8_SA(b, h) + aoff + m * 2048 + k * 1024); } while (0)
; #define PG8_LDB(dst, b, h) do { _Pragma("unroll") for (int n = 0; n < 2; ++n) _Pragma("unroll") for (int k = 0; k < 2; ++k) dst[n][k] = *(const PG8_LAS bf16x8*)(lds + PG8_SB(b, h) + boff + n * 2048 + k * 1024); } while (0)
; #define PG8_MMA(ai, bj, At, Bt) do { __builtin_amdgcn_s_setprio(1); _Pragma("unroll") for (int m = 0; m < 4; ++m) _Pragma("unroll") for (int n = 0; n < 2; ++n) _Pragma("unroll") for (int k = 0; k < 2; ++k) \
;         acc[ai][bj][m][n] = __builtin_amdgcn_mfma_f32_16x16x32_bf16(Bt[n][k], At[m][k], acc[ai][bj][m][n], 0, 0, 0); __builtin_amdgcn_s_setprio(0); } while (0)
; #define PG8_WAIT_V(n) asm volatile("s_waitcnt vmcnt(" #n ")" ::: "memory")
; #define PG8_WAIT_L(n) asm volatile("s_waitcnt lgkmcnt(" #n ")" ::: "memory")
; #define PG8_BAR __builtin_amdgcn_s_barrier()
; #define PG8_SCHED __builtin_amdgcn_sched_barrier(0)
; template <class Epi, class Sched, bool ALIGN_EPI = false, bool SP2 = false>
; __device__ __forceinline__ void gemm_phase(PG8_LAS unsigned char* lds, const Gemm g, const Sched& S, const Epi& E) {
;     ...
;             PG8_WAIT_V(8); PG8_WAIT_L(0); PG8_BAR; PG8_MMA(1, 0, At, B0); PG8_MMA(1, 1, At, B1); PG8_BAR; PG8_SCHED;
;             PG8_LDB(B0, 1, 0); PG8_LDB(B1, 1, 1); PG8_SCHED; PG8_LDA(At, 1, 0); PG8_STAGE(PG8_SA(0, 1), a2 + hstepA, voffA);
;             PG8_WAIT_V(8); PG8_WAIT_L(0); PG8_BAR; PG8_MMA(0, 0, At, B0); PG8_MMA(0, 1, At, B1); PG8_BAR; PG8_SCHED;
;             PG8_LDA(At, 1, 1); PG8_STAGE(PG8_SB(1, 0), b3, voffB); PG8_STAGE(PG8_SB(1, 1), b3 + hstepB, voffB); PG8_STAGE(PG8_SA(1, 0), a3, voffA);
	s_setprio 1
	s_waitcnt lgkmcnt(0)
	v_mfma_f32_16x16x32_bf16 v[62:65], v[146:149], v[190:193], v[62:65]
	v_mfma_f32_16x16x32_bf16 v[58:61], v[162:165], v[190:193], v[58:61]
	v_mfma_f32_16x16x32_bf16 v[50:53], v[146:149], v[198:201], v[50:53]
	v_mfma_f32_16x16x32_bf16 v[42:45], v[162:165], v[198:201], v[42:45]
	v_mfma_f32_16x16x32_bf16 v[34:37], v[146:149], v[206:209], v[34:37]
	v_mfma_f32_16x16x32_bf16 v[26:29], v[162:165], v[206:209], v[26:29]
	v_mfma_f32_16x16x32_bf16 v[18:21], v[146:149], v[218:221], v[18:21]
	v_mfma_f32_16x16x32_bf16 v[10:13], v[162:165], v[218:221], v[10:13]
	v_mfma_f32_16x16x32_bf16 v[62:65], v[158:161], v[194:197], v[62:65]
	v_mfma_f32_16x16x32_bf16 v[58:61], v[166:169], v[194:197], v[58:61]
	v_mfma_f32_16x16x32_bf16 v[50:53], v[158:161], v[202:205], v[50:53]
	v_mfma_f32_16x16x32_bf16 v[42:45], v[166:169], v[202:205], v[42:45]
	v_mfma_f32_16x16x32_bf16 v[34:37], v[158:161], v[210:213], v[34:37]
	v_mfma_f32_16x16x32_bf16 v[26:29], v[166:169], v[210:213], v[26:29]
	v_mfma_f32_16x16x32_bf16 v[18:21], v[158:161], v[222:225], v[18:21]
	v_mfma_f32_16x16x32_bf16 v[10:13], v[166:169], v[222:225], v[10:13]
	s_setprio 0
	s_setprio 1
	v_mfma_f32_16x16x32_bf16 v[54:57], v[174:177], v[190:193], v[54:57]
	v_mfma_f32_16x16x32_bf16 v[46:49], v[182:185], v[190:193], v[46:49]
	v_mfma_f32_16x16x32_bf16 v[38:41], v[174:177], v[198:201], v[38:41]
	v_mfma_f32_16x16x32_bf16 v[30:33], v[182:185], v[198:201], v[30:33]
	v_mfma_f32_16x16x32_bf16 v[22:25], v[174:177], v[206:209], v[22:25]
	v_mfma_f32_16x16x32_bf16 v[14:17], v[182:185], v[206:209], v[14:17]
	v_mfma_f32_16x16x32_bf16 v[6:9], v[174:177], v[218:221], v[6:9]
	v_mfma_f32_16x16x32_bf16 v[2:5], v[182:185], v[218:221], v[2:5]
	v_mfma_f32_16x16x32_bf16 v[54:57], v[178:181], v[194:197], v[54:57]
	v_mfma_f32_16x16x32_bf16 v[46:49], v[186:189], v[194:197], v[46:49]
	v_mfma_f32_16x16x32_bf16 v[38:41], v[178:181], v[202:205], v[38:41]
	v_mfma_f32_16x16x32_bf16 v[30:33], v[186:189], v[202:205], v[30:33]
	v_mfma_f32_16x16x32_bf16 v[22:25], v[178:181], v[210:213], v[22:25]
	v_mfma_f32_16x16x32_bf16 v[14:17], v[186:189], v[210:213], v[14:17]
	v_mfma_f32_16x16x32_bf16 v[6:9], v[178:181], v[222:225], v[6:9]
	v_mfma_f32_16x16x32_bf16 v[2:5], v[186:189], v[222:225], v[2:5]
	s_setprio 0
	s_barrier
	s_mov_b32 m0, s25
	s_nop 0
	global_load_lds_dwordx4 v[226:227], off
	s_mov_b32 m0, s40
	s_nop 0
	global_load_lds_dwordx4 v[228:229], off
	s_add_i32 s54, 0, 0x18000
	v_add_u32_e32 v150, s54, v151
	s_add_i32 s55, 0, 0x1c000
	ds_read_b128 v[146:149], v150
	ds_read_b128 v[158:161], v150 offset:1024
	ds_read_b128 v[162:165], v150 offset:2048
	ds_read_b128 v[166:169], v150 offset:3072
	v_add_u32_e32 v150, s55, v151
	ds_read_b128 v[174:177], v150
	ds_read_b128 v[178:181], v150 offset:1024
	ds_read_b128 v[182:185], v150 offset:2048
	ds_read_b128 v[186:189], v150 offset:3072
	s_add_u32 s30, s30, 0x100000
	s_addc_u32 s31, s31, 0
	s_mov_b32 m0, s41
	v_lshl_add_u64 v[230:231], s[30:31], 0, v[136:137]
	ds_read_b128 v[190:193], v157 offset:32768
	ds_read_b128 v[194:197], v157 offset:33792
	ds_read_b128 v[198:201], v157 offset:34816
	ds_read_b128 v[202:205], v157 offset:35840
	ds_read_b128 v[206:209], v157 offset:36864
	ds_read_b128 v[210:213], v157 offset:37888
	ds_read_b128 v[218:221], v157 offset:38912
	ds_read_b128 v[222:225], v157 offset:39936
	global_load_lds_dwordx4 v[230:231], off
	v_lshl_add_u64 v[230:231], s[30:31], 0, v[132:133]
	s_mov_b32 m0, s42
	s_nop 0
	global_load_lds_dwordx4 v[230:231], off
	s_waitcnt vmcnt(8)
	s_waitcnt lgkmcnt(0)
	s_barrier
	s_setprio 1
	s_waitcnt lgkmcnt(0)
	v_mfma_f32_16x16x32_bf16 v[126:129], v[146:149], v[190:193], v[126:129]
	v_mfma_f32_16x16x32_bf16 v[122:125], v[162:165], v[190:193], v[122:125]
	v_mfma_f32_16x16x32_bf16 v[118:121], v[146:149], v[198:201], v[118:121]
	v_mfma_f32_16x16x32_bf16 v[114:117], v[162:165], v[198:201], v[114:117]
	v_mfma_f32_16x16x32_bf16 v[106:109], v[146:149], v[206:209], v[106:109]
	v_mfma_f32_16x16x32_bf16 v[98:101], v[162:165], v[206:209], v[98:101]
	v_mfma_f32_16x16x32_bf16 v[78:81], v[146:149], v[218:221], v[78:81]
	v_mfma_f32_16x16x32_bf16 v[74:77], v[162:165], v[218:221], v[74:77]
	v_mfma_f32_16x16x32_bf16 v[126:129], v[158:161], v[194:197], v[126:129]
	v_mfma_f32_16x16x32_bf16 v[122:125], v[166:169], v[194:197], v[122:125]
	v_mfma_f32_16x16x32_bf16 v[118:121], v[158:161], v[202:205], v[118:121]
	v_mfma_f32_16x16x32_bf16 v[114:117], v[166:169], v[202:205], v[114:117]
	v_mfma_f32_16x16x32_bf16 v[106:109], v[158:161], v[210:213], v[106:109]
	v_mfma_f32_16x16x32_bf16 v[98:101], v[166:169], v[210:213], v[98:101]
	v_mfma_f32_16x16x32_bf16 v[78:81], v[158:161], v[222:225], v[78:81]
	v_mfma_f32_16x16x32_bf16 v[74:77], v[166:169], v[222:225], v[74:77]
	s_setprio 0
	s_setprio 1
	v_mfma_f32_16x16x32_bf16 v[110:113], v[174:177], v[190:193], v[110:113]
	v_mfma_f32_16x16x32_bf16 v[102:105], v[182:185], v[190:193], v[102:105]
	v_mfma_f32_16x16x32_bf16 v[94:97], v[174:177], v[198:201], v[94:97]
	v_mfma_f32_16x16x32_bf16 v[90:93], v[182:185], v[198:201], v[90:93]
	v_mfma_f32_16x16x32_bf16 v[86:89], v[174:177], v[206:209], v[86:89]
	v_mfma_f32_16x16x32_bf16 v[82:85], v[182:185], v[206:209], v[82:85]
	v_mfma_f32_16x16x32_bf16 v[70:73], v[174:177], v[218:221], v[70:73]
	v_mfma_f32_16x16x32_bf16 v[66:69], v[182:185], v[218:221], v[66:69]
	v_mfma_f32_16x16x32_bf16 v[110:113], v[178:181], v[194:197], v[110:113]
	v_mfma_f32_16x16x32_bf16 v[102:105], v[186:189], v[194:197], v[102:105]
	v_mfma_f32_16x16x32_bf16 v[94:97], v[178:181], v[202:205], v[94:97]
	v_mfma_f32_16x16x32_bf16 v[90:93], v[186:189], v[202:205], v[90:93]
	v_mfma_f32_16x16x32_bf16 v[86:89], v[178:181], v[210:213], v[86:89]
	v_mfma_f32_16x16x32_bf16 v[82:85], v[186:189], v[210:213], v[82:85]
	v_mfma_f32_16x16x32_bf16 v[70:73], v[178:181], v[222:225], v[70:73]
	v_mfma_f32_16x16x32_bf16 v[66:69], v[186:189], v[222:225], v[66:69]
	s_setprio 0
	s_barrier
; #define PG8_STAGE(bufoff, gbase, voff) do { _Pragma("unroll") for (int _i = 0; _i < 2; ++_i) \
;         __builtin_amdgcn_global_load_lds((const unsigned*)((const char*)(gbase) + (voff)[_i]), (PG8_LAS unsigned*)(lds + (bufoff) + ldsw + _i * 8192), 16, 0, 0); } while (0)
; #define PG8_LDA(dst, b, h) do { _Pragma("unroll") for (int m = 0; m < 4; ++m) _Pragma("unroll") for (int k = 0; k < 2; ++k) dst[m][k] = *(const PG8_LAS bf16x8*)(lds + PG8_SA(b, h) + aoff + m * 2048 + k * 1024); } while (0)
; #define PG8_MMA(ai, bj, At, Bt) do { __builtin_amdgcn_s_setprio(1); _Pragma("unroll") for (int m = 0; m < 4; ++m) _Pragma("unroll") for (int n = 0; n < 2; ++n) _Pragma("unroll") for (int k = 0; k < 2; ++k) \
;         acc[ai][bj][m][n] = __builtin_amdgcn_mfma_f32_16x16x32_bf16(Bt[n][k], At[m][k], acc[ai][bj][m][n], 0, 0, 0); __builtin_amdgcn_s_setprio(0); } while (0)
; #define PG8_WAIT_V(n) asm volatile("s_waitcnt vmcnt(" #n ")" ::: "memory")
; #define PG8_WAIT_L(n) asm volatile("s_waitcnt lgkmcnt(" #n ")" ::: "memory")
; #define PG8_BAR __builtin_amdgcn_s_barrier()
; #define PG8_SCHED __builtin_amdgcn_sched_barrier(0)
; template <class Epi, class Sched, bool ALIGN_EPI = false, bool SP2 = false>
; __device__ __forceinline__ void gemm_phase(PG8_LAS unsigned char* lds, const Gemm g, const Sched& S, const Epi& E) {
;     ...
;             PG8_LDA(At, 1, 1); PG8_STAGE(PG8_SB(1, 0), b3, voffB); PG8_STAGE(PG8_SB(1, 1), b3 + hstepB, voffB); PG8_STAGE(PG8_SA(1, 0), a3, voffA);
;             PG8_WAIT_V(8); PG8_WAIT_L(0); PG8_BAR; PG8_MMA(1, 0, At, B0); PG8_MMA(1, 1, At, B1); PG8_BAR; PG8_SCHED;
	s_add_i32 s30, s54, s37
	v_lshl_add_u64 v[170:171], v[170:171], 0, s[12:13]
	s_mov_b32 m0, s30
	ds_read_b128 v[190:193], v157 offset:49152
	ds_read_b128 v[194:197], v157 offset:50176
	ds_read_b128 v[198:201], v157 offset:51200
	ds_read_b128 v[202:205], v157 offset:52224
	ds_read_b128 v[206:209], v157 offset:53248
	ds_read_b128 v[210:213], v157 offset:54272
	ds_read_b128 v[218:221], v157 offset:55296
	ds_read_b128 v[222:225], v157 offset:56320
	global_load_lds_dwordx4 v[170:171], off
	s_add_i32 m0, s30, 0x2000
	s_add_u32 s28, s28, 0x100080
	v_lshl_add_u64 v[170:171], v[214:215], 0, s[12:13]
	s_addc_u32 s29, s29, 0
	s_add_i32 s30, s55, s37
	global_load_lds_dwordx4 v[170:171], off
	v_lshl_add_u64 v[170:171], s[28:29], 0, v[134:135]
	s_mov_b32 m0, s30
	s_nop 0
	global_load_lds_dwordx4 v[170:171], off
	v_lshl_add_u64 v[170:171], s[28:29], 0, v[130:131]
	s_add_i32 m0, s30, 0x2000
	s_nop 0
	global_load_lds_dwordx4 v[170:171], off
	s_waitcnt vmcnt(6)
	s_waitcnt lgkmcnt(0)
	s_barrier
	s_setprio 1
	s_waitcnt lgkmcnt(0)
	v_mfma_f32_16x16x32_bf16 v[62:65], v[146:149], v[190:193], v[62:65]
	v_mfma_f32_16x16x32_bf16 v[58:61], v[162:165], v[190:193], v[58:61]
	v_mfma_f32_16x16x32_bf16 v[50:53], v[146:149], v[198:201], v[50:53]
	v_mfma_f32_16x16x32_bf16 v[42:45], v[162:165], v[198:201], v[42:45]
	v_mfma_f32_16x16x32_bf16 v[34:37], v[146:149], v[206:209], v[34:37]
	v_mfma_f32_16x16x32_bf16 v[26:29], v[162:165], v[206:209], v[26:29]
	v_mfma_f32_16x16x32_bf16 v[18:21], v[146:149], v[218:221], v[18:21]
	v_mfma_f32_16x16x32_bf16 v[10:13], v[162:165], v[218:221], v[10:13]
	v_mfma_f32_16x16x32_bf16 v[62:65], v[158:161], v[194:197], v[62:65]
	v_mfma_f32_16x16x32_bf16 v[58:61], v[166:169], v[194:197], v[58:61]
	v_mfma_f32_16x16x32_bf16 v[50:53], v[158:161], v[202:205], v[50:53]
	v_mfma_f32_16x16x32_bf16 v[42:45], v[166:169], v[202:205], v[42:45]
	v_mfma_f32_16x16x32_bf16 v[34:37], v[158:161], v[210:213], v[34:37]
	v_mfma_f32_16x16x32_bf16 v[26:29], v[166:169], v[210:213], v[26:29]
	v_mfma_f32_16x16x32_bf16 v[18:21], v[158:161], v[222:225], v[18:21]
	v_mfma_f32_16x16x32_bf16 v[10:13], v[166:169], v[222:225], v[10:13]
	s_setprio 0
	s_setprio 1
	v_mfma_f32_16x16x32_bf16 v[54:57], v[174:177], v[190:193], v[54:57]
	v_mfma_f32_16x16x32_bf16 v[46:49], v[182:185], v[190:193], v[46:49]
	v_mfma_f32_16x16x32_bf16 v[38:41], v[174:177], v[198:201], v[38:41]
	v_mfma_f32_16x16x32_bf16 v[30:33], v[182:185], v[198:201], v[30:33]
	v_mfma_f32_16x16x32_bf16 v[22:25], v[174:177], v[206:209], v[22:25]
	v_mfma_f32_16x16x32_bf16 v[14:17], v[182:185], v[206:209], v[14:17]
	v_mfma_f32_16x16x32_bf16 v[6:9], v[174:177], v[218:221], v[6:9]
	v_mfma_f32_16x16x32_bf16 v[2:5], v[182:185], v[218:221], v[2:5]
	v_mfma_f32_16x16x32_bf16 v[54:57], v[178:181], v[194:197], v[54:57]
	v_mfma_f32_16x16x32_bf16 v[46:49], v[186:189], v[194:197], v[46:49]
	v_mfma_f32_16x16x32_bf16 v[38:41], v[178:181], v[202:205], v[38:41]
	v_mfma_f32_16x16x32_bf16 v[30:33], v[186:189], v[202:205], v[30:33]
	v_mfma_f32_16x16x32_bf16 v[22:25], v[178:181], v[210:213], v[22:25]
	v_mfma_f32_16x16x32_bf16 v[14:17], v[186:189], v[210:213], v[14:17]
	v_mfma_f32_16x16x32_bf16 v[6:9], v[178:181], v[222:225], v[6:9]
	v_mfma_f32_16x16x32_bf16 v[2:5], v[186:189], v[222:225], v[2:5]
	s_setprio 0
	s_barrier
	v_lshl_add_u64 v[170:171], v[226:227], 0, s[12:13]
	s_mov_b32 m0, s43
	s_nop 0
	global_load_lds_dwordx4 v[170:171], off
	v_lshl_add_u64 v[170:171], v[228:229], 0, s[12:13]
	s_mov_b32 m0, s44
	s_nop 0
	global_load_lds_dwordx4 v[170:171], off
	s_add_i32 s53, s53, 2
	s_add_u32 s26, s26, 0x100
	s_addc_u32 s27, s27, 0
	s_add_u32 s51, s51, 0x100
	s_addc_u32 s52, s52, 0
	s_cmp_gt_u32 s53, 61
	s_cbranch_scc0 .LBB0_443
	s_and_b64 vcc, exec, s[14:15]
	s_cbranch_vccz .LBB0_446
	s_barrier

; #define PG8_STAGE(bufoff, gbase, voff) do { _Pragma("unroll") for (int _i = 0; _i < 2; ++_i) \
;         __builtin_amdgcn_global_load_lds((const unsigned*)((const char*)(gbase) + (voff)[_i]), (PG8_LAS unsigned*)(lds + (bufoff) + ldsw + _i * 8192), 16, 0, 0); } while (0)
; #define PG8_LDA(dst, b, h) do { _Pragma("unroll") for (int m = 0; m < 4; ++m) _Pragma("unroll") for (int k = 0; k < 2; ++k) dst[m][k] = *(const PG8_LAS bf16x8*)(lds + PG8_SA(b, h) + aoff + m * 2048 + k * 1024); } while (0)
; #define PG8_LDB(dst, b, h) do { _Pragma("unroll") for (int n = 0; n < 2; ++n) _Pragma("unroll") for (int k = 0; k < 2; ++k) dst[n][k] = *(const PG8_LAS bf16x8*)(lds + PG8_SB(b, h) + boff + n * 2048 + k * 1024); } while (0)
; #define PG8_MMA(ai, bj, At, Bt) do { __builtin_amdgcn_s_setprio(1); _Pragma("unroll") for (int m = 0; m < 4; ++m) _Pragma("unroll") for (int n = 0; n < 2; ++n) _Pragma("unroll") for (int k = 0; k < 2; ++k) \
;         acc[ai][bj][m][n] = __builtin_amdgcn_mfma_f32_16x16x32_bf16(Bt[n][k], At[m][k], acc[ai][bj][m][n], 0, 0, 0); __builtin_amdgcn_s_setprio(0); } while (0)
; #define PG8_WAIT_V(n) asm volatile("s_waitcnt vmcnt(" #n ")" ::: "memory")
; #define PG8_WAIT_L(n) asm volatile("s_waitcnt lgkmcnt(" #n ")" ::: "memory")
; #define PG8_BAR __builtin_amdgcn_s_barrier()
; #define PG8_SCHED __builtin_amdgcn_sched_barrier(0)
; template <class Epi, class Sched, bool ALIGN_EPI = false, bool SP2 = false>
; __device__ __forceinline__ void gemm_phase(PG8_LAS unsigned char* lds, const Gemm g, const Sched& S, const Epi& E) {
;     ...
;         for (int t = 0; t < nt; t += 2) {
;             const bool last = (t == nt - 2);
;             const char* a1 = cA + (size_t)(t + 1) * kstep;
;             const char* a2 = last ? nA : cA + (size_t)(t + 2) * kstep; const char* b2 = last ? nB : cB + (size_t)(t + 2) * kstep;
;             const char* a3 = a2 + kstep; const char* b3 = b2 + kstep;
;             if (last && has_next) S.a_ready(nxt);
;             if constexpr (SP2) {
;             PG8_LDB(B0, 0, 0); PG8_LDB(B1, 0, 1); PG8_SCHED; PG8_LDA(At, 0, 0); PG8_STAGE(PG8_SA(1, 1), a1 + hstepA, voffA);
;             PG8_WAIT_V(8); PG8_WAIT_L(0); PG8_BAR; PG8_MMA(0, 0, At, B0); PG8_MMA(0, 1, At, B1); PG8_BAR; PG8_SCHED;
;             PG8_LDA(At, 0, 1); PG8_STAGE(PG8_SB(0, 0), b2, voffB); PG8_STAGE(PG8_SB(0, 1), b2 + hstepB, voffB); PG8_STAGE(PG8_SA(0, 0), a2, voffA);
.LBB0_966:
	ds_read_b128 v[154:157], v150
	ds_read_b128 v[158:161], v150 offset:1024
	ds_read_b128 v[162:165], v150 offset:2048
	ds_read_b128 v[166:169], v150 offset:3072
	ds_read_b128 v[170:173], v151
	ds_read_b128 v[174:177], v151 offset:1024
	ds_read_b128 v[178:181], v151 offset:2048
	ds_read_b128 v[182:185], v151 offset:3072
	s_add_u32 s34, s30, 0xfff00080
	s_addc_u32 s35, s31, -1
	s_cmp_eq_u32 s61, 60
	s_cselect_b32 s37, s23, s35
	s_cselect_b32 s36, s57, s34
	s_cselect_b32 s35, s21, s60
	s_cselect_b32 s34, s58, s59
	v_lshl_add_u64 v[146:147], s[30:31], 0, v[138:139]
	s_add_i32 m0, s29, 0xc000
	ds_read_b128 v[186:189], v152
	ds_read_b128 v[190:193], v152 offset:1024
	ds_read_b128 v[194:197], v152 offset:2048
	ds_read_b128 v[198:201], v152 offset:3072
	ds_read_b128 v[202:205], v152 offset:4096
	ds_read_b128 v[206:209], v152 offset:5120
	ds_read_b128 v[210:213], v152 offset:6144
	ds_read_b128 v[218:221], v152 offset:7168
	global_load_lds_dwordx4 v[146:147], off
	v_lshl_add_u64 v[146:147], s[30:31], 0, v[140:141]
	s_add_i32 m0, s29, 0xe000
	s_nop 0
	global_load_lds_dwordx4 v[146:147], off
	s_waitcnt vmcnt(8)
	s_waitcnt lgkmcnt(0)
	s_barrier
	s_setprio 1
	s_waitcnt lgkmcnt(0)
	v_mfma_f32_16x16x32_bf16 v[126:129], v[154:157], v[186:189], v[126:129]
	v_mfma_f32_16x16x32_bf16 v[122:125], v[162:165], v[186:189], v[122:125]
	v_mfma_f32_16x16x32_bf16 v[114:117], v[154:157], v[194:197], v[114:117]
	v_mfma_f32_16x16x32_bf16 v[106:109], v[162:165], v[194:197], v[106:109]
	v_mfma_f32_16x16x32_bf16 v[98:101], v[154:157], v[202:205], v[98:101]
	v_mfma_f32_16x16x32_bf16 v[90:93], v[162:165], v[202:205], v[90:93]
	v_mfma_f32_16x16x32_bf16 v[82:85], v[154:157], v[210:213], v[82:85]
	v_mfma_f32_16x16x32_bf16 v[74:77], v[162:165], v[210:213], v[74:77]
	v_mfma_f32_16x16x32_bf16 v[126:129], v[158:161], v[190:193], v[126:129]
	v_mfma_f32_16x16x32_bf16 v[122:125], v[166:169], v[190:193], v[122:125]
	v_mfma_f32_16x16x32_bf16 v[114:117], v[158:161], v[198:201], v[114:117]
	v_mfma_f32_16x16x32_bf16 v[106:109], v[166:169], v[198:201], v[106:109]
	v_mfma_f32_16x16x32_bf16 v[98:101], v[158:161], v[206:209], v[98:101]
	v_mfma_f32_16x16x32_bf16 v[90:93], v[166:169], v[206:209], v[90:93]
	v_mfma_f32_16x16x32_bf16 v[82:85], v[158:161], v[218:221], v[82:85]
	v_mfma_f32_16x16x32_bf16 v[74:77], v[166:169], v[218:221], v[74:77]
	s_setprio 0
	s_setprio 1
	v_mfma_f32_16x16x32_bf16 v[118:121], v[170:173], v[186:189], v[118:121]
	v_mfma_f32_16x16x32_bf16 v[110:113], v[178:181], v[186:189], v[110:113]
	v_mfma_f32_16x16x32_bf16 v[102:105], v[170:173], v[194:197], v[102:105]
	v_mfma_f32_16x16x32_bf16 v[94:97], v[178:181], v[194:197], v[94:97]
	v_mfma_f32_16x16x32_bf16 v[86:89], v[170:173], v[202:205], v[86:89]
	v_mfma_f32_16x16x32_bf16 v[78:81], v[178:181], v[202:205], v[78:81]
	v_mfma_f32_16x16x32_bf16 v[70:73], v[170:173], v[210:213], v[70:73]
	v_mfma_f32_16x16x32_bf16 v[66:69], v[178:181], v[210:213], v[66:69]
	v_mfma_f32_16x16x32_bf16 v[118:121], v[174:177], v[190:193], v[118:121]
	v_mfma_f32_16x16x32_bf16 v[110:113], v[182:185], v[190:193], v[110:113]
	v_mfma_f32_16x16x32_bf16 v[102:105], v[174:177], v[198:201], v[102:105]
	v_mfma_f32_16x16x32_bf16 v[94:97], v[182:185], v[198:201], v[94:97]
	v_mfma_f32_16x16x32_bf16 v[86:89], v[174:177], v[206:209], v[86:89]
	v_mfma_f32_16x16x32_bf16 v[78:81], v[182:185], v[206:209], v[78:81]
	v_mfma_f32_16x16x32_bf16 v[70:73], v[174:177], v[218:221], v[70:73]
	v_mfma_f32_16x16x32_bf16 v[66:69], v[182:185], v[218:221], v[66:69]
	s_setprio 0
	s_barrier
	s_add_i32 s62, s50, s42
	v_lshl_add_u64 v[146:147], s[34:35], 0, v[132:133]
	s_mov_b32 m0, s62
	ds_read_b128 v[186:189], v152 offset:16384
	ds_read_b128 v[190:193], v152 offset:17408
	ds_read_b128 v[194:197], v152 offset:18432
	ds_read_b128 v[198:201], v152 offset:19456
	ds_read_b128 v[202:205], v152 offset:20480
	ds_read_b128 v[206:209], v152 offset:21504
	ds_read_b128 v[210:213], v152 offset:22528
	ds_read_b128 v[218:221], v152 offset:23552
	global_load_lds_dwordx4 v[146:147], off
	s_add_i32 m0, s62, 0x2000
	s_add_u32 s62, s34, 0x100000
	v_lshl_add_u64 v[214:215], s[34:35], 0, v[136:137]
	s_addc_u32 s63, s35, 0
	s_add_i32 s64, s51, s42
	global_load_lds_dwordx4 v[214:215], off
	v_lshl_add_u64 v[222:223], s[62:63], 0, v[132:133]
	s_mov_b32 m0, s64
	v_lshl_add_u64 v[224:225], s[36:37], 0, v[134:135]
	global_load_lds_dwordx4 v[222:223], off
	v_lshl_add_u64 v[222:223], s[62:63], 0, v[136:137]
	s_add_i32 m0, s64, 0x2000
	s_nop 0
	global_load_lds_dwordx4 v[222:223], off
	v_lshl_add_u64 v[222:223], s[36:37], 0, v[130:131]
	s_waitcnt vmcnt(6)
	s_waitcnt lgkmcnt(0)
	s_barrier
; #define PG8_STAGE(bufoff, gbase, voff) do { _Pragma("unroll") for (int _i = 0; _i < 2; ++_i) \
;         __builtin_amdgcn_global_load_lds((const unsigned*)((const char*)(gbase) + (voff)[_i]), (PG8_LAS unsigned*)(lds + (bufoff) + ldsw + _i * 8192), 16, 0, 0); } while (0)
; #define PG8_LDA(dst, b, h) do { _Pragma("unroll") for (int m = 0; m < 4; ++m) _Pragma("unroll") for (int k = 0; k < 2; ++k) dst[m][k] = *(const PG8_LAS bf16x8*)(lds + PG8_SA(b, h) + aoff + m * 2048 + k * 1024); } while (0)
; #define PG8_LDB(dst, b, h) do { _Pragma("unroll") for (int n = 0; n < 2; ++n) _Pragma("unroll") for (int k = 0; k < 2; ++k) dst[n][k] = *(const PG8_LAS bf16x8*)(lds + PG8_SB(b, h) + boff + n * 2048 + k * 1024); } while (0)
; #define PG8_MMA(ai, bj, At, Bt) do { __builtin_amdgcn_s_setprio(1); _Pragma("unroll") for (int m = 0; m < 4; ++m) _Pragma("unroll") for (int n = 0; n < 2; ++n) _Pragma("unroll") for (int k = 0; k < 2; ++k) \
;         acc[ai][bj][m][n] = __builtin_amdgcn_mfma_f32_16x16x32_bf16(Bt[n][k], At[m][k], acc[ai][bj][m][n], 0, 0, 0); __builtin_amdgcn_s_setprio(0); } while (0)
; #define PG8_WAIT_V(n) asm volatile("s_waitcnt vmcnt(" #n ")" ::: "memory")
; #define PG8_WAIT_L(n) asm volatile("s_waitcnt lgkmcnt(" #n ")" ::: "memory")
; #define PG8_BAR __builtin_amdgcn_s_barrier()
; #define PG8_SCHED __builtin_amdgcn_sched_barrier(0)
; template <class Epi, class Sched, bool ALIGN_EPI = false, bool SP2 = false>
; __device__ __forceinline__ void gemm_phase(PG8_LAS unsigned char* lds, const Gemm g, const Sched& S, const Epi& E) {
;     ...
;             PG8_WAIT_V(8); PG8_WAIT_L(0); PG8_BAR; PG8_MMA(1, 0, At, B0); PG8_MMA(1, 1, At, B1); PG8_BAR; PG8_SCHED;
;             PG8_LDB(B0, 1, 0); PG8_LDB(B1, 1, 1); PG8_SCHED; PG8_LDA(At, 1, 0); PG8_STAGE(PG8_SA(0, 1), a2 + hstepA, voffA);
;             PG8_WAIT_V(8); PG8_WAIT_L(0); PG8_BAR; PG8_MMA(0, 0, At, B0); PG8_MMA(0, 1, At, B1); PG8_BAR; PG8_SCHED;
;             PG8_LDA(At, 1, 1); PG8_STAGE(PG8_SB(1, 0), b3, voffB); PG8_STAGE(PG8_SB(1, 1), b3 + hstepB, voffB); PG8_STAGE(PG8_SA(1, 0), a3, voffA);
	s_setprio 1
	s_waitcnt lgkmcnt(0)
	v_mfma_f32_16x16x32_bf16 v[62:65], v[154:157], v[186:189], v[62:65]
	v_mfma_f32_16x16x32_bf16 v[58:61], v[162:165], v[186:189], v[58:61]
	v_mfma_f32_16x16x32_bf16 v[50:53], v[154:157], v[194:197], v[50:53]
	v_mfma_f32_16x16x32_bf16 v[42:45], v[162:165], v[194:197], v[42:45]
	v_mfma_f32_16x16x32_bf16 v[34:37], v[154:157], v[202:205], v[34:37]
	v_mfma_f32_16x16x32_bf16 v[26:29], v[162:165], v[202:205], v[26:29]
	v_mfma_f32_16x16x32_bf16 v[18:21], v[154:157], v[210:213], v[18:21]
	v_mfma_f32_16x16x32_bf16 v[10:13], v[162:165], v[210:213], v[10:13]
	v_mfma_f32_16x16x32_bf16 v[62:65], v[158:161], v[190:193], v[62:65]
	v_mfma_f32_16x16x32_bf16 v[58:61], v[166:169], v[190:193], v[58:61]
	v_mfma_f32_16x16x32_bf16 v[50:53], v[158:161], v[198:201], v[50:53]
	v_mfma_f32_16x16x32_bf16 v[42:45], v[166:169], v[198:201], v[42:45]
	v_mfma_f32_16x16x32_bf16 v[34:37], v[158:161], v[206:209], v[34:37]
	v_mfma_f32_16x16x32_bf16 v[26:29], v[166:169], v[206:209], v[26:29]
	v_mfma_f32_16x16x32_bf16 v[18:21], v[158:161], v[218:221], v[18:21]
	v_mfma_f32_16x16x32_bf16 v[10:13], v[166:169], v[218:221], v[10:13]
	s_setprio 0
	s_setprio 1
	v_mfma_f32_16x16x32_bf16 v[54:57], v[170:173], v[186:189], v[54:57]
	v_mfma_f32_16x16x32_bf16 v[46:49], v[178:181], v[186:189], v[46:49]
	v_mfma_f32_16x16x32_bf16 v[38:41], v[170:173], v[194:197], v[38:41]
	v_mfma_f32_16x16x32_bf16 v[30:33], v[178:181], v[194:197], v[30:33]
	v_mfma_f32_16x16x32_bf16 v[22:25], v[170:173], v[202:205], v[22:25]
	v_mfma_f32_16x16x32_bf16 v[14:17], v[178:181], v[202:205], v[14:17]
	v_mfma_f32_16x16x32_bf16 v[6:9], v[170:173], v[210:213], v[6:9]
	v_mfma_f32_16x16x32_bf16 v[2:5], v[178:181], v[210:213], v[2:5]
	v_mfma_f32_16x16x32_bf16 v[54:57], v[174:177], v[190:193], v[54:57]
	v_mfma_f32_16x16x32_bf16 v[46:49], v[182:185], v[190:193], v[46:49]
	v_mfma_f32_16x16x32_bf16 v[38:41], v[174:177], v[198:201], v[38:41]
	v_mfma_f32_16x16x32_bf16 v[30:33], v[182:185], v[198:201], v[30:33]
	v_mfma_f32_16x16x32_bf16 v[22:25], v[174:177], v[206:209], v[22:25]
	v_mfma_f32_16x16x32_bf16 v[14:17], v[182:185], v[206:209], v[14:17]
	v_mfma_f32_16x16x32_bf16 v[6:9], v[174:177], v[218:221], v[6:9]
	v_mfma_f32_16x16x32_bf16 v[2:5], v[182:185], v[218:221], v[2:5]
	s_setprio 0
	s_barrier
	s_mov_b32 m0, s29
	s_nop 0
	global_load_lds_dwordx4 v[222:223], off
	s_mov_b32 m0, s43
	s_nop 0
	global_load_lds_dwordx4 v[224:225], off
	s_add_i32 s62, 0, 0x18000
	v_add_u32_e32 v153, s62, v148
	s_add_i32 s63, 0, 0x1c000
	ds_read_b128 v[154:157], v153
	ds_read_b128 v[158:161], v153 offset:1024
	ds_read_b128 v[162:165], v153 offset:2048
	ds_read_b128 v[166:169], v153 offset:3072
	v_add_u32_e32 v153, s63, v148
	ds_read_b128 v[170:173], v153
	ds_read_b128 v[174:177], v153 offset:1024
	ds_read_b128 v[178:181], v153 offset:2048
	ds_read_b128 v[182:185], v153 offset:3072
	s_add_u32 s36, s36, 0x100000
	s_addc_u32 s37, s37, 0
	s_mov_b32 m0, s44
	v_lshl_add_u64 v[226:227], s[36:37], 0, v[130:131]
	ds_read_b128 v[186:189], v152 offset:32768
	ds_read_b128 v[190:193], v152 offset:33792
	ds_read_b128 v[194:197], v152 offset:34816
	ds_read_b128 v[198:201], v152 offset:35840
	ds_read_b128 v[202:205], v152 offset:36864
	ds_read_b128 v[206:209], v152 offset:37888
	ds_read_b128 v[210:213], v152 offset:38912
	ds_read_b128 v[218:221], v152 offset:39936
	global_load_lds_dwordx4 v[226:227], off
	v_lshl_add_u64 v[226:227], s[36:37], 0, v[134:135]
	s_mov_b32 m0, s45
	s_nop 0
	global_load_lds_dwordx4 v[226:227], off
	s_waitcnt vmcnt(8)
	s_waitcnt lgkmcnt(0)
	s_barrier
	s_setprio 1
	s_waitcnt lgkmcnt(0)
	v_mfma_f32_16x16x32_bf16 v[126:129], v[154:157], v[186:189], v[126:129]
	v_mfma_f32_16x16x32_bf16 v[122:125], v[162:165], v[186:189], v[122:125]
	v_mfma_f32_16x16x32_bf16 v[114:117], v[154:157], v[194:197], v[114:117]
	v_mfma_f32_16x16x32_bf16 v[106:109], v[162:165], v[194:197], v[106:109]
	v_mfma_f32_16x16x32_bf16 v[98:101], v[154:157], v[202:205], v[98:101]
	v_mfma_f32_16x16x32_bf16 v[90:93], v[162:165], v[202:205], v[90:93]
	v_mfma_f32_16x16x32_bf16 v[82:85], v[154:157], v[210:213], v[82:85]
	v_mfma_f32_16x16x32_bf16 v[74:77], v[162:165], v[210:213], v[74:77]
	v_mfma_f32_16x16x32_bf16 v[126:129], v[158:161], v[190:193], v[126:129]
	v_mfma_f32_16x16x32_bf16 v[122:125], v[166:169], v[190:193], v[122:125]
	v_mfma_f32_16x16x32_bf16 v[114:117], v[158:161], v[198:201], v[114:117]
	v_mfma_f32_16x16x32_bf16 v[106:109], v[166:169], v[198:201], v[106:109]
	v_mfma_f32_16x16x32_bf16 v[98:101], v[158:161], v[206:209], v[98:101]
	v_mfma_f32_16x16x32_bf16 v[90:93], v[166:169], v[206:209], v[90:93]
	v_mfma_f32_16x16x32_bf16 v[82:85], v[158:161], v[218:221], v[82:85]
	v_mfma_f32_16x16x32_bf16 v[74:77], v[166:169], v[218:221], v[74:77]
	s_setprio 0
	s_setprio 1
	v_mfma_f32_16x16x32_bf16 v[118:121], v[170:173], v[186:189], v[118:121]
	v_mfma_f32_16x16x32_bf16 v[110:113], v[178:181], v[186:189], v[110:113]
	v_mfma_f32_16x16x32_bf16 v[102:105], v[170:173], v[194:197], v[102:105]
	v_mfma_f32_16x16x32_bf16 v[94:97], v[178:181], v[194:197], v[94:97]
	v_mfma_f32_16x16x32_bf16 v[86:89], v[170:173], v[202:205], v[86:89]
	v_mfma_f32_16x16x32_bf16 v[78:81], v[178:181], v[202:205], v[78:81]
	v_mfma_f32_16x16x32_bf16 v[70:73], v[170:173], v[210:213], v[70:73]
	v_mfma_f32_16x16x32_bf16 v[66:69], v[178:181], v[210:213], v[66:69]
	v_mfma_f32_16x16x32_bf16 v[118:121], v[174:177], v[190:193], v[118:121]
	v_mfma_f32_16x16x32_bf16 v[110:113], v[182:185], v[190:193], v[110:113]
	v_mfma_f32_16x16x32_bf16 v[102:105], v[174:177], v[198:201], v[102:105]
	v_mfma_f32_16x16x32_bf16 v[94:97], v[182:185], v[198:201], v[94:97]
	v_mfma_f32_16x16x32_bf16 v[86:89], v[174:177], v[206:209], v[86:89]
	v_mfma_f32_16x16x32_bf16 v[78:81], v[182:185], v[206:209], v[78:81]
	v_mfma_f32_16x16x32_bf16 v[70:73], v[174:177], v[218:221], v[70:73]
	v_mfma_f32_16x16x32_bf16 v[66:69], v[182:185], v[218:221], v[66:69]
	s_setprio 0
	s_barrier
; #define PG8_STAGE(bufoff, gbase, voff) do { _Pragma("unroll") for (int _i = 0; _i < 2; ++_i) \
;         __builtin_amdgcn_global_load_lds((const unsigned*)((const char*)(gbase) + (voff)[_i]), (PG8_LAS unsigned*)(lds + (bufoff) + ldsw + _i * 8192), 16, 0, 0); } while (0)
; #define PG8_LDA(dst, b, h) do { _Pragma("unroll") for (int m = 0; m < 4; ++m) _Pragma("unroll") for (int k = 0; k < 2; ++k) dst[m][k] = *(const PG8_LAS bf16x8*)(lds + PG8_SA(b, h) + aoff + m * 2048 + k * 1024); } while (0)
; #define PG8_MMA(ai, bj, At, Bt) do { __builtin_amdgcn_s_setprio(1); _Pragma("unroll") for (int m = 0; m < 4; ++m) _Pragma("unroll") for (int n = 0; n < 2; ++n) _Pragma("unroll") for (int k = 0; k < 2; ++k) \
;         acc[ai][bj][m][n] = __builtin_amdgcn_mfma_f32_16x16x32_bf16(Bt[n][k], At[m][k], acc[ai][bj][m][n], 0, 0, 0); __builtin_amdgcn_s_setprio(0); } while (0)
; #define PG8_WAIT_V(n) asm volatile("s_waitcnt vmcnt(" #n ")" ::: "memory")
; #define PG8_WAIT_L(n) asm volatile("s_waitcnt lgkmcnt(" #n ")" ::: "memory")
; #define PG8_BAR __builtin_amdgcn_s_barrier()
; #define PG8_SCHED __builtin_amdgcn_sched_barrier(0)
; template <class Epi, class Sched, bool ALIGN_EPI = false, bool SP2 = false>
; __device__ __forceinline__ void gemm_phase(PG8_LAS unsigned char* lds, const Gemm g, const Sched& S, const Epi& E) {
;     ...
;             PG8_LDA(At, 1, 1); PG8_STAGE(PG8_SB(1, 0), b3, voffB); PG8_STAGE(PG8_SB(1, 1), b3 + hstepB, voffB); PG8_STAGE(PG8_SA(1, 0), a3, voffA);
;             PG8_WAIT_V(8); PG8_WAIT_L(0); PG8_BAR; PG8_MMA(1, 0, At, B0); PG8_MMA(1, 1, At, B1); PG8_BAR; PG8_SCHED;
	s_add_i32 s36, s62, s42
	v_lshl_add_u64 v[146:147], v[146:147], 0, s[10:11]
	s_mov_b32 m0, s36
	ds_read_b128 v[186:189], v152 offset:49152
	ds_read_b128 v[190:193], v152 offset:50176
	ds_read_b128 v[194:197], v152 offset:51200
	ds_read_b128 v[198:201], v152 offset:52224
	ds_read_b128 v[202:205], v152 offset:53248
	ds_read_b128 v[206:209], v152 offset:54272
	ds_read_b128 v[210:213], v152 offset:55296
	ds_read_b128 v[218:221], v152 offset:56320
	global_load_lds_dwordx4 v[146:147], off
	s_add_i32 m0, s36, 0x2000
	s_add_u32 s34, s34, 0x100080
	v_lshl_add_u64 v[146:147], v[214:215], 0, s[10:11]
	s_addc_u32 s35, s35, 0
	s_add_i32 s36, s63, s42
	global_load_lds_dwordx4 v[146:147], off
	v_lshl_add_u64 v[146:147], s[34:35], 0, v[132:133]
	s_mov_b32 m0, s36
	s_nop 0
	global_load_lds_dwordx4 v[146:147], off
	v_lshl_add_u64 v[146:147], s[34:35], 0, v[136:137]
	s_add_i32 m0, s36, 0x2000
	s_nop 0
	global_load_lds_dwordx4 v[146:147], off
	s_waitcnt vmcnt(6)
	s_waitcnt lgkmcnt(0)
	s_barrier
	s_setprio 1
	s_waitcnt lgkmcnt(0)
	v_mfma_f32_16x16x32_bf16 v[62:65], v[154:157], v[186:189], v[62:65]
	v_mfma_f32_16x16x32_bf16 v[58:61], v[162:165], v[186:189], v[58:61]
	v_mfma_f32_16x16x32_bf16 v[50:53], v[154:157], v[194:197], v[50:53]
	v_mfma_f32_16x16x32_bf16 v[42:45], v[162:165], v[194:197], v[42:45]
	v_mfma_f32_16x16x32_bf16 v[34:37], v[154:157], v[202:205], v[34:37]
	v_mfma_f32_16x16x32_bf16 v[26:29], v[162:165], v[202:205], v[26:29]
	v_mfma_f32_16x16x32_bf16 v[18:21], v[154:157], v[210:213], v[18:21]
	v_mfma_f32_16x16x32_bf16 v[10:13], v[162:165], v[210:213], v[10:13]
	v_mfma_f32_16x16x32_bf16 v[62:65], v[158:161], v[190:193], v[62:65]
	v_mfma_f32_16x16x32_bf16 v[58:61], v[166:169], v[190:193], v[58:61]
	v_mfma_f32_16x16x32_bf16 v[50:53], v[158:161], v[198:201], v[50:53]
	v_mfma_f32_16x16x32_bf16 v[42:45], v[166:169], v[198:201], v[42:45]
	v_mfma_f32_16x16x32_bf16 v[34:37], v[158:161], v[206:209], v[34:37]
	v_mfma_f32_16x16x32_bf16 v[26:29], v[166:169], v[206:209], v[26:29]
	v_mfma_f32_16x16x32_bf16 v[18:21], v[158:161], v[218:221], v[18:21]
	v_mfma_f32_16x16x32_bf16 v[10:13], v[166:169], v[218:221], v[10:13]
	s_setprio 0
	s_setprio 1
	v_mfma_f32_16x16x32_bf16 v[54:57], v[170:173], v[186:189], v[54:57]
	v_mfma_f32_16x16x32_bf16 v[46:49], v[178:181], v[186:189], v[46:49]
	v_mfma_f32_16x16x32_bf16 v[38:41], v[170:173], v[194:197], v[38:41]
	v_mfma_f32_16x16x32_bf16 v[30:33], v[178:181], v[194:197], v[30:33]
	v_mfma_f32_16x16x32_bf16 v[22:25], v[170:173], v[202:205], v[22:25]
	v_mfma_f32_16x16x32_bf16 v[14:17], v[178:181], v[202:205], v[14:17]
	v_mfma_f32_16x16x32_bf16 v[6:9], v[170:173], v[210:213], v[6:9]
	v_mfma_f32_16x16x32_bf16 v[2:5], v[178:181], v[210:213], v[2:5]
	v_mfma_f32_16x16x32_bf16 v[54:57], v[174:177], v[190:193], v[54:57]
	v_mfma_f32_16x16x32_bf16 v[46:49], v[182:185], v[190:193], v[46:49]
	v_mfma_f32_16x16x32_bf16 v[38:41], v[174:177], v[198:201], v[38:41]
	v_mfma_f32_16x16x32_bf16 v[30:33], v[182:185], v[198:201], v[30:33]
	v_mfma_f32_16x16x32_bf16 v[22:25], v[174:177], v[206:209], v[22:25]
	v_mfma_f32_16x16x32_bf16 v[14:17], v[182:185], v[206:209], v[14:17]
	v_mfma_f32_16x16x32_bf16 v[6:9], v[174:177], v[218:221], v[6:9]
	v_mfma_f32_16x16x32_bf16 v[2:5], v[182:185], v[218:221], v[2:5]
	s_setprio 0
	s_barrier
	v_lshl_add_u64 v[146:147], v[222:223], 0, s[10:11]
	s_mov_b32 m0, s47
	s_nop 0
	global_load_lds_dwordx4 v[146:147], off
	v_lshl_add_u64 v[146:147], v[224:225], 0, s[10:11]
	s_mov_b32 m0, s48
	s_nop 0
	global_load_lds_dwordx4 v[146:147], off
	s_add_i32 s61, s61, 2
	s_add_u32 s30, s30, 0x100
	s_addc_u32 s31, s31, 0
	s_add_u32 s59, s59, 0x100
	s_addc_u32 s60, s60, 0
	s_cmp_gt_u32 s61, 61
	s_cbranch_scc0 .LBB0_966
	s_and_b64 vcc, exec, s[12:13]
	s_cbranch_vccz .LBB0_969
	s_barrier

; #define PG8_STAGE(bufoff, gbase, voff) do { _Pragma("unroll") for (int _i = 0; _i < 2; ++_i) \
;         __builtin_amdgcn_global_load_lds((const unsigned*)((const char*)(gbase) + (voff)[_i]), (PG8_LAS unsigned*)(lds + (bufoff) + ldsw + _i * 8192), 16, 0, 0); } while (0)
; #define PG8_LDA(dst, b, h) do { _Pragma("unroll") for (int m = 0; m < 4; ++m) _Pragma("unroll") for (int k = 0; k < 2; ++k) dst[m][k] = *(const PG8_LAS bf16x8*)(lds + PG8_SA(b, h) + aoff + m * 2048 + k * 1024); } while (0)
; #define PG8_LDB(dst, b, h) do { _Pragma("unroll") for (int n = 0; n < 2; ++n) _Pragma("unroll") for (int k = 0; k < 2; ++k) dst[n][k] = *(const PG8_LAS bf16x8*)(lds + PG8_SB(b, h) + boff + n * 2048 + k * 1024); } while (0)
; #define PG8_MMA(ai, bj, At, Bt) do { __builtin_amdgcn_s_setprio(1); _Pragma("unroll") for (int m = 0; m < 4; ++m) _Pragma("unroll") for (int n = 0; n < 2; ++n) _Pragma("unroll") for (int k = 0; k < 2; ++k) \
;         acc[ai][bj][m][n] = __builtin_amdgcn_mfma_f32_16x16x32_bf16(Bt[n][k], At[m][k], acc[ai][bj][m][n], 0, 0, 0); __builtin_amdgcn_s_setprio(0); } while (0)
; #define PG8_WAIT_V(n) asm volatile("s_waitcnt vmcnt(" #n ")" ::: "memory")
; #define PG8_WAIT_L(n) asm volatile("s_waitcnt lgkmcnt(" #n ")" ::: "memory")
; #define PG8_BAR __builtin_amdgcn_s_barrier()
; #define PG8_SCHED __builtin_amdgcn_sched_barrier(0)
; template <class Epi, class Sched, bool ALIGN_EPI = false, bool SP2 = false>
; __device__ __forceinline__ void gemm_phase(PG8_LAS unsigned char* lds, const Gemm g, const Sched& S, const Epi& E) {
;     ...
;         for (int t = 0; t < nt; t += 2) {
;             const bool last = (t == nt - 2);
;             const char* a1 = cA + (size_t)(t + 1) * kstep;
;             const char* a2 = last ? nA : cA + (size_t)(t + 2) * kstep; const char* b2 = last ? nB : cB + (size_t)(t + 2) * kstep;
;             const char* a3 = a2 + kstep; const char* b3 = b2 + kstep;
;             if (last && has_next) S.a_ready(nxt);
;             if constexpr (SP2) {
;             PG8_LDB(B0, 0, 0); PG8_LDB(B1, 0, 1); PG8_SCHED; PG8_LDA(At, 0, 0); PG8_STAGE(PG8_SA(1, 1), a1 + hstepA, voffA);
;             PG8_WAIT_V(8); PG8_WAIT_L(0); PG8_BAR; PG8_MMA(0, 0, At, B0); PG8_MMA(0, 1, At, B1); PG8_BAR; PG8_SCHED;
;             PG8_LDA(At, 0, 1); PG8_STAGE(PG8_SB(0, 0), b2, voffB); PG8_STAGE(PG8_SB(0, 1), b2 + hstepB, voffB); PG8_STAGE(PG8_SA(0, 0), a2, voffA);
.LBB0_1097:
	ds_read_b128 v[156:159], v153
	ds_read_b128 v[160:163], v153 offset:1024
	ds_read_b128 v[164:167], v153 offset:2048
	ds_read_b128 v[168:171], v153 offset:3072
	ds_read_b128 v[172:175], v154
	ds_read_b128 v[176:179], v154 offset:1024
	ds_read_b128 v[180:183], v154 offset:2048
	ds_read_b128 v[184:187], v154 offset:3072
	s_add_u32 s36, s34, 0xfff00080
	s_addc_u32 s37, s35, -1
	s_cmp_eq_u32 s63, 60
	s_cselect_b32 s39, s25, s37
	s_cselect_b32 s38, s59, s36
	s_cselect_b32 s37, s23, s62
	s_cselect_b32 s36, s60, s61
	v_lshl_add_u64 v[148:149], s[34:35], 0, v[138:139]
	s_add_i32 m0, s31, 0xc000
	ds_read_b128 v[188:191], v155
	ds_read_b128 v[192:195], v155 offset:1024
	ds_read_b128 v[196:199], v155 offset:2048
	ds_read_b128 v[200:203], v155 offset:3072
	ds_read_b128 v[204:207], v155 offset:4096
	ds_read_b128 v[208:211], v155 offset:5120
	ds_read_b128 v[212:215], v155 offset:6144
	ds_read_b128 v[218:221], v155 offset:7168
	global_load_lds_dwordx4 v[148:149], off
	v_lshl_add_u64 v[148:149], s[34:35], 0, v[140:141]
	s_add_i32 m0, s31, 0xe000
	s_nop 0
	global_load_lds_dwordx4 v[148:149], off
	s_waitcnt vmcnt(8)
	s_waitcnt lgkmcnt(0)
	s_barrier
	s_setprio 1
	s_waitcnt lgkmcnt(0)
	v_mfma_f32_16x16x32_bf16 v[126:129], v[156:159], v[188:191], v[126:129]
	v_mfma_f32_16x16x32_bf16 v[122:125], v[164:167], v[188:191], v[122:125]
	v_mfma_f32_16x16x32_bf16 v[118:121], v[156:159], v[196:199], v[118:121]
	v_mfma_f32_16x16x32_bf16 v[114:117], v[164:167], v[196:199], v[114:117]
	v_mfma_f32_16x16x32_bf16 v[110:113], v[156:159], v[204:207], v[110:113]
	v_mfma_f32_16x16x32_bf16 v[102:105], v[164:167], v[204:207], v[102:105]
	v_mfma_f32_16x16x32_bf16 v[94:97], v[156:159], v[212:215], v[94:97]
	v_mfma_f32_16x16x32_bf16 v[74:77], v[164:167], v[212:215], v[74:77]
	v_mfma_f32_16x16x32_bf16 v[126:129], v[160:163], v[192:195], v[126:129]
	v_mfma_f32_16x16x32_bf16 v[122:125], v[168:171], v[192:195], v[122:125]
	v_mfma_f32_16x16x32_bf16 v[118:121], v[160:163], v[200:203], v[118:121]
	v_mfma_f32_16x16x32_bf16 v[114:117], v[168:171], v[200:203], v[114:117]
	v_mfma_f32_16x16x32_bf16 v[110:113], v[160:163], v[208:211], v[110:113]
	v_mfma_f32_16x16x32_bf16 v[102:105], v[168:171], v[208:211], v[102:105]
	v_mfma_f32_16x16x32_bf16 v[94:97], v[160:163], v[218:221], v[94:97]
	v_mfma_f32_16x16x32_bf16 v[74:77], v[168:171], v[218:221], v[74:77]
	s_setprio 0
	s_setprio 1
	v_mfma_f32_16x16x32_bf16 v[106:109], v[172:175], v[188:191], v[106:109]
	v_mfma_f32_16x16x32_bf16 v[98:101], v[180:183], v[188:191], v[98:101]
	v_mfma_f32_16x16x32_bf16 v[90:93], v[172:175], v[196:199], v[90:93]
	v_mfma_f32_16x16x32_bf16 v[86:89], v[180:183], v[196:199], v[86:89]
	v_mfma_f32_16x16x32_bf16 v[82:85], v[172:175], v[204:207], v[82:85]
	v_mfma_f32_16x16x32_bf16 v[78:81], v[180:183], v[204:207], v[78:81]
	v_mfma_f32_16x16x32_bf16 v[70:73], v[172:175], v[212:215], v[70:73]
	v_mfma_f32_16x16x32_bf16 v[66:69], v[180:183], v[212:215], v[66:69]
	v_mfma_f32_16x16x32_bf16 v[106:109], v[176:179], v[192:195], v[106:109]
	v_mfma_f32_16x16x32_bf16 v[98:101], v[184:187], v[192:195], v[98:101]
	v_mfma_f32_16x16x32_bf16 v[90:93], v[176:179], v[200:203], v[90:93]
	v_mfma_f32_16x16x32_bf16 v[86:89], v[184:187], v[200:203], v[86:89]
	v_mfma_f32_16x16x32_bf16 v[82:85], v[176:179], v[208:211], v[82:85]
	v_mfma_f32_16x16x32_bf16 v[78:81], v[184:187], v[208:211], v[78:81]
	v_mfma_f32_16x16x32_bf16 v[70:73], v[176:179], v[218:221], v[70:73]
	v_mfma_f32_16x16x32_bf16 v[66:69], v[184:187], v[218:221], v[66:69]
	s_setprio 0
	s_barrier
	s_add_i32 s64, s52, s44
	v_lshl_add_u64 v[148:149], s[36:37], 0, v[132:133]
	s_mov_b32 m0, s64
	ds_read_b128 v[188:191], v155 offset:16384
	ds_read_b128 v[192:195], v155 offset:17408
	ds_read_b128 v[196:199], v155 offset:18432
	ds_read_b128 v[200:203], v155 offset:19456
	ds_read_b128 v[204:207], v155 offset:20480
	ds_read_b128 v[208:211], v155 offset:21504
	ds_read_b128 v[212:215], v155 offset:22528
	ds_read_b128 v[218:221], v155 offset:23552
	global_load_lds_dwordx4 v[148:149], off
	s_add_i32 m0, s64, 0x2000
	s_add_u32 s64, s36, 0x100000
	v_lshl_add_u64 v[222:223], s[36:37], 0, v[136:137]
	s_addc_u32 s65, s37, 0
	s_add_i32 s66, s53, s44
	global_load_lds_dwordx4 v[222:223], off
	v_lshl_add_u64 v[224:225], s[64:65], 0, v[132:133]
	s_mov_b32 m0, s66
	v_lshl_add_u64 v[226:227], s[38:39], 0, v[134:135]
	global_load_lds_dwordx4 v[224:225], off
	v_lshl_add_u64 v[224:225], s[64:65], 0, v[136:137]
	s_add_i32 m0, s66, 0x2000
	s_nop 0
	global_load_lds_dwordx4 v[224:225], off
	v_lshl_add_u64 v[224:225], s[38:39], 0, v[130:131]
	s_waitcnt vmcnt(6)
	s_waitcnt lgkmcnt(0)
	s_barrier
; #define PG8_STAGE(bufoff, gbase, voff) do { _Pragma("unroll") for (int _i = 0; _i < 2; ++_i) \
;         __builtin_amdgcn_global_load_lds((const unsigned*)((const char*)(gbase) + (voff)[_i]), (PG8_LAS unsigned*)(lds + (bufoff) + ldsw + _i * 8192), 16, 0, 0); } while (0)
; #define PG8_LDA(dst, b, h) do { _Pragma("unroll") for (int m = 0; m < 4; ++m) _Pragma("unroll") for (int k = 0; k < 2; ++k) dst[m][k] = *(const PG8_LAS bf16x8*)(lds + PG8_SA(b, h) + aoff + m * 2048 + k * 1024); } while (0)
; #define PG8_LDB(dst, b, h) do { _Pragma("unroll") for (int n = 0; n < 2; ++n) _Pragma("unroll") for (int k = 0; k < 2; ++k) dst[n][k] = *(const PG8_LAS bf16x8*)(lds + PG8_SB(b, h) + boff + n * 2048 + k * 1024); } while (0)
; #define PG8_MMA(ai, bj, At, Bt) do { __builtin_amdgcn_s_setprio(1); _Pragma("unroll") for (int m = 0; m < 4; ++m) _Pragma("unroll") for (int n = 0; n < 2; ++n) _Pragma("unroll") for (int k = 0; k < 2; ++k) \
;         acc[ai][bj][m][n] = __builtin_amdgcn_mfma_f32_16x16x32_bf16(Bt[n][k], At[m][k], acc[ai][bj][m][n], 0, 0, 0); __builtin_amdgcn_s_setprio(0); } while (0)
; #define PG8_WAIT_V(n) asm volatile("s_waitcnt vmcnt(" #n ")" ::: "memory")
; #define PG8_WAIT_L(n) asm volatile("s_waitcnt lgkmcnt(" #n ")" ::: "memory")
; #define PG8_BAR __builtin_amdgcn_s_barrier()
; #define PG8_SCHED __builtin_amdgcn_sched_barrier(0)
; template <class Epi, class Sched, bool ALIGN_EPI = false, bool SP2 = false>
; __device__ __forceinline__ void gemm_phase(PG8_LAS unsigned char* lds, const Gemm g, const Sched& S, const Epi& E) {
;     ...
;             PG8_WAIT_V(8); PG8_WAIT_L(0); PG8_BAR; PG8_MMA(1, 0, At, B0); PG8_MMA(1, 1, At, B1); PG8_BAR; PG8_SCHED;
;             PG8_LDB(B0, 1, 0); PG8_LDB(B1, 1, 1); PG8_SCHED; PG8_LDA(At, 1, 0); PG8_STAGE(PG8_SA(0, 1), a2 + hstepA, voffA);
;             PG8_WAIT_V(8); PG8_WAIT_L(0); PG8_BAR; PG8_MMA(0, 0, At, B0); PG8_MMA(0, 1, At, B1); PG8_BAR; PG8_SCHED;
;             PG8_LDA(At, 1, 1); PG8_STAGE(PG8_SB(1, 0), b3, voffB); PG8_STAGE(PG8_SB(1, 1), b3 + hstepB, voffB); PG8_STAGE(PG8_SA(1, 0), a3, voffA);
	s_setprio 1
	s_waitcnt lgkmcnt(0)
	v_mfma_f32_16x16x32_bf16 v[62:65], v[156:159], v[188:191], v[62:65]
	v_mfma_f32_16x16x32_bf16 v[58:61], v[164:167], v[188:191], v[58:61]
	v_mfma_f32_16x16x32_bf16 v[50:53], v[156:159], v[196:199], v[50:53]
	v_mfma_f32_16x16x32_bf16 v[42:45], v[164:167], v[196:199], v[42:45]
	v_mfma_f32_16x16x32_bf16 v[34:37], v[156:159], v[204:207], v[34:37]
	v_mfma_f32_16x16x32_bf16 v[26:29], v[164:167], v[204:207], v[26:29]
	v_mfma_f32_16x16x32_bf16 v[18:21], v[156:159], v[212:215], v[18:21]
	v_mfma_f32_16x16x32_bf16 v[10:13], v[164:167], v[212:215], v[10:13]
	v_mfma_f32_16x16x32_bf16 v[62:65], v[160:163], v[192:195], v[62:65]
	v_mfma_f32_16x16x32_bf16 v[58:61], v[168:171], v[192:195], v[58:61]
	v_mfma_f32_16x16x32_bf16 v[50:53], v[160:163], v[200:203], v[50:53]
	v_mfma_f32_16x16x32_bf16 v[42:45], v[168:171], v[200:203], v[42:45]
	v_mfma_f32_16x16x32_bf16 v[34:37], v[160:163], v[208:211], v[34:37]
	v_mfma_f32_16x16x32_bf16 v[26:29], v[168:171], v[208:211], v[26:29]
	v_mfma_f32_16x16x32_bf16 v[18:21], v[160:163], v[218:221], v[18:21]
	v_mfma_f32_16x16x32_bf16 v[10:13], v[168:171], v[218:221], v[10:13]
	s_setprio 0
	s_setprio 1
	v_mfma_f32_16x16x32_bf16 v[54:57], v[172:175], v[188:191], v[54:57]
	v_mfma_f32_16x16x32_bf16 v[46:49], v[180:183], v[188:191], v[46:49]
	v_mfma_f32_16x16x32_bf16 v[38:41], v[172:175], v[196:199], v[38:41]
	v_mfma_f32_16x16x32_bf16 v[30:33], v[180:183], v[196:199], v[30:33]
	v_mfma_f32_16x16x32_bf16 v[22:25], v[172:175], v[204:207], v[22:25]
	v_mfma_f32_16x16x32_bf16 v[14:17], v[180:183], v[204:207], v[14:17]
	v_mfma_f32_16x16x32_bf16 v[6:9], v[172:175], v[212:215], v[6:9]
	v_mfma_f32_16x16x32_bf16 v[2:5], v[180:183], v[212:215], v[2:5]
	v_mfma_f32_16x16x32_bf16 v[54:57], v[176:179], v[192:195], v[54:57]
	v_mfma_f32_16x16x32_bf16 v[46:49], v[184:187], v[192:195], v[46:49]
	v_mfma_f32_16x16x32_bf16 v[38:41], v[176:179], v[200:203], v[38:41]
	v_mfma_f32_16x16x32_bf16 v[30:33], v[184:187], v[200:203], v[30:33]
	v_mfma_f32_16x16x32_bf16 v[22:25], v[176:179], v[208:211], v[22:25]
	v_mfma_f32_16x16x32_bf16 v[14:17], v[184:187], v[208:211], v[14:17]
	v_mfma_f32_16x16x32_bf16 v[6:9], v[176:179], v[218:221], v[6:9]
	v_mfma_f32_16x16x32_bf16 v[2:5], v[184:187], v[218:221], v[2:5]
	s_setprio 0
	s_barrier
	s_mov_b32 m0, s31
	s_nop 0
	global_load_lds_dwordx4 v[224:225], off
	s_mov_b32 m0, s45
	s_nop 0
	global_load_lds_dwordx4 v[226:227], off
	s_add_i32 s64, 0, 0x18000
	v_add_u32_e32 v146, s64, v147
	s_add_i32 s65, 0, 0x1c000
	ds_read_b128 v[156:159], v146
	ds_read_b128 v[160:163], v146 offset:1024
	ds_read_b128 v[164:167], v146 offset:2048
	ds_read_b128 v[168:171], v146 offset:3072
	v_add_u32_e32 v146, s65, v147
	ds_read_b128 v[172:175], v146
	ds_read_b128 v[176:179], v146 offset:1024
	ds_read_b128 v[180:183], v146 offset:2048
	ds_read_b128 v[184:187], v146 offset:3072
	s_add_u32 s38, s38, 0x100000
	s_addc_u32 s39, s39, 0
	s_mov_b32 m0, s46
	v_lshl_add_u64 v[228:229], s[38:39], 0, v[130:131]
	ds_read_b128 v[188:191], v155 offset:32768
	ds_read_b128 v[192:195], v155 offset:33792
	ds_read_b128 v[196:199], v155 offset:34816
	ds_read_b128 v[200:203], v155 offset:35840
	ds_read_b128 v[204:207], v155 offset:36864
	ds_read_b128 v[208:211], v155 offset:37888
	ds_read_b128 v[212:215], v155 offset:38912
	ds_read_b128 v[218:221], v155 offset:39936
	global_load_lds_dwordx4 v[228:229], off
	v_lshl_add_u64 v[228:229], s[38:39], 0, v[134:135]
	s_mov_b32 m0, s47
	s_nop 0
	global_load_lds_dwordx4 v[228:229], off
	s_waitcnt vmcnt(8)
	s_waitcnt lgkmcnt(0)
	s_barrier
	s_setprio 1
	s_waitcnt lgkmcnt(0)
	v_mfma_f32_16x16x32_bf16 v[126:129], v[156:159], v[188:191], v[126:129]
	v_mfma_f32_16x16x32_bf16 v[122:125], v[164:167], v[188:191], v[122:125]
	v_mfma_f32_16x16x32_bf16 v[118:121], v[156:159], v[196:199], v[118:121]
	v_mfma_f32_16x16x32_bf16 v[114:117], v[164:167], v[196:199], v[114:117]
	v_mfma_f32_16x16x32_bf16 v[110:113], v[156:159], v[204:207], v[110:113]
	v_mfma_f32_16x16x32_bf16 v[102:105], v[164:167], v[204:207], v[102:105]
	v_mfma_f32_16x16x32_bf16 v[94:97], v[156:159], v[212:215], v[94:97]
	v_mfma_f32_16x16x32_bf16 v[74:77], v[164:167], v[212:215], v[74:77]
	v_mfma_f32_16x16x32_bf16 v[126:129], v[160:163], v[192:195], v[126:129]
	v_mfma_f32_16x16x32_bf16 v[122:125], v[168:171], v[192:195], v[122:125]
	v_mfma_f32_16x16x32_bf16 v[118:121], v[160:163], v[200:203], v[118:121]
	v_mfma_f32_16x16x32_bf16 v[114:117], v[168:171], v[200:203], v[114:117]
	v_mfma_f32_16x16x32_bf16 v[110:113], v[160:163], v[208:211], v[110:113]
	v_mfma_f32_16x16x32_bf16 v[102:105], v[168:171], v[208:211], v[102:105]
	v_mfma_f32_16x16x32_bf16 v[94:97], v[160:163], v[218:221], v[94:97]
	v_mfma_f32_16x16x32_bf16 v[74:77], v[168:171], v[218:221], v[74:77]
	s_setprio 0
	s_setprio 1
	v_mfma_f32_16x16x32_bf16 v[106:109], v[172:175], v[188:191], v[106:109]
	v_mfma_f32_16x16x32_bf16 v[98:101], v[180:183], v[188:191], v[98:101]
	v_mfma_f32_16x16x32_bf16 v[90:93], v[172:175], v[196:199], v[90:93]
	v_mfma_f32_16x16x32_bf16 v[86:89], v[180:183], v[196:199], v[86:89]
	v_mfma_f32_16x16x32_bf16 v[82:85], v[172:175], v[204:207], v[82:85]
	v_mfma_f32_16x16x32_bf16 v[78:81], v[180:183], v[204:207], v[78:81]
	v_mfma_f32_16x16x32_bf16 v[70:73], v[172:175], v[212:215], v[70:73]
	v_mfma_f32_16x16x32_bf16 v[66:69], v[180:183], v[212:215], v[66:69]
	v_mfma_f32_16x16x32_bf16 v[106:109], v[176:179], v[192:195], v[106:109]
	v_mfma_f32_16x16x32_bf16 v[98:101], v[184:187], v[192:195], v[98:101]
	v_mfma_f32_16x16x32_bf16 v[90:93], v[176:179], v[200:203], v[90:93]
	v_mfma_f32_16x16x32_bf16 v[86:89], v[184:187], v[200:203], v[86:89]
	v_mfma_f32_16x16x32_bf16 v[82:85], v[176:179], v[208:211], v[82:85]
	v_mfma_f32_16x16x32_bf16 v[78:81], v[184:187], v[208:211], v[78:81]
	v_mfma_f32_16x16x32_bf16 v[70:73], v[176:179], v[218:221], v[70:73]
	v_mfma_f32_16x16x32_bf16 v[66:69], v[184:187], v[218:221], v[66:69]
	s_setprio 0
	s_barrier
; #define PG8_STAGE(bufoff, gbase, voff) do { _Pragma("unroll") for (int _i = 0; _i < 2; ++_i) \
;         __builtin_amdgcn_global_load_lds((const unsigned*)((const char*)(gbase) + (voff)[_i]), (PG8_LAS unsigned*)(lds + (bufoff) + ldsw + _i * 8192), 16, 0, 0); } while (0)
; #define PG8_LDA(dst, b, h) do { _Pragma("unroll") for (int m = 0; m < 4; ++m) _Pragma("unroll") for (int k = 0; k < 2; ++k) dst[m][k] = *(const PG8_LAS bf16x8*)(lds + PG8_SA(b, h) + aoff + m * 2048 + k * 1024); } while (0)
; #define PG8_MMA(ai, bj, At, Bt) do { __builtin_amdgcn_s_setprio(1); _Pragma("unroll") for (int m = 0; m < 4; ++m) _Pragma("unroll") for (int n = 0; n < 2; ++n) _Pragma("unroll") for (int k = 0; k < 2; ++k) \
;         acc[ai][bj][m][n] = __builtin_amdgcn_mfma_f32_16x16x32_bf16(Bt[n][k], At[m][k], acc[ai][bj][m][n], 0, 0, 0); __builtin_amdgcn_s_setprio(0); } while (0)
; #define PG8_WAIT_V(n) asm volatile("s_waitcnt vmcnt(" #n ")" ::: "memory")
; #define PG8_WAIT_L(n) asm volatile("s_waitcnt lgkmcnt(" #n ")" ::: "memory")
; #define PG8_BAR __builtin_amdgcn_s_barrier()
; #define PG8_SCHED __builtin_amdgcn_sched_barrier(0)
; template <class Epi, class Sched, bool ALIGN_EPI = false, bool SP2 = false>
; __device__ __forceinline__ void gemm_phase(PG8_LAS unsigned char* lds, const Gemm g, const Sched& S, const Epi& E) {
;     ...
;             PG8_LDA(At, 1, 1); PG8_STAGE(PG8_SB(1, 0), b3, voffB); PG8_STAGE(PG8_SB(1, 1), b3 + hstepB, voffB); PG8_STAGE(PG8_SA(1, 0), a3, voffA);
;             PG8_WAIT_V(8); PG8_WAIT_L(0); PG8_BAR; PG8_MMA(1, 0, At, B0); PG8_MMA(1, 1, At, B1); PG8_BAR; PG8_SCHED;
	s_add_i32 s38, s64, s44
	v_lshl_add_u64 v[148:149], v[148:149], 0, s[10:11]
	s_mov_b32 m0, s38
	ds_read_b128 v[188:191], v155 offset:49152
	ds_read_b128 v[192:195], v155 offset:50176
	ds_read_b128 v[196:199], v155 offset:51200
	ds_read_b128 v[200:203], v155 offset:52224
	ds_read_b128 v[204:207], v155 offset:53248
	ds_read_b128 v[208:211], v155 offset:54272
	ds_read_b128 v[212:215], v155 offset:55296
	ds_read_b128 v[218:221], v155 offset:56320
	global_load_lds_dwordx4 v[148:149], off
	s_add_i32 m0, s38, 0x2000
	s_add_u32 s36, s36, 0x100080
	v_lshl_add_u64 v[148:149], v[222:223], 0, s[10:11]
	s_addc_u32 s37, s37, 0
	s_add_i32 s38, s65, s44
	global_load_lds_dwordx4 v[148:149], off
	v_lshl_add_u64 v[148:149], s[36:37], 0, v[132:133]
	s_mov_b32 m0, s38
	s_nop 0
	global_load_lds_dwordx4 v[148:149], off
	v_lshl_add_u64 v[148:149], s[36:37], 0, v[136:137]
	s_add_i32 m0, s38, 0x2000
	s_nop 0
	global_load_lds_dwordx4 v[148:149], off
	s_waitcnt vmcnt(6)
	s_waitcnt lgkmcnt(0)
	s_barrier
	s_setprio 1
	s_waitcnt lgkmcnt(0)
	v_mfma_f32_16x16x32_bf16 v[62:65], v[156:159], v[188:191], v[62:65]
	v_mfma_f32_16x16x32_bf16 v[58:61], v[164:167], v[188:191], v[58:61]
	v_mfma_f32_16x16x32_bf16 v[50:53], v[156:159], v[196:199], v[50:53]
	v_mfma_f32_16x16x32_bf16 v[42:45], v[164:167], v[196:199], v[42:45]
	v_mfma_f32_16x16x32_bf16 v[34:37], v[156:159], v[204:207], v[34:37]
	v_mfma_f32_16x16x32_bf16 v[26:29], v[164:167], v[204:207], v[26:29]
	v_mfma_f32_16x16x32_bf16 v[18:21], v[156:159], v[212:215], v[18:21]
	v_mfma_f32_16x16x32_bf16 v[10:13], v[164:167], v[212:215], v[10:13]
	v_mfma_f32_16x16x32_bf16 v[62:65], v[160:163], v[192:195], v[62:65]
	v_mfma_f32_16x16x32_bf16 v[58:61], v[168:171], v[192:195], v[58:61]
	v_mfma_f32_16x16x32_bf16 v[50:53], v[160:163], v[200:203], v[50:53]
	v_mfma_f32_16x16x32_bf16 v[42:45], v[168:171], v[200:203], v[42:45]
	v_mfma_f32_16x16x32_bf16 v[34:37], v[160:163], v[208:211], v[34:37]
	v_mfma_f32_16x16x32_bf16 v[26:29], v[168:171], v[208:211], v[26:29]
	v_mfma_f32_16x16x32_bf16 v[18:21], v[160:163], v[218:221], v[18:21]
	v_mfma_f32_16x16x32_bf16 v[10:13], v[168:171], v[218:221], v[10:13]
	s_setprio 0
	s_setprio 1
	v_mfma_f32_16x16x32_bf16 v[54:57], v[172:175], v[188:191], v[54:57]
	v_mfma_f32_16x16x32_bf16 v[46:49], v[180:183], v[188:191], v[46:49]
	v_mfma_f32_16x16x32_bf16 v[38:41], v[172:175], v[196:199], v[38:41]
	v_mfma_f32_16x16x32_bf16 v[30:33], v[180:183], v[196:199], v[30:33]
	v_mfma_f32_16x16x32_bf16 v[22:25], v[172:175], v[204:207], v[22:25]
	v_mfma_f32_16x16x32_bf16 v[14:17], v[180:183], v[204:207], v[14:17]
	v_mfma_f32_16x16x32_bf16 v[6:9], v[172:175], v[212:215], v[6:9]
	v_mfma_f32_16x16x32_bf16 v[2:5], v[180:183], v[212:215], v[2:5]
	v_mfma_f32_16x16x32_bf16 v[54:57], v[176:179], v[192:195], v[54:57]
	v_mfma_f32_16x16x32_bf16 v[46:49], v[184:187], v[192:195], v[46:49]
	v_mfma_f32_16x16x32_bf16 v[38:41], v[176:179], v[200:203], v[38:41]
	v_mfma_f32_16x16x32_bf16 v[30:33], v[184:187], v[200:203], v[30:33]
	v_mfma_f32_16x16x32_bf16 v[22:25], v[176:179], v[208:211], v[22:25]
	v_mfma_f32_16x16x32_bf16 v[14:17], v[184:187], v[208:211], v[14:17]
	v_mfma_f32_16x16x32_bf16 v[6:9], v[176:179], v[218:221], v[6:9]
	v_mfma_f32_16x16x32_bf16 v[2:5], v[184:187], v[218:221], v[2:5]
	s_setprio 0
	s_barrier
	v_lshl_add_u64 v[148:149], v[224:225], 0, s[10:11]
	s_mov_b32 m0, s49
	s_nop 0
	global_load_lds_dwordx4 v[148:149], off
	v_lshl_add_u64 v[148:149], v[226:227], 0, s[10:11]
	s_mov_b32 m0, s50
	s_nop 0
	global_load_lds_dwordx4 v[148:149], off
	s_add_i32 s63, s63, 2
	s_add_u32 s34, s34, 0x100
	s_addc_u32 s35, s35, 0
	s_add_u32 s61, s61, 0x100
	s_addc_u32 s62, s62, 0
	s_cmp_gt_u32 s63, 61
	s_cbranch_scc0 .LBB0_1097
	s_and_b64 vcc, exec, s[12:13]
	s_cbranch_vccz .LBB0_1100
	s_barrier

; #define PG8_STAGE(bufoff, gbase, voff) do { _Pragma("unroll") for (int _i = 0; _i < 2; ++_i) \
;         __builtin_amdgcn_global_load_lds((const unsigned*)((const char*)(gbase) + (voff)[_i]), (PG8_LAS unsigned*)(lds + (bufoff) + ldsw + _i * 8192), 16, 0, 0); } while (0)
; #define PG8_LDA(dst, b, h) do { _Pragma("unroll") for (int m = 0; m < 4; ++m) _Pragma("unroll") for (int k = 0; k < 2; ++k) dst[m][k] = *(const PG8_LAS bf16x8*)(lds + PG8_SA(b, h) + aoff + m * 2048 + k * 1024); } while (0)
; #define PG8_LDB(dst, b, h) do { _Pragma("unroll") for (int n = 0; n < 2; ++n) _Pragma("unroll") for (int k = 0; k < 2; ++k) dst[n][k] = *(const PG8_LAS bf16x8*)(lds + PG8_SB(b, h) + boff + n * 2048 + k * 1024); } while (0)
; #define PG8_MMA(ai, bj, At, Bt) do { __builtin_amdgcn_s_setprio(1); _Pragma("unroll") for (int m = 0; m < 4; ++m) _Pragma("unroll") for (int n = 0; n < 2; ++n) _Pragma("unroll") for (int k = 0; k < 2; ++k) \
;         acc[ai][bj][m][n] = __builtin_amdgcn_mfma_f32_16x16x32_bf16(Bt[n][k], At[m][k], acc[ai][bj][m][n], 0, 0, 0); __builtin_amdgcn_s_setprio(0); } while (0)
; #define PG8_WAIT_V(n) asm volatile("s_waitcnt vmcnt(" #n ")" ::: "memory")
; #define PG8_WAIT_L(n) asm volatile("s_waitcnt lgkmcnt(" #n ")" ::: "memory")
; #define PG8_BAR __builtin_amdgcn_s_barrier()
; #define PG8_SCHED __builtin_amdgcn_sched_barrier(0)
; template <class Epi, class Sched, bool ALIGN_EPI = false, bool SP2 = false>
; __device__ __forceinline__ void gemm_phase(PG8_LAS unsigned char* lds, const Gemm g, const Sched& S, const Epi& E) {
;     ...
;         for (int t = 0; t < nt; t += 2) {
;             const bool last = (t == nt - 2);
;             const char* a1 = cA + (size_t)(t + 1) * kstep;
;             const char* a2 = last ? nA : cA + (size_t)(t + 2) * kstep; const char* b2 = last ? nB : cB + (size_t)(t + 2) * kstep;
;             const char* a3 = a2 + kstep; const char* b3 = b2 + kstep;
;             if (last && has_next) S.a_ready(nxt);
;             if constexpr (SP2) {
;             PG8_LDB(B0, 0, 0); PG8_LDB(B1, 0, 1); PG8_SCHED; PG8_LDA(At, 0, 0); PG8_STAGE(PG8_SA(1, 1), a1 + hstepA, voffA);
;             PG8_WAIT_V(8); PG8_WAIT_L(0); PG8_BAR; PG8_MMA(0, 0, At, B0); PG8_MMA(0, 1, At, B1); PG8_BAR; PG8_SCHED;
;             PG8_LDA(At, 0, 1); PG8_STAGE(PG8_SB(0, 0), b2, voffB); PG8_STAGE(PG8_SB(0, 1), b2 + hstepB, voffB); PG8_STAGE(PG8_SA(0, 0), a2, voffA);
.LBB0_1743:
	s_lshl_b32 s36, s62, 7
	s_add_u32 s37, s24, s36
	s_addc_u32 s38, s25, 0
	v_add_u32_e32 v140, s53, v143
	s_add_u32 s39, s37, 0x100
	ds_read_b128 v[146:149], v140
	ds_read_b128 v[150:153], v140 offset:1024
	ds_read_b128 v[154:157], v140 offset:2048
	ds_read_b128 v[158:161], v140 offset:3072
	v_add_u32_e32 v140, s54, v143
	s_addc_u32 s63, s38, 0
	ds_read_b128 v[162:165], v140
	ds_read_b128 v[166:169], v140 offset:1024
	ds_read_b128 v[170:173], v140 offset:2048
	ds_read_b128 v[174:177], v140 offset:3072
	s_and_b64 s[34:35], s[30:31], exec
	s_cselect_b32 s35, s23, s63
	s_cselect_b32 s34, s59, s39
	s_add_u32 s36, s26, s36
	s_addc_u32 s39, s27, 0
	s_add_u32 s36, s36, 0x100
	s_addc_u32 s39, s39, 0
	s_and_b64 s[30:31], s[30:31], exec
	s_cselect_b32 s31, s60, s39
	s_cselect_b32 s30, s61, s36
	s_add_u32 s36, s37, 0x100080
	s_addc_u32 s37, s38, 0
	v_lshl_add_u64 v[140:141], s[36:37], 0, v[130:131]
	s_add_i32 m0, s45, 0xc000
	ds_read_b128 v[178:181], v144
	ds_read_b128 v[182:185], v144 offset:1024
	ds_read_b128 v[186:189], v144 offset:2048
	ds_read_b128 v[190:193], v144 offset:3072
	ds_read_b128 v[194:197], v144 offset:4096
	ds_read_b128 v[198:201], v144 offset:5120
	ds_read_b128 v[202:205], v144 offset:6144
	ds_read_b128 v[206:209], v144 offset:7168
	global_load_lds_dwordx4 v[140:141], off
	v_lshl_add_u64 v[140:141], s[36:37], 0, v[134:135]
	s_add_i32 m0, s45, 0xe000
	s_nop 0
	global_load_lds_dwordx4 v[140:141], off
	s_waitcnt vmcnt(8)
	s_waitcnt lgkmcnt(0)
	s_barrier
	s_setprio 1
	s_waitcnt lgkmcnt(0)
	v_mfma_f32_16x16x32_bf16 v[126:129], v[146:149], v[178:181], v[126:129]
	v_mfma_f32_16x16x32_bf16 v[122:125], v[154:157], v[178:181], v[122:125]
	v_mfma_f32_16x16x32_bf16 v[114:117], v[146:149], v[186:189], v[114:117]
	v_mfma_f32_16x16x32_bf16 v[106:109], v[154:157], v[186:189], v[106:109]
	v_mfma_f32_16x16x32_bf16 v[98:101], v[146:149], v[194:197], v[98:101]
	v_mfma_f32_16x16x32_bf16 v[90:93], v[154:157], v[194:197], v[90:93]
	v_mfma_f32_16x16x32_bf16 v[82:85], v[146:149], v[202:205], v[82:85]
	v_mfma_f32_16x16x32_bf16 v[74:77], v[154:157], v[202:205], v[74:77]
	v_mfma_f32_16x16x32_bf16 v[126:129], v[150:153], v[182:185], v[126:129]
	v_mfma_f32_16x16x32_bf16 v[122:125], v[158:161], v[182:185], v[122:125]
	v_mfma_f32_16x16x32_bf16 v[114:117], v[150:153], v[190:193], v[114:117]
	v_mfma_f32_16x16x32_bf16 v[106:109], v[158:161], v[190:193], v[106:109]
	v_mfma_f32_16x16x32_bf16 v[98:101], v[150:153], v[198:201], v[98:101]
	v_mfma_f32_16x16x32_bf16 v[90:93], v[158:161], v[198:201], v[90:93]
	v_mfma_f32_16x16x32_bf16 v[82:85], v[150:153], v[206:209], v[82:85]
	v_mfma_f32_16x16x32_bf16 v[74:77], v[158:161], v[206:209], v[74:77]
	s_setprio 0
	s_setprio 1
	v_mfma_f32_16x16x32_bf16 v[118:121], v[162:165], v[178:181], v[118:121]
	v_mfma_f32_16x16x32_bf16 v[110:113], v[170:173], v[178:181], v[110:113]
	v_mfma_f32_16x16x32_bf16 v[102:105], v[162:165], v[186:189], v[102:105]
	v_mfma_f32_16x16x32_bf16 v[94:97], v[170:173], v[186:189], v[94:97]
	v_mfma_f32_16x16x32_bf16 v[86:89], v[162:165], v[194:197], v[86:89]
	v_mfma_f32_16x16x32_bf16 v[78:81], v[170:173], v[194:197], v[78:81]
	v_mfma_f32_16x16x32_bf16 v[70:73], v[162:165], v[202:205], v[70:73]
	v_mfma_f32_16x16x32_bf16 v[66:69], v[170:173], v[202:205], v[66:69]
	v_mfma_f32_16x16x32_bf16 v[118:121], v[166:169], v[182:185], v[118:121]
	v_mfma_f32_16x16x32_bf16 v[110:113], v[174:177], v[182:185], v[110:113]
	v_mfma_f32_16x16x32_bf16 v[102:105], v[166:169], v[190:193], v[102:105]
	v_mfma_f32_16x16x32_bf16 v[94:97], v[174:177], v[190:193], v[94:97]
	v_mfma_f32_16x16x32_bf16 v[86:89], v[166:169], v[198:201], v[86:89]
	v_mfma_f32_16x16x32_bf16 v[78:81], v[174:177], v[198:201], v[78:81]
	v_mfma_f32_16x16x32_bf16 v[70:73], v[166:169], v[206:209], v[70:73]
	v_mfma_f32_16x16x32_bf16 v[66:69], v[174:177], v[206:209], v[66:69]
	s_setprio 0
	s_barrier
	s_add_i32 s36, s53, s43
	v_lshl_add_u64 v[140:141], s[30:31], 0, v[132:133]
	s_mov_b32 m0, s36
	ds_read_b128 v[178:181], v144 offset:16384
	ds_read_b128 v[182:185], v144 offset:17408
	ds_read_b128 v[186:189], v144 offset:18432
	ds_read_b128 v[190:193], v144 offset:19456
	ds_read_b128 v[194:197], v144 offset:20480
	ds_read_b128 v[198:201], v144 offset:21504
	ds_read_b128 v[202:205], v144 offset:22528
	ds_read_b128 v[206:209], v144 offset:23552
	global_load_lds_dwordx4 v[140:141], off
	s_add_i32 m0, s36, 0x2000
	s_add_u32 s36, s30, 0x100000
	v_lshl_add_u64 v[210:211], s[30:31], 0, v[136:137]
	s_addc_u32 s37, s31, 0
	s_add_i32 s38, s54, s43
	global_load_lds_dwordx4 v[210:211], off
	v_lshl_add_u64 v[212:213], s[36:37], 0, v[132:133]
	s_mov_b32 m0, s38
	v_lshl_add_u64 v[214:215], s[34:35], 0, v[134:135]
	global_load_lds_dwordx4 v[212:213], off
	v_lshl_add_u64 v[212:213], s[36:37], 0, v[136:137]
	s_add_i32 m0, s38, 0x2000
	s_nop 0
	global_load_lds_dwordx4 v[212:213], off
	v_lshl_add_u64 v[212:213], s[34:35], 0, v[130:131]
	s_waitcnt vmcnt(6)
	s_waitcnt lgkmcnt(0)
	s_barrier
; #define PG8_STAGE(bufoff, gbase, voff) do { _Pragma("unroll") for (int _i = 0; _i < 2; ++_i) \
;         __builtin_amdgcn_global_load_lds((const unsigned*)((const char*)(gbase) + (voff)[_i]), (PG8_LAS unsigned*)(lds + (bufoff) + ldsw + _i * 8192), 16, 0, 0); } while (0)
; #define PG8_LDA(dst, b, h) do { _Pragma("unroll") for (int m = 0; m < 4; ++m) _Pragma("unroll") for (int k = 0; k < 2; ++k) dst[m][k] = *(const PG8_LAS bf16x8*)(lds + PG8_SA(b, h) + aoff + m * 2048 + k * 1024); } while (0)
; #define PG8_LDB(dst, b, h) do { _Pragma("unroll") for (int n = 0; n < 2; ++n) _Pragma("unroll") for (int k = 0; k < 2; ++k) dst[n][k] = *(const PG8_LAS bf16x8*)(lds + PG8_SB(b, h) + boff + n * 2048 + k * 1024); } while (0)
; #define PG8_MMA(ai, bj, At, Bt) do { __builtin_amdgcn_s_setprio(1); _Pragma("unroll") for (int m = 0; m < 4; ++m) _Pragma("unroll") for (int n = 0; n < 2; ++n) _Pragma("unroll") for (int k = 0; k < 2; ++k) \
;         acc[ai][bj][m][n] = __builtin_amdgcn_mfma_f32_16x16x32_bf16(Bt[n][k], At[m][k], acc[ai][bj][m][n], 0, 0, 0); __builtin_amdgcn_s_setprio(0); } while (0)
; #define PG8_WAIT_V(n) asm volatile("s_waitcnt vmcnt(" #n ")" ::: "memory")
; #define PG8_WAIT_L(n) asm volatile("s_waitcnt lgkmcnt(" #n ")" ::: "memory")
; #define PG8_BAR __builtin_amdgcn_s_barrier()
; #define PG8_SCHED __builtin_amdgcn_sched_barrier(0)
; template <class Epi, class Sched, bool ALIGN_EPI = false, bool SP2 = false>
; __device__ __forceinline__ void gemm_phase(PG8_LAS unsigned char* lds, const Gemm g, const Sched& S, const Epi& E) {
;     ...
;             PG8_WAIT_V(8); PG8_WAIT_L(0); PG8_BAR; PG8_MMA(1, 0, At, B0); PG8_MMA(1, 1, At, B1); PG8_BAR; PG8_SCHED;
;             PG8_LDB(B0, 1, 0); PG8_LDB(B1, 1, 1); PG8_SCHED; PG8_LDA(At, 1, 0); PG8_STAGE(PG8_SA(0, 1), a2 + hstepA, voffA);
;             PG8_WAIT_V(8); PG8_WAIT_L(0); PG8_BAR; PG8_MMA(0, 0, At, B0); PG8_MMA(0, 1, At, B1); PG8_BAR; PG8_SCHED;
;             PG8_LDA(At, 1, 1); PG8_STAGE(PG8_SB(1, 0), b3, voffB); PG8_STAGE(PG8_SB(1, 1), b3 + hstepB, voffB); PG8_STAGE(PG8_SA(1, 0), a3, voffA);
	s_setprio 1
	s_waitcnt lgkmcnt(0)
	v_mfma_f32_16x16x32_bf16 v[62:65], v[146:149], v[178:181], v[62:65]
	v_mfma_f32_16x16x32_bf16 v[58:61], v[154:157], v[178:181], v[58:61]
	v_mfma_f32_16x16x32_bf16 v[50:53], v[146:149], v[186:189], v[50:53]
	v_mfma_f32_16x16x32_bf16 v[42:45], v[154:157], v[186:189], v[42:45]
	v_mfma_f32_16x16x32_bf16 v[34:37], v[146:149], v[194:197], v[34:37]
	v_mfma_f32_16x16x32_bf16 v[26:29], v[154:157], v[194:197], v[26:29]
	v_mfma_f32_16x16x32_bf16 v[18:21], v[146:149], v[202:205], v[18:21]
	v_mfma_f32_16x16x32_bf16 v[10:13], v[154:157], v[202:205], v[10:13]
	v_mfma_f32_16x16x32_bf16 v[62:65], v[150:153], v[182:185], v[62:65]
	v_mfma_f32_16x16x32_bf16 v[58:61], v[158:161], v[182:185], v[58:61]
	v_mfma_f32_16x16x32_bf16 v[50:53], v[150:153], v[190:193], v[50:53]
	v_mfma_f32_16x16x32_bf16 v[42:45], v[158:161], v[190:193], v[42:45]
	v_mfma_f32_16x16x32_bf16 v[34:37], v[150:153], v[198:201], v[34:37]
	v_mfma_f32_16x16x32_bf16 v[26:29], v[158:161], v[198:201], v[26:29]
	v_mfma_f32_16x16x32_bf16 v[18:21], v[150:153], v[206:209], v[18:21]
	v_mfma_f32_16x16x32_bf16 v[10:13], v[158:161], v[206:209], v[10:13]
	s_setprio 0
	s_setprio 1
	v_mfma_f32_16x16x32_bf16 v[54:57], v[162:165], v[178:181], v[54:57]
	v_mfma_f32_16x16x32_bf16 v[46:49], v[170:173], v[178:181], v[46:49]
	v_mfma_f32_16x16x32_bf16 v[38:41], v[162:165], v[186:189], v[38:41]
	v_mfma_f32_16x16x32_bf16 v[30:33], v[170:173], v[186:189], v[30:33]
	v_mfma_f32_16x16x32_bf16 v[22:25], v[162:165], v[194:197], v[22:25]
	v_mfma_f32_16x16x32_bf16 v[14:17], v[170:173], v[194:197], v[14:17]
	v_mfma_f32_16x16x32_bf16 v[6:9], v[162:165], v[202:205], v[6:9]
	v_mfma_f32_16x16x32_bf16 v[2:5], v[170:173], v[202:205], v[2:5]
	v_mfma_f32_16x16x32_bf16 v[54:57], v[166:169], v[182:185], v[54:57]
	v_mfma_f32_16x16x32_bf16 v[46:49], v[174:177], v[182:185], v[46:49]
	v_mfma_f32_16x16x32_bf16 v[38:41], v[166:169], v[190:193], v[38:41]
	v_mfma_f32_16x16x32_bf16 v[30:33], v[174:177], v[190:193], v[30:33]
	v_mfma_f32_16x16x32_bf16 v[22:25], v[166:169], v[198:201], v[22:25]
	v_mfma_f32_16x16x32_bf16 v[14:17], v[174:177], v[198:201], v[14:17]
	v_mfma_f32_16x16x32_bf16 v[6:9], v[166:169], v[206:209], v[6:9]
	v_mfma_f32_16x16x32_bf16 v[2:5], v[174:177], v[206:209], v[2:5]
	s_setprio 0
	s_barrier
	s_mov_b32 m0, s45
	s_nop 0
	global_load_lds_dwordx4 v[212:213], off
	s_mov_b32 m0, s46
	s_nop 0
	global_load_lds_dwordx4 v[214:215], off
	s_add_i32 s36, 0, 0x18000
	v_add_u32_e32 v145, s36, v143
	s_add_i32 s37, 0, 0x1c000
	ds_read_b128 v[146:149], v145
	ds_read_b128 v[150:153], v145 offset:1024
	ds_read_b128 v[154:157], v145 offset:2048
	ds_read_b128 v[158:161], v145 offset:3072
	v_add_u32_e32 v145, s37, v143
	ds_read_b128 v[162:165], v145
	ds_read_b128 v[166:169], v145 offset:1024
	ds_read_b128 v[170:173], v145 offset:2048
	ds_read_b128 v[174:177], v145 offset:3072
	s_add_u32 s34, s34, 0x100000
	s_addc_u32 s35, s35, 0
	s_mov_b32 m0, s47
	v_lshl_add_u64 v[218:219], s[34:35], 0, v[130:131]
	ds_read_b128 v[178:181], v144 offset:32768
	ds_read_b128 v[182:185], v144 offset:33792
	ds_read_b128 v[186:189], v144 offset:34816
	ds_read_b128 v[190:193], v144 offset:35840
	ds_read_b128 v[194:197], v144 offset:36864
	ds_read_b128 v[198:201], v144 offset:37888
	ds_read_b128 v[202:205], v144 offset:38912
	ds_read_b128 v[206:209], v144 offset:39936
	global_load_lds_dwordx4 v[218:219], off
	v_lshl_add_u64 v[218:219], s[34:35], 0, v[134:135]
	s_mov_b32 m0, s48
	s_nop 0
	global_load_lds_dwordx4 v[218:219], off
	s_waitcnt vmcnt(8)
	s_waitcnt lgkmcnt(0)
	s_barrier
	s_setprio 1
	s_waitcnt lgkmcnt(0)
	v_mfma_f32_16x16x32_bf16 v[126:129], v[146:149], v[178:181], v[126:129]
	v_mfma_f32_16x16x32_bf16 v[122:125], v[154:157], v[178:181], v[122:125]
	v_mfma_f32_16x16x32_bf16 v[114:117], v[146:149], v[186:189], v[114:117]
	v_mfma_f32_16x16x32_bf16 v[106:109], v[154:157], v[186:189], v[106:109]
	v_mfma_f32_16x16x32_bf16 v[98:101], v[146:149], v[194:197], v[98:101]
	v_mfma_f32_16x16x32_bf16 v[90:93], v[154:157], v[194:197], v[90:93]
	v_mfma_f32_16x16x32_bf16 v[82:85], v[146:149], v[202:205], v[82:85]
	v_mfma_f32_16x16x32_bf16 v[74:77], v[154:157], v[202:205], v[74:77]
	v_mfma_f32_16x16x32_bf16 v[126:129], v[150:153], v[182:185], v[126:129]
	v_mfma_f32_16x16x32_bf16 v[122:125], v[158:161], v[182:185], v[122:125]
	v_mfma_f32_16x16x32_bf16 v[114:117], v[150:153], v[190:193], v[114:117]
	v_mfma_f32_16x16x32_bf16 v[106:109], v[158:161], v[190:193], v[106:109]
	v_mfma_f32_16x16x32_bf16 v[98:101], v[150:153], v[198:201], v[98:101]
	v_mfma_f32_16x16x32_bf16 v[90:93], v[158:161], v[198:201], v[90:93]
	v_mfma_f32_16x16x32_bf16 v[82:85], v[150:153], v[206:209], v[82:85]
	v_mfma_f32_16x16x32_bf16 v[74:77], v[158:161], v[206:209], v[74:77]
	s_setprio 0
	s_setprio 1
	v_mfma_f32_16x16x32_bf16 v[118:121], v[162:165], v[178:181], v[118:121]
	v_mfma_f32_16x16x32_bf16 v[110:113], v[170:173], v[178:181], v[110:113]
	v_mfma_f32_16x16x32_bf16 v[102:105], v[162:165], v[186:189], v[102:105]
	v_mfma_f32_16x16x32_bf16 v[94:97], v[170:173], v[186:189], v[94:97]
	v_mfma_f32_16x16x32_bf16 v[86:89], v[162:165], v[194:197], v[86:89]
	v_mfma_f32_16x16x32_bf16 v[78:81], v[170:173], v[194:197], v[78:81]
	v_mfma_f32_16x16x32_bf16 v[70:73], v[162:165], v[202:205], v[70:73]
	v_mfma_f32_16x16x32_bf16 v[66:69], v[170:173], v[202:205], v[66:69]
	v_mfma_f32_16x16x32_bf16 v[118:121], v[166:169], v[182:185], v[118:121]
	v_mfma_f32_16x16x32_bf16 v[110:113], v[174:177], v[182:185], v[110:113]
	v_mfma_f32_16x16x32_bf16 v[102:105], v[166:169], v[190:193], v[102:105]
	v_mfma_f32_16x16x32_bf16 v[94:97], v[174:177], v[190:193], v[94:97]
	v_mfma_f32_16x16x32_bf16 v[86:89], v[166:169], v[198:201], v[86:89]
	v_mfma_f32_16x16x32_bf16 v[78:81], v[174:177], v[198:201], v[78:81]
	v_mfma_f32_16x16x32_bf16 v[70:73], v[166:169], v[206:209], v[70:73]
	v_mfma_f32_16x16x32_bf16 v[66:69], v[174:177], v[206:209], v[66:69]
	s_setprio 0
	s_barrier
; #define PG8_STAGE(bufoff, gbase, voff) do { _Pragma("unroll") for (int _i = 0; _i < 2; ++_i) \
;         __builtin_amdgcn_global_load_lds((const unsigned*)((const char*)(gbase) + (voff)[_i]), (PG8_LAS unsigned*)(lds + (bufoff) + ldsw + _i * 8192), 16, 0, 0); } while (0)
; #define PG8_LDA(dst, b, h) do { _Pragma("unroll") for (int m = 0; m < 4; ++m) _Pragma("unroll") for (int k = 0; k < 2; ++k) dst[m][k] = *(const PG8_LAS bf16x8*)(lds + PG8_SA(b, h) + aoff + m * 2048 + k * 1024); } while (0)
; #define PG8_MMA(ai, bj, At, Bt) do { __builtin_amdgcn_s_setprio(1); _Pragma("unroll") for (int m = 0; m < 4; ++m) _Pragma("unroll") for (int n = 0; n < 2; ++n) _Pragma("unroll") for (int k = 0; k < 2; ++k) \
;         acc[ai][bj][m][n] = __builtin_amdgcn_mfma_f32_16x16x32_bf16(Bt[n][k], At[m][k], acc[ai][bj][m][n], 0, 0, 0); __builtin_amdgcn_s_setprio(0); } while (0)
; #define PG8_WAIT_V(n) asm volatile("s_waitcnt vmcnt(" #n ")" ::: "memory")
; #define PG8_WAIT_L(n) asm volatile("s_waitcnt lgkmcnt(" #n ")" ::: "memory")
; #define PG8_BAR __builtin_amdgcn_s_barrier()
; #define PG8_SCHED __builtin_amdgcn_sched_barrier(0)
; template <class Epi, class Sched, bool ALIGN_EPI = false, bool SP2 = false>
; __device__ __forceinline__ void gemm_phase(PG8_LAS unsigned char* lds, const Gemm g, const Sched& S, const Epi& E) {
;     ...
;             PG8_LDA(At, 1, 1); PG8_STAGE(PG8_SB(1, 0), b3, voffB); PG8_STAGE(PG8_SB(1, 1), b3 + hstepB, voffB); PG8_STAGE(PG8_SA(1, 0), a3, voffA);
;             PG8_WAIT_V(8); PG8_WAIT_L(0); PG8_BAR; PG8_MMA(1, 0, At, B0); PG8_MMA(1, 1, At, B1); PG8_BAR; PG8_SCHED;
	s_add_i32 s34, s36, s43
	v_lshl_add_u64 v[140:141], v[140:141], 0, s[10:11]
	s_mov_b32 m0, s34
	ds_read_b128 v[178:181], v144 offset:49152
	ds_read_b128 v[182:185], v144 offset:50176
	ds_read_b128 v[186:189], v144 offset:51200
	ds_read_b128 v[190:193], v144 offset:52224
	ds_read_b128 v[194:197], v144 offset:53248
	ds_read_b128 v[198:201], v144 offset:54272
	ds_read_b128 v[202:205], v144 offset:55296
	ds_read_b128 v[206:209], v144 offset:56320
	global_load_lds_dwordx4 v[140:141], off
	s_add_i32 m0, s34, 0x2000
	s_add_u32 s30, s30, 0x100080
	v_lshl_add_u64 v[140:141], v[210:211], 0, s[10:11]
	s_addc_u32 s31, s31, 0
	s_add_i32 s34, s37, s43
	global_load_lds_dwordx4 v[140:141], off
	v_lshl_add_u64 v[140:141], s[30:31], 0, v[132:133]
	s_mov_b32 m0, s34
	s_nop 0
	global_load_lds_dwordx4 v[140:141], off
	v_lshl_add_u64 v[140:141], s[30:31], 0, v[136:137]
	s_add_i32 m0, s34, 0x2000
	s_nop 0
	global_load_lds_dwordx4 v[140:141], off
	s_waitcnt vmcnt(6)
	s_waitcnt lgkmcnt(0)
	s_barrier
	s_setprio 1
	s_waitcnt lgkmcnt(0)
	v_mfma_f32_16x16x32_bf16 v[62:65], v[146:149], v[178:181], v[62:65]
	v_mfma_f32_16x16x32_bf16 v[58:61], v[154:157], v[178:181], v[58:61]
	v_mfma_f32_16x16x32_bf16 v[50:53], v[146:149], v[186:189], v[50:53]
	v_mfma_f32_16x16x32_bf16 v[42:45], v[154:157], v[186:189], v[42:45]
	v_mfma_f32_16x16x32_bf16 v[34:37], v[146:149], v[194:197], v[34:37]
	v_mfma_f32_16x16x32_bf16 v[26:29], v[154:157], v[194:197], v[26:29]
	v_mfma_f32_16x16x32_bf16 v[18:21], v[146:149], v[202:205], v[18:21]
	v_mfma_f32_16x16x32_bf16 v[10:13], v[154:157], v[202:205], v[10:13]
	v_mfma_f32_16x16x32_bf16 v[62:65], v[150:153], v[182:185], v[62:65]
	v_mfma_f32_16x16x32_bf16 v[58:61], v[158:161], v[182:185], v[58:61]
	v_mfma_f32_16x16x32_bf16 v[50:53], v[150:153], v[190:193], v[50:53]
	v_mfma_f32_16x16x32_bf16 v[42:45], v[158:161], v[190:193], v[42:45]
	v_mfma_f32_16x16x32_bf16 v[34:37], v[150:153], v[198:201], v[34:37]
	v_mfma_f32_16x16x32_bf16 v[26:29], v[158:161], v[198:201], v[26:29]
	v_mfma_f32_16x16x32_bf16 v[18:21], v[150:153], v[206:209], v[18:21]
	v_mfma_f32_16x16x32_bf16 v[10:13], v[158:161], v[206:209], v[10:13]
	s_setprio 0
	s_setprio 1
	v_mfma_f32_16x16x32_bf16 v[54:57], v[162:165], v[178:181], v[54:57]
	v_mfma_f32_16x16x32_bf16 v[46:49], v[170:173], v[178:181], v[46:49]
	v_mfma_f32_16x16x32_bf16 v[38:41], v[162:165], v[186:189], v[38:41]
	v_mfma_f32_16x16x32_bf16 v[30:33], v[170:173], v[186:189], v[30:33]
	v_mfma_f32_16x16x32_bf16 v[22:25], v[162:165], v[194:197], v[22:25]
	v_mfma_f32_16x16x32_bf16 v[14:17], v[170:173], v[194:197], v[14:17]
	v_mfma_f32_16x16x32_bf16 v[6:9], v[162:165], v[202:205], v[6:9]
	v_mfma_f32_16x16x32_bf16 v[2:5], v[170:173], v[202:205], v[2:5]
	v_mfma_f32_16x16x32_bf16 v[54:57], v[166:169], v[182:185], v[54:57]
	v_mfma_f32_16x16x32_bf16 v[46:49], v[174:177], v[182:185], v[46:49]
	v_mfma_f32_16x16x32_bf16 v[38:41], v[166:169], v[190:193], v[38:41]
	v_mfma_f32_16x16x32_bf16 v[30:33], v[174:177], v[190:193], v[30:33]
	v_mfma_f32_16x16x32_bf16 v[22:25], v[166:169], v[198:201], v[22:25]
	v_mfma_f32_16x16x32_bf16 v[14:17], v[174:177], v[198:201], v[14:17]
	v_mfma_f32_16x16x32_bf16 v[6:9], v[166:169], v[206:209], v[6:9]
	v_mfma_f32_16x16x32_bf16 v[2:5], v[174:177], v[206:209], v[2:5]
	s_setprio 0
	s_barrier
	v_lshl_add_u64 v[140:141], v[212:213], 0, s[10:11]
	s_mov_b32 m0, s49
	s_nop 0
	global_load_lds_dwordx4 v[140:141], off
	v_lshl_add_u64 v[140:141], v[214:215], 0, s[10:11]
	s_mov_b32 m0, s50
	s_nop 0
	global_load_lds_dwordx4 v[140:141], off
	s_add_i32 s30, s62, 2
	s_cmp_gt_u32 s62, 61
	s_mov_b32 s62, s30
	s_cbranch_scc1 .LBB0_1770

; #define PG8_STAGE(bufoff, gbase, voff) do { _Pragma("unroll") for (int _i = 0; _i < 2; ++_i) \
;         __builtin_amdgcn_global_load_lds((const unsigned*)((const char*)(gbase) + (voff)[_i]), (PG8_LAS unsigned*)(lds + (bufoff) + ldsw + _i * 8192), 16, 0, 0); } while (0)
; #define PG8_LDA(dst, b, h) do { _Pragma("unroll") for (int m = 0; m < 4; ++m) _Pragma("unroll") for (int k = 0; k < 2; ++k) dst[m][k] = *(const PG8_LAS bf16x8*)(lds + PG8_SA(b, h) + aoff + m * 2048 + k * 1024); } while (0)
; #define PG8_LDB(dst, b, h) do { _Pragma("unroll") for (int n = 0; n < 2; ++n) _Pragma("unroll") for (int k = 0; k < 2; ++k) dst[n][k] = *(const PG8_LAS bf16x8*)(lds + PG8_SB(b, h) + boff + n * 2048 + k * 1024); } while (0)
; #define PG8_MMA(ai, bj, At, Bt) do { __builtin_amdgcn_s_setprio(1); _Pragma("unroll") for (int m = 0; m < 4; ++m) _Pragma("unroll") for (int n = 0; n < 2; ++n) _Pragma("unroll") for (int k = 0; k < 2; ++k) \
;         acc[ai][bj][m][n] = __builtin_amdgcn_mfma_f32_16x16x32_bf16(Bt[n][k], At[m][k], acc[ai][bj][m][n], 0, 0, 0); __builtin_amdgcn_s_setprio(0); } while (0)
; #define PG8_WAIT_V(n) asm volatile("s_waitcnt vmcnt(" #n ")" ::: "memory")
; #define PG8_WAIT_L(n) asm volatile("s_waitcnt lgkmcnt(" #n ")" ::: "memory")
; #define PG8_BAR __builtin_amdgcn_s_barrier()
; #define PG8_SCHED __builtin_amdgcn_sched_barrier(0)
; template <class Epi, class Sched, bool ALIGN_EPI = false, bool SP2 = false>
; __device__ __forceinline__ void gemm_phase(PG8_LAS unsigned char* lds, const Gemm g, const Sched& S, const Epi& E) {
;     ...
;         for (int t = 0; t < nt; t += 2) {
;             const bool last = (t == nt - 2);
;             const char* a1 = cA + (size_t)(t + 1) * kstep;
;             const char* a2 = last ? nA : cA + (size_t)(t + 2) * kstep; const char* b2 = last ? nB : cB + (size_t)(t + 2) * kstep;
;             const char* a3 = a2 + kstep; const char* b3 = b2 + kstep;
;             if (last && has_next) S.a_ready(nxt);
;             if constexpr (SP2) {
;             PG8_LDB(B0, 0, 0); PG8_LDB(B1, 0, 1); PG8_SCHED; PG8_LDA(At, 0, 0); PG8_STAGE(PG8_SA(1, 1), a1 + hstepA, voffA);
;             PG8_WAIT_V(8); PG8_WAIT_L(0); PG8_BAR; PG8_MMA(0, 0, At, B0); PG8_MMA(0, 1, At, B1); PG8_BAR; PG8_SCHED;
;             PG8_LDA(At, 0, 1); PG8_STAGE(PG8_SB(0, 0), b2, voffB); PG8_STAGE(PG8_SB(0, 1), b2 + hstepB, voffB); PG8_STAGE(PG8_SA(0, 0), a2, voffA);
.LBB0_1868:
	ds_read_b128 v[160:163], v156
	ds_read_b128 v[164:167], v156 offset:1024
	ds_read_b128 v[168:171], v156 offset:2048
	ds_read_b128 v[172:175], v156 offset:3072
	ds_read_b128 v[176:179], v157
	ds_read_b128 v[180:183], v157 offset:1024
	ds_read_b128 v[184:187], v157 offset:2048
	ds_read_b128 v[188:191], v157 offset:3072
	s_add_u32 s34, s30, 0xfff00080
	s_addc_u32 s35, s31, -1
	s_cmp_eq_u32 s61, 60
	s_cselect_b32 s37, s23, s35
	s_cselect_b32 s36, s57, s34
	s_cselect_b32 s35, s21, s60
	s_cselect_b32 s34, s58, s59
	v_lshl_add_u64 v[146:147], s[30:31], 0, v[138:139]
	s_add_i32 m0, s29, 0xc000
	ds_read_b128 v[192:195], v158
	ds_read_b128 v[196:199], v158 offset:1024
	ds_read_b128 v[200:203], v158 offset:2048
	ds_read_b128 v[204:207], v158 offset:3072
	ds_read_b128 v[208:211], v158 offset:4096
	ds_read_b128 v[212:215], v158 offset:5120
	ds_read_b128 v[218:221], v158 offset:6144
	ds_read_b128 v[222:225], v158 offset:7168
	global_load_lds_dwordx4 v[146:147], off
	v_lshl_add_u64 v[146:147], s[30:31], 0, v[140:141]
	s_add_i32 m0, s29, 0xe000
	s_nop 0
	global_load_lds_dwordx4 v[146:147], off
	s_waitcnt vmcnt(8)
	s_waitcnt lgkmcnt(0)
	s_barrier
	s_setprio 1
	s_waitcnt lgkmcnt(0)
	v_mfma_f32_16x16x32_bf16 v[126:129], v[160:163], v[192:195], v[126:129]
	v_mfma_f32_16x16x32_bf16 v[122:125], v[168:171], v[192:195], v[122:125]
	v_mfma_f32_16x16x32_bf16 v[114:117], v[160:163], v[200:203], v[114:117]
	v_mfma_f32_16x16x32_bf16 v[106:109], v[168:171], v[200:203], v[106:109]
	v_mfma_f32_16x16x32_bf16 v[98:101], v[160:163], v[208:211], v[98:101]
	v_mfma_f32_16x16x32_bf16 v[90:93], v[168:171], v[208:211], v[90:93]
	v_mfma_f32_16x16x32_bf16 v[82:85], v[160:163], v[218:221], v[82:85]
	v_mfma_f32_16x16x32_bf16 v[74:77], v[168:171], v[218:221], v[74:77]
	v_mfma_f32_16x16x32_bf16 v[126:129], v[164:167], v[196:199], v[126:129]
	v_mfma_f32_16x16x32_bf16 v[122:125], v[172:175], v[196:199], v[122:125]
	v_mfma_f32_16x16x32_bf16 v[114:117], v[164:167], v[204:207], v[114:117]
	v_mfma_f32_16x16x32_bf16 v[106:109], v[172:175], v[204:207], v[106:109]
	v_mfma_f32_16x16x32_bf16 v[98:101], v[164:167], v[212:215], v[98:101]
	v_mfma_f32_16x16x32_bf16 v[90:93], v[172:175], v[212:215], v[90:93]
	v_mfma_f32_16x16x32_bf16 v[82:85], v[164:167], v[222:225], v[82:85]
	v_mfma_f32_16x16x32_bf16 v[74:77], v[172:175], v[222:225], v[74:77]
	s_setprio 0
	s_setprio 1
	v_mfma_f32_16x16x32_bf16 v[118:121], v[176:179], v[192:195], v[118:121]
	v_mfma_f32_16x16x32_bf16 v[110:113], v[184:187], v[192:195], v[110:113]
	v_mfma_f32_16x16x32_bf16 v[102:105], v[176:179], v[200:203], v[102:105]
	v_mfma_f32_16x16x32_bf16 v[94:97], v[184:187], v[200:203], v[94:97]
	v_mfma_f32_16x16x32_bf16 v[86:89], v[176:179], v[208:211], v[86:89]
	v_mfma_f32_16x16x32_bf16 v[78:81], v[184:187], v[208:211], v[78:81]
	v_mfma_f32_16x16x32_bf16 v[70:73], v[176:179], v[218:221], v[70:73]
	v_mfma_f32_16x16x32_bf16 v[66:69], v[184:187], v[218:221], v[66:69]
	v_mfma_f32_16x16x32_bf16 v[118:121], v[180:183], v[196:199], v[118:121]
	v_mfma_f32_16x16x32_bf16 v[110:113], v[188:191], v[196:199], v[110:113]
	v_mfma_f32_16x16x32_bf16 v[102:105], v[180:183], v[204:207], v[102:105]
	v_mfma_f32_16x16x32_bf16 v[94:97], v[188:191], v[204:207], v[94:97]
	v_mfma_f32_16x16x32_bf16 v[86:89], v[180:183], v[212:215], v[86:89]
	v_mfma_f32_16x16x32_bf16 v[78:81], v[188:191], v[212:215], v[78:81]
	v_mfma_f32_16x16x32_bf16 v[70:73], v[180:183], v[222:225], v[70:73]
	v_mfma_f32_16x16x32_bf16 v[66:69], v[188:191], v[222:225], v[66:69]
	s_setprio 0
	s_barrier
	s_add_i32 s62, s50, s42
	v_lshl_add_u64 v[146:147], s[34:35], 0, v[132:133]
	s_mov_b32 m0, s62
	ds_read_b128 v[192:195], v158 offset:16384
	ds_read_b128 v[196:199], v158 offset:17408
	ds_read_b128 v[200:203], v158 offset:18432
	ds_read_b128 v[204:207], v158 offset:19456
	ds_read_b128 v[208:211], v158 offset:20480
	ds_read_b128 v[212:215], v158 offset:21504
	ds_read_b128 v[218:221], v158 offset:22528
	ds_read_b128 v[222:225], v158 offset:23552
	global_load_lds_dwordx4 v[146:147], off
	s_add_i32 m0, s62, 0x2000
	s_add_u32 s62, s34, 0x100000
	v_lshl_add_u64 v[226:227], s[34:35], 0, v[136:137]
	s_addc_u32 s63, s35, 0
	s_add_i32 s64, s51, s42
	global_load_lds_dwordx4 v[226:227], off
	v_lshl_add_u64 v[228:229], s[62:63], 0, v[132:133]
	s_mov_b32 m0, s64
	v_lshl_add_u64 v[230:231], s[36:37], 0, v[134:135]
	global_load_lds_dwordx4 v[228:229], off
	v_lshl_add_u64 v[228:229], s[62:63], 0, v[136:137]
	s_add_i32 m0, s64, 0x2000
	s_nop 0
	global_load_lds_dwordx4 v[228:229], off
	v_lshl_add_u64 v[228:229], s[36:37], 0, v[130:131]
	s_waitcnt vmcnt(6)
	s_waitcnt lgkmcnt(0)
	s_barrier
; #define PG8_STAGE(bufoff, gbase, voff) do { _Pragma("unroll") for (int _i = 0; _i < 2; ++_i) \
;         __builtin_amdgcn_global_load_lds((const unsigned*)((const char*)(gbase) + (voff)[_i]), (PG8_LAS unsigned*)(lds + (bufoff) + ldsw + _i * 8192), 16, 0, 0); } while (0)
; #define PG8_LDA(dst, b, h) do { _Pragma("unroll") for (int m = 0; m < 4; ++m) _Pragma("unroll") for (int k = 0; k < 2; ++k) dst[m][k] = *(const PG8_LAS bf16x8*)(lds + PG8_SA(b, h) + aoff + m * 2048 + k * 1024); } while (0)
; #define PG8_LDB(dst, b, h) do { _Pragma("unroll") for (int n = 0; n < 2; ++n) _Pragma("unroll") for (int k = 0; k < 2; ++k) dst[n][k] = *(const PG8_LAS bf16x8*)(lds + PG8_SB(b, h) + boff + n * 2048 + k * 1024); } while (0)
; #define PG8_MMA(ai, bj, At, Bt) do { __builtin_amdgcn_s_setprio(1); _Pragma("unroll") for (int m = 0; m < 4; ++m) _Pragma("unroll") for (int n = 0; n < 2; ++n) _Pragma("unroll") for (int k = 0; k < 2; ++k) \
;         acc[ai][bj][m][n] = __builtin_amdgcn_mfma_f32_16x16x32_bf16(Bt[n][k], At[m][k], acc[ai][bj][m][n], 0, 0, 0); __builtin_amdgcn_s_setprio(0); } while (0)
; #define PG8_WAIT_V(n) asm volatile("s_waitcnt vmcnt(" #n ")" ::: "memory")
; #define PG8_WAIT_L(n) asm volatile("s_waitcnt lgkmcnt(" #n ")" ::: "memory")
; #define PG8_BAR __builtin_amdgcn_s_barrier()
; #define PG8_SCHED __builtin_amdgcn_sched_barrier(0)
; template <class Epi, class Sched, bool ALIGN_EPI = false, bool SP2 = false>
; __device__ __forceinline__ void gemm_phase(PG8_LAS unsigned char* lds, const Gemm g, const Sched& S, const Epi& E) {
;     ...
;             PG8_WAIT_V(8); PG8_WAIT_L(0); PG8_BAR; PG8_MMA(1, 0, At, B0); PG8_MMA(1, 1, At, B1); PG8_BAR; PG8_SCHED;
;             PG8_LDB(B0, 1, 0); PG8_LDB(B1, 1, 1); PG8_SCHED; PG8_LDA(At, 1, 0); PG8_STAGE(PG8_SA(0, 1), a2 + hstepA, voffA);
;             PG8_WAIT_V(8); PG8_WAIT_L(0); PG8_BAR; PG8_MMA(0, 0, At, B0); PG8_MMA(0, 1, At, B1); PG8_BAR; PG8_SCHED;
;             PG8_LDA(At, 1, 1); PG8_STAGE(PG8_SB(1, 0), b3, voffB); PG8_STAGE(PG8_SB(1, 1), b3 + hstepB, voffB); PG8_STAGE(PG8_SA(1, 0), a3, voffA);
	s_setprio 1
	s_waitcnt lgkmcnt(0)
	v_mfma_f32_16x16x32_bf16 v[62:65], v[160:163], v[192:195], v[62:65]
	v_mfma_f32_16x16x32_bf16 v[58:61], v[168:171], v[192:195], v[58:61]
	v_mfma_f32_16x16x32_bf16 v[50:53], v[160:163], v[200:203], v[50:53]
	v_mfma_f32_16x16x32_bf16 v[42:45], v[168:171], v[200:203], v[42:45]
	v_mfma_f32_16x16x32_bf16 v[34:37], v[160:163], v[208:211], v[34:37]
	v_mfma_f32_16x16x32_bf16 v[26:29], v[168:171], v[208:211], v[26:29]
	v_mfma_f32_16x16x32_bf16 v[18:21], v[160:163], v[218:221], v[18:21]
	v_mfma_f32_16x16x32_bf16 v[10:13], v[168:171], v[218:221], v[10:13]
	v_mfma_f32_16x16x32_bf16 v[62:65], v[164:167], v[196:199], v[62:65]
	v_mfma_f32_16x16x32_bf16 v[58:61], v[172:175], v[196:199], v[58:61]
	v_mfma_f32_16x16x32_bf16 v[50:53], v[164:167], v[204:207], v[50:53]
	v_mfma_f32_16x16x32_bf16 v[42:45], v[172:175], v[204:207], v[42:45]
	v_mfma_f32_16x16x32_bf16 v[34:37], v[164:167], v[212:215], v[34:37]
	v_mfma_f32_16x16x32_bf16 v[26:29], v[172:175], v[212:215], v[26:29]
	v_mfma_f32_16x16x32_bf16 v[18:21], v[164:167], v[222:225], v[18:21]
	v_mfma_f32_16x16x32_bf16 v[10:13], v[172:175], v[222:225], v[10:13]
	s_setprio 0
	s_setprio 1
	v_mfma_f32_16x16x32_bf16 v[54:57], v[176:179], v[192:195], v[54:57]
	v_mfma_f32_16x16x32_bf16 v[46:49], v[184:187], v[192:195], v[46:49]
	v_mfma_f32_16x16x32_bf16 v[38:41], v[176:179], v[200:203], v[38:41]
	v_mfma_f32_16x16x32_bf16 v[30:33], v[184:187], v[200:203], v[30:33]
	v_mfma_f32_16x16x32_bf16 v[22:25], v[176:179], v[208:211], v[22:25]
	v_mfma_f32_16x16x32_bf16 v[14:17], v[184:187], v[208:211], v[14:17]
	v_mfma_f32_16x16x32_bf16 v[6:9], v[176:179], v[218:221], v[6:9]
	v_mfma_f32_16x16x32_bf16 v[2:5], v[184:187], v[218:221], v[2:5]
	v_mfma_f32_16x16x32_bf16 v[54:57], v[180:183], v[196:199], v[54:57]
	v_mfma_f32_16x16x32_bf16 v[46:49], v[188:191], v[196:199], v[46:49]
	v_mfma_f32_16x16x32_bf16 v[38:41], v[180:183], v[204:207], v[38:41]
	v_mfma_f32_16x16x32_bf16 v[30:33], v[188:191], v[204:207], v[30:33]
	v_mfma_f32_16x16x32_bf16 v[22:25], v[180:183], v[212:215], v[22:25]
	v_mfma_f32_16x16x32_bf16 v[14:17], v[188:191], v[212:215], v[14:17]
	v_mfma_f32_16x16x32_bf16 v[6:9], v[180:183], v[222:225], v[6:9]
	v_mfma_f32_16x16x32_bf16 v[2:5], v[188:191], v[222:225], v[2:5]
	s_setprio 0
	s_barrier
	s_mov_b32 m0, s29
	s_nop 0
	global_load_lds_dwordx4 v[228:229], off
	s_mov_b32 m0, s43
	s_nop 0
	global_load_lds_dwordx4 v[230:231], off
	s_add_i32 s62, 0, 0x18000
	v_add_u32_e32 v159, s62, v154
	s_add_i32 s63, 0, 0x1c000
	ds_read_b128 v[160:163], v159
	ds_read_b128 v[164:167], v159 offset:1024
	ds_read_b128 v[168:171], v159 offset:2048
	ds_read_b128 v[172:175], v159 offset:3072
	v_add_u32_e32 v159, s63, v154
	ds_read_b128 v[176:179], v159
	ds_read_b128 v[180:183], v159 offset:1024
	ds_read_b128 v[184:187], v159 offset:2048
	ds_read_b128 v[188:191], v159 offset:3072
	s_add_u32 s36, s36, 0x100000
	s_addc_u32 s37, s37, 0
	s_mov_b32 m0, s44
	v_lshl_add_u64 v[232:233], s[36:37], 0, v[130:131]
	ds_read_b128 v[192:195], v158 offset:32768
	ds_read_b128 v[196:199], v158 offset:33792
	ds_read_b128 v[200:203], v158 offset:34816
	ds_read_b128 v[204:207], v158 offset:35840
	ds_read_b128 v[208:211], v158 offset:36864
	ds_read_b128 v[212:215], v158 offset:37888
	ds_read_b128 v[218:221], v158 offset:38912
	ds_read_b128 v[222:225], v158 offset:39936
	global_load_lds_dwordx4 v[232:233], off
	v_lshl_add_u64 v[232:233], s[36:37], 0, v[134:135]
	s_mov_b32 m0, s45
	s_nop 0
	global_load_lds_dwordx4 v[232:233], off
	s_waitcnt vmcnt(8)
	s_waitcnt lgkmcnt(0)
	s_barrier
	s_setprio 1
	s_waitcnt lgkmcnt(0)
	v_mfma_f32_16x16x32_bf16 v[126:129], v[160:163], v[192:195], v[126:129]
	v_mfma_f32_16x16x32_bf16 v[122:125], v[168:171], v[192:195], v[122:125]
	v_mfma_f32_16x16x32_bf16 v[114:117], v[160:163], v[200:203], v[114:117]
	v_mfma_f32_16x16x32_bf16 v[106:109], v[168:171], v[200:203], v[106:109]
	v_mfma_f32_16x16x32_bf16 v[98:101], v[160:163], v[208:211], v[98:101]
	v_mfma_f32_16x16x32_bf16 v[90:93], v[168:171], v[208:211], v[90:93]
	v_mfma_f32_16x16x32_bf16 v[82:85], v[160:163], v[218:221], v[82:85]
	v_mfma_f32_16x16x32_bf16 v[74:77], v[168:171], v[218:221], v[74:77]
	v_mfma_f32_16x16x32_bf16 v[126:129], v[164:167], v[196:199], v[126:129]
	v_mfma_f32_16x16x32_bf16 v[122:125], v[172:175], v[196:199], v[122:125]
	v_mfma_f32_16x16x32_bf16 v[114:117], v[164:167], v[204:207], v[114:117]
	v_mfma_f32_16x16x32_bf16 v[106:109], v[172:175], v[204:207], v[106:109]
	v_mfma_f32_16x16x32_bf16 v[98:101], v[164:167], v[212:215], v[98:101]
	v_mfma_f32_16x16x32_bf16 v[90:93], v[172:175], v[212:215], v[90:93]
	v_mfma_f32_16x16x32_bf16 v[82:85], v[164:167], v[222:225], v[82:85]
	v_mfma_f32_16x16x32_bf16 v[74:77], v[172:175], v[222:225], v[74:77]
	s_setprio 0
	s_setprio 1
	v_mfma_f32_16x16x32_bf16 v[118:121], v[176:179], v[192:195], v[118:121]
	v_mfma_f32_16x16x32_bf16 v[110:113], v[184:187], v[192:195], v[110:113]
	v_mfma_f32_16x16x32_bf16 v[102:105], v[176:179], v[200:203], v[102:105]
	v_mfma_f32_16x16x32_bf16 v[94:97], v[184:187], v[200:203], v[94:97]
	v_mfma_f32_16x16x32_bf16 v[86:89], v[176:179], v[208:211], v[86:89]
	v_mfma_f32_16x16x32_bf16 v[78:81], v[184:187], v[208:211], v[78:81]
	v_mfma_f32_16x16x32_bf16 v[70:73], v[176:179], v[218:221], v[70:73]
	v_mfma_f32_16x16x32_bf16 v[66:69], v[184:187], v[218:221], v[66:69]
	v_mfma_f32_16x16x32_bf16 v[118:121], v[180:183], v[196:199], v[118:121]
	v_mfma_f32_16x16x32_bf16 v[110:113], v[188:191], v[196:199], v[110:113]
	v_mfma_f32_16x16x32_bf16 v[102:105], v[180:183], v[204:207], v[102:105]
	v_mfma_f32_16x16x32_bf16 v[94:97], v[188:191], v[204:207], v[94:97]
	v_mfma_f32_16x16x32_bf16 v[86:89], v[180:183], v[212:215], v[86:89]
	v_mfma_f32_16x16x32_bf16 v[78:81], v[188:191], v[212:215], v[78:81]
	v_mfma_f32_16x16x32_bf16 v[70:73], v[180:183], v[222:225], v[70:73]
	v_mfma_f32_16x16x32_bf16 v[66:69], v[188:191], v[222:225], v[66:69]
	s_setprio 0
	s_barrier
; #define PG8_STAGE(bufoff, gbase, voff) do { _Pragma("unroll") for (int _i = 0; _i < 2; ++_i) \
;         __builtin_amdgcn_global_load_lds((const unsigned*)((const char*)(gbase) + (voff)[_i]), (PG8_LAS unsigned*)(lds + (bufoff) + ldsw + _i * 8192), 16, 0, 0); } while (0)
; #define PG8_LDA(dst, b, h) do { _Pragma("unroll") for (int m = 0; m < 4; ++m) _Pragma("unroll") for (int k = 0; k < 2; ++k) dst[m][k] = *(const PG8_LAS bf16x8*)(lds + PG8_SA(b, h) + aoff + m * 2048 + k * 1024); } while (0)
; #define PG8_MMA(ai, bj, At, Bt) do { __builtin_amdgcn_s_setprio(1); _Pragma("unroll") for (int m = 0; m < 4; ++m) _Pragma("unroll") for (int n = 0; n < 2; ++n) _Pragma("unroll") for (int k = 0; k < 2; ++k) \
;         acc[ai][bj][m][n] = __builtin_amdgcn_mfma_f32_16x16x32_bf16(Bt[n][k], At[m][k], acc[ai][bj][m][n], 0, 0, 0); __builtin_amdgcn_s_setprio(0); } while (0)
; #define PG8_WAIT_V(n) asm volatile("s_waitcnt vmcnt(" #n ")" ::: "memory")
; #define PG8_WAIT_L(n) asm volatile("s_waitcnt lgkmcnt(" #n ")" ::: "memory")
; #define PG8_BAR __builtin_amdgcn_s_barrier()
; #define PG8_SCHED __builtin_amdgcn_sched_barrier(0)
; template <class Epi, class Sched, bool ALIGN_EPI = false, bool SP2 = false>
; __device__ __forceinline__ void gemm_phase(PG8_LAS unsigned char* lds, const Gemm g, const Sched& S, const Epi& E) {
;     ...
;             PG8_LDA(At, 1, 1); PG8_STAGE(PG8_SB(1, 0), b3, voffB); PG8_STAGE(PG8_SB(1, 1), b3 + hstepB, voffB); PG8_STAGE(PG8_SA(1, 0), a3, voffA);
;             PG8_WAIT_V(8); PG8_WAIT_L(0); PG8_BAR; PG8_MMA(1, 0, At, B0); PG8_MMA(1, 1, At, B1); PG8_BAR; PG8_SCHED;
	s_add_i32 s36, s62, s42
	v_lshl_add_u64 v[146:147], v[146:147], 0, s[10:11]
	s_mov_b32 m0, s36
	ds_read_b128 v[192:195], v158 offset:49152
	ds_read_b128 v[196:199], v158 offset:50176
	ds_read_b128 v[200:203], v158 offset:51200
	ds_read_b128 v[204:207], v158 offset:52224
	ds_read_b128 v[208:211], v158 offset:53248
	ds_read_b128 v[212:215], v158 offset:54272
	ds_read_b128 v[218:221], v158 offset:55296
	ds_read_b128 v[222:225], v158 offset:56320
	global_load_lds_dwordx4 v[146:147], off
	s_add_i32 m0, s36, 0x2000
	s_add_u32 s34, s34, 0x100080
	v_lshl_add_u64 v[146:147], v[226:227], 0, s[10:11]
	s_addc_u32 s35, s35, 0
	s_add_i32 s36, s63, s42
	global_load_lds_dwordx4 v[146:147], off
	v_lshl_add_u64 v[146:147], s[34:35], 0, v[132:133]
	s_mov_b32 m0, s36
	s_nop 0
	global_load_lds_dwordx4 v[146:147], off
	v_lshl_add_u64 v[146:147], s[34:35], 0, v[136:137]
	s_add_i32 m0, s36, 0x2000
	s_nop 0
	global_load_lds_dwordx4 v[146:147], off
	s_waitcnt vmcnt(6)
	s_waitcnt lgkmcnt(0)
	s_barrier
	s_setprio 1
	s_waitcnt lgkmcnt(0)
	v_mfma_f32_16x16x32_bf16 v[62:65], v[160:163], v[192:195], v[62:65]
	v_mfma_f32_16x16x32_bf16 v[58:61], v[168:171], v[192:195], v[58:61]
	v_mfma_f32_16x16x32_bf16 v[50:53], v[160:163], v[200:203], v[50:53]
	v_mfma_f32_16x16x32_bf16 v[42:45], v[168:171], v[200:203], v[42:45]
	v_mfma_f32_16x16x32_bf16 v[34:37], v[160:163], v[208:211], v[34:37]
	v_mfma_f32_16x16x32_bf16 v[26:29], v[168:171], v[208:211], v[26:29]
	v_mfma_f32_16x16x32_bf16 v[18:21], v[160:163], v[218:221], v[18:21]
	v_mfma_f32_16x16x32_bf16 v[10:13], v[168:171], v[218:221], v[10:13]
	v_mfma_f32_16x16x32_bf16 v[62:65], v[164:167], v[196:199], v[62:65]
	v_mfma_f32_16x16x32_bf16 v[58:61], v[172:175], v[196:199], v[58:61]
	v_mfma_f32_16x16x32_bf16 v[50:53], v[164:167], v[204:207], v[50:53]
	v_mfma_f32_16x16x32_bf16 v[42:45], v[172:175], v[204:207], v[42:45]
	v_mfma_f32_16x16x32_bf16 v[34:37], v[164:167], v[212:215], v[34:37]
	v_mfma_f32_16x16x32_bf16 v[26:29], v[172:175], v[212:215], v[26:29]
	v_mfma_f32_16x16x32_bf16 v[18:21], v[164:167], v[222:225], v[18:21]
	v_mfma_f32_16x16x32_bf16 v[10:13], v[172:175], v[222:225], v[10:13]
	s_setprio 0
	s_setprio 1
	v_mfma_f32_16x16x32_bf16 v[54:57], v[176:179], v[192:195], v[54:57]
	v_mfma_f32_16x16x32_bf16 v[46:49], v[184:187], v[192:195], v[46:49]
	v_mfma_f32_16x16x32_bf16 v[38:41], v[176:179], v[200:203], v[38:41]
	v_mfma_f32_16x16x32_bf16 v[30:33], v[184:187], v[200:203], v[30:33]
	v_mfma_f32_16x16x32_bf16 v[22:25], v[176:179], v[208:211], v[22:25]
	v_mfma_f32_16x16x32_bf16 v[14:17], v[184:187], v[208:211], v[14:17]
	v_mfma_f32_16x16x32_bf16 v[6:9], v[176:179], v[218:221], v[6:9]
	v_mfma_f32_16x16x32_bf16 v[2:5], v[184:187], v[218:221], v[2:5]
	v_mfma_f32_16x16x32_bf16 v[54:57], v[180:183], v[196:199], v[54:57]
	v_mfma_f32_16x16x32_bf16 v[46:49], v[188:191], v[196:199], v[46:49]
	v_mfma_f32_16x16x32_bf16 v[38:41], v[180:183], v[204:207], v[38:41]
	v_mfma_f32_16x16x32_bf16 v[30:33], v[188:191], v[204:207], v[30:33]
	v_mfma_f32_16x16x32_bf16 v[22:25], v[180:183], v[212:215], v[22:25]
	v_mfma_f32_16x16x32_bf16 v[14:17], v[188:191], v[212:215], v[14:17]
	v_mfma_f32_16x16x32_bf16 v[6:9], v[180:183], v[222:225], v[6:9]
	v_mfma_f32_16x16x32_bf16 v[2:5], v[188:191], v[222:225], v[2:5]
	s_setprio 0
	s_barrier
	v_lshl_add_u64 v[146:147], v[228:229], 0, s[10:11]
	s_mov_b32 m0, s47
	s_nop 0
	global_load_lds_dwordx4 v[146:147], off
	v_lshl_add_u64 v[146:147], v[230:231], 0, s[10:11]
	s_mov_b32 m0, s48
	s_nop 0
	global_load_lds_dwordx4 v[146:147], off
	s_add_i32 s61, s61, 2
	s_add_u32 s30, s30, 0x100
	s_addc_u32 s31, s31, 0
	s_add_u32 s59, s59, 0x100
	s_addc_u32 s60, s60, 0
	s_cmp_gt_u32 s61, 61
	s_cbranch_scc0 .LBB0_1868
	s_and_b64 vcc, exec, s[12:13]
	s_cbranch_vccz .LBB0_1871
	s_barrier

; #define PG8_STAGE(bufoff, gbase, voff) do { _Pragma("unroll") for (int _i = 0; _i < 2; ++_i) \
;         __builtin_amdgcn_global_load_lds((const unsigned*)((const char*)(gbase) + (voff)[_i]), (PG8_LAS unsigned*)(lds + (bufoff) + ldsw + _i * 8192), 16, 0, 0); } while (0)
; #define PG8_LDA(dst, b, h) do { _Pragma("unroll") for (int m = 0; m < 4; ++m) _Pragma("unroll") for (int k = 0; k < 2; ++k) dst[m][k] = *(const PG8_LAS bf16x8*)(lds + PG8_SA(b, h) + aoff + m * 2048 + k * 1024); } while (0)
; #define PG8_LDB(dst, b, h) do { _Pragma("unroll") for (int n = 0; n < 2; ++n) _Pragma("unroll") for (int k = 0; k < 2; ++k) dst[n][k] = *(const PG8_LAS bf16x8*)(lds + PG8_SB(b, h) + boff + n * 2048 + k * 1024); } while (0)
; #define PG8_MMA(ai, bj, At, Bt) do { __builtin_amdgcn_s_setprio(1); _Pragma("unroll") for (int m = 0; m < 4; ++m) _Pragma("unroll") for (int n = 0; n < 2; ++n) _Pragma("unroll") for (int k = 0; k < 2; ++k) \
;         acc[ai][bj][m][n] = __builtin_amdgcn_mfma_f32_16x16x32_bf16(Bt[n][k], At[m][k], acc[ai][bj][m][n], 0, 0, 0); __builtin_amdgcn_s_setprio(0); } while (0)
; #define PG8_WAIT_V(n) asm volatile("s_waitcnt vmcnt(" #n ")" ::: "memory")
; #define PG8_WAIT_L(n) asm volatile("s_waitcnt lgkmcnt(" #n ")" ::: "memory")
; #define PG8_BAR __builtin_amdgcn_s_barrier()
; #define PG8_SCHED __builtin_amdgcn_sched_barrier(0)
; template <class Epi, class Sched, bool ALIGN_EPI = false, bool SP2 = false>
; __device__ __forceinline__ void gemm_phase(PG8_LAS unsigned char* lds, const Gemm g, const Sched& S, const Epi& E) {
;     ...
;         for (int t = 0; t < nt; t += 2) {
;             const bool last = (t == nt - 2);
;             const char* a1 = cA + (size_t)(t + 1) * kstep;
;             const char* a2 = last ? nA : cA + (size_t)(t + 2) * kstep; const char* b2 = last ? nB : cB + (size_t)(t + 2) * kstep;
;             const char* a3 = a2 + kstep; const char* b3 = b2 + kstep;
;             if (last && has_next) S.a_ready(nxt);
;             if constexpr (SP2) {
;             PG8_LDB(B0, 0, 0); PG8_LDB(B1, 0, 1); PG8_SCHED; PG8_LDA(At, 0, 0); PG8_STAGE(PG8_SA(1, 1), a1 + hstepA, voffA);
;             PG8_WAIT_V(8); PG8_WAIT_L(0); PG8_BAR; PG8_MMA(0, 0, At, B0); PG8_MMA(0, 1, At, B1); PG8_BAR; PG8_SCHED;
;             PG8_LDA(At, 0, 1); PG8_STAGE(PG8_SB(0, 0), b2, voffB); PG8_STAGE(PG8_SB(0, 1), b2 + hstepB, voffB); PG8_STAGE(PG8_SA(0, 0), a2, voffA);
.LBB0_1880:
	ds_read_b128 v[148:151], v143
	ds_read_b128 v[152:155], v143 offset:1024
	ds_read_b128 v[156:159], v143 offset:2048
	ds_read_b128 v[160:163], v143 offset:3072
	ds_read_b128 v[164:167], v144
	ds_read_b128 v[168:171], v144 offset:1024
	ds_read_b128 v[172:175], v144 offset:2048
	ds_read_b128 v[176:179], v144 offset:3072
	s_add_u32 s16, s12, s14
	s_addc_u32 s17, s13, s15
	s_add_u32 s16, s16, 0x34000100
	s_addc_u32 s17, s17, 0
	s_add_u32 s42, s28, s14
	s_addc_u32 s43, s29, s15
	s_cmpk_eq_i32 s14, 0x1f00
	s_cselect_b32 s19, s9, s17
	s_cselect_b32 s18, s8, s16
	s_cselect_b32 s17, s7, s43
	s_cselect_b32 s16, s6, s42
	s_mov_b32 m0, s31
	v_lshl_add_u64 v[212:213], v[138:139], 0, s[14:15]
	ds_read_b128 v[180:183], v145
	ds_read_b128 v[184:187], v145 offset:1024
	ds_read_b128 v[188:191], v145 offset:2048
	ds_read_b128 v[192:195], v145 offset:3072
	ds_read_b128 v[196:199], v145 offset:4096
	ds_read_b128 v[200:203], v145 offset:5120
	ds_read_b128 v[204:207], v145 offset:6144
	ds_read_b128 v[208:211], v145 offset:7168
	global_load_lds_dwordx4 v[212:213], off
	v_lshl_add_u64 v[212:213], v[140:141], 0, s[14:15]
	s_mov_b32 m0, s33
	s_nop 0
	global_load_lds_dwordx4 v[212:213], off
	s_waitcnt vmcnt(8)
	s_waitcnt lgkmcnt(0)
	s_barrier
	s_setprio 1
	s_waitcnt lgkmcnt(0)
	v_mfma_f32_16x16x32_bf16 v[126:129], v[148:151], v[180:183], v[126:129]
	v_mfma_f32_16x16x32_bf16 v[122:125], v[156:159], v[180:183], v[122:125]
	v_mfma_f32_16x16x32_bf16 v[114:117], v[148:151], v[188:191], v[114:117]
	v_mfma_f32_16x16x32_bf16 v[106:109], v[156:159], v[188:191], v[106:109]
	v_mfma_f32_16x16x32_bf16 v[98:101], v[148:151], v[196:199], v[98:101]
	v_mfma_f32_16x16x32_bf16 v[90:93], v[156:159], v[196:199], v[90:93]
	v_mfma_f32_16x16x32_bf16 v[82:85], v[148:151], v[204:207], v[82:85]
	v_mfma_f32_16x16x32_bf16 v[74:77], v[156:159], v[204:207], v[74:77]
	v_mfma_f32_16x16x32_bf16 v[126:129], v[152:155], v[184:187], v[126:129]
	v_mfma_f32_16x16x32_bf16 v[122:125], v[160:163], v[184:187], v[122:125]
	v_mfma_f32_16x16x32_bf16 v[114:117], v[152:155], v[192:195], v[114:117]
	v_mfma_f32_16x16x32_bf16 v[106:109], v[160:163], v[192:195], v[106:109]
	v_mfma_f32_16x16x32_bf16 v[98:101], v[152:155], v[200:203], v[98:101]
	v_mfma_f32_16x16x32_bf16 v[90:93], v[160:163], v[200:203], v[90:93]
	v_mfma_f32_16x16x32_bf16 v[82:85], v[152:155], v[208:211], v[82:85]
	v_mfma_f32_16x16x32_bf16 v[74:77], v[160:163], v[208:211], v[74:77]
	s_setprio 0
	s_setprio 1
	v_mfma_f32_16x16x32_bf16 v[118:121], v[164:167], v[180:183], v[118:121]
	v_mfma_f32_16x16x32_bf16 v[110:113], v[172:175], v[180:183], v[110:113]
	v_mfma_f32_16x16x32_bf16 v[102:105], v[164:167], v[188:191], v[102:105]
	v_mfma_f32_16x16x32_bf16 v[94:97], v[172:175], v[188:191], v[94:97]
	v_mfma_f32_16x16x32_bf16 v[86:89], v[164:167], v[196:199], v[86:89]
	v_mfma_f32_16x16x32_bf16 v[78:81], v[172:175], v[196:199], v[78:81]
	v_mfma_f32_16x16x32_bf16 v[70:73], v[164:167], v[204:207], v[70:73]
	v_mfma_f32_16x16x32_bf16 v[66:69], v[172:175], v[204:207], v[66:69]
	v_mfma_f32_16x16x32_bf16 v[118:121], v[168:171], v[184:187], v[118:121]
	v_mfma_f32_16x16x32_bf16 v[110:113], v[176:179], v[184:187], v[110:113]
	v_mfma_f32_16x16x32_bf16 v[102:105], v[168:171], v[192:195], v[102:105]
	v_mfma_f32_16x16x32_bf16 v[94:97], v[176:179], v[192:195], v[94:97]
	v_mfma_f32_16x16x32_bf16 v[86:89], v[168:171], v[200:203], v[86:89]
	v_mfma_f32_16x16x32_bf16 v[78:81], v[176:179], v[200:203], v[78:81]
	v_mfma_f32_16x16x32_bf16 v[70:73], v[168:171], v[208:211], v[70:73]
	v_mfma_f32_16x16x32_bf16 v[66:69], v[176:179], v[208:211], v[66:69]
	s_setprio 0
	s_barrier
	s_mov_b32 m0, s34
	v_lshl_add_u64 v[212:213], s[16:17], 0, v[132:133]
	s_add_u32 s42, s16, 0x100000
	ds_read_b128 v[180:183], v145 offset:16384
	ds_read_b128 v[184:187], v145 offset:17408
	ds_read_b128 v[188:191], v145 offset:18432
	ds_read_b128 v[192:195], v145 offset:19456
	ds_read_b128 v[196:199], v145 offset:20480
	ds_read_b128 v[200:203], v145 offset:21504
	ds_read_b128 v[204:207], v145 offset:22528
	ds_read_b128 v[208:211], v145 offset:23552
	global_load_lds_dwordx4 v[212:213], off
	v_lshl_add_u64 v[214:215], s[16:17], 0, v[136:137]
	s_mov_b32 m0, s35
	s_addc_u32 s43, s17, 0
	global_load_lds_dwordx4 v[214:215], off
	v_lshl_add_u64 v[218:219], s[42:43], 0, v[132:133]
	s_mov_b32 m0, s36
	v_lshl_add_u64 v[220:221], s[18:19], 0, v[134:135]
	global_load_lds_dwordx4 v[218:219], off
	v_lshl_add_u64 v[218:219], s[42:43], 0, v[136:137]
	s_mov_b32 m0, s37
	s_nop 0
	global_load_lds_dwordx4 v[218:219], off
	v_lshl_add_u64 v[218:219], s[18:19], 0, v[130:131]
	s_waitcnt vmcnt(6)
	s_waitcnt lgkmcnt(0)
	s_barrier
; #define PG8_STAGE(bufoff, gbase, voff) do { _Pragma("unroll") for (int _i = 0; _i < 2; ++_i) \
;         __builtin_amdgcn_global_load_lds((const unsigned*)((const char*)(gbase) + (voff)[_i]), (PG8_LAS unsigned*)(lds + (bufoff) + ldsw + _i * 8192), 16, 0, 0); } while (0)
; #define PG8_LDA(dst, b, h) do { _Pragma("unroll") for (int m = 0; m < 4; ++m) _Pragma("unroll") for (int k = 0; k < 2; ++k) dst[m][k] = *(const PG8_LAS bf16x8*)(lds + PG8_SA(b, h) + aoff + m * 2048 + k * 1024); } while (0)
; #define PG8_LDB(dst, b, h) do { _Pragma("unroll") for (int n = 0; n < 2; ++n) _Pragma("unroll") for (int k = 0; k < 2; ++k) dst[n][k] = *(const PG8_LAS bf16x8*)(lds + PG8_SB(b, h) + boff + n * 2048 + k * 1024); } while (0)
; #define PG8_MMA(ai, bj, At, Bt) do { __builtin_amdgcn_s_setprio(1); _Pragma("unroll") for (int m = 0; m < 4; ++m) _Pragma("unroll") for (int n = 0; n < 2; ++n) _Pragma("unroll") for (int k = 0; k < 2; ++k) \
;         acc[ai][bj][m][n] = __builtin_amdgcn_mfma_f32_16x16x32_bf16(Bt[n][k], At[m][k], acc[ai][bj][m][n], 0, 0, 0); __builtin_amdgcn_s_setprio(0); } while (0)
; #define PG8_WAIT_V(n) asm volatile("s_waitcnt vmcnt(" #n ")" ::: "memory")
; #define PG8_WAIT_L(n) asm volatile("s_waitcnt lgkmcnt(" #n ")" ::: "memory")
; #define PG8_BAR __builtin_amdgcn_s_barrier()
; #define PG8_SCHED __builtin_amdgcn_sched_barrier(0)
; template <class Epi, class Sched, bool ALIGN_EPI = false, bool SP2 = false>
; __device__ __forceinline__ void gemm_phase(PG8_LAS unsigned char* lds, const Gemm g, const Sched& S, const Epi& E) {
;     ...
;             PG8_WAIT_V(8); PG8_WAIT_L(0); PG8_BAR; PG8_MMA(1, 0, At, B0); PG8_MMA(1, 1, At, B1); PG8_BAR; PG8_SCHED;
;             PG8_LDB(B0, 1, 0); PG8_LDB(B1, 1, 1); PG8_SCHED; PG8_LDA(At, 1, 0); PG8_STAGE(PG8_SA(0, 1), a2 + hstepA, voffA);
;             PG8_WAIT_V(8); PG8_WAIT_L(0); PG8_BAR; PG8_MMA(0, 0, At, B0); PG8_MMA(0, 1, At, B1); PG8_BAR; PG8_SCHED;
;             PG8_LDA(At, 1, 1); PG8_STAGE(PG8_SB(1, 0), b3, voffB); PG8_STAGE(PG8_SB(1, 1), b3 + hstepB, voffB); PG8_STAGE(PG8_SA(1, 0), a3, voffA);
	s_setprio 1
	s_waitcnt lgkmcnt(0)
	v_mfma_f32_16x16x32_bf16 v[62:65], v[148:151], v[180:183], v[62:65]
	v_mfma_f32_16x16x32_bf16 v[58:61], v[156:159], v[180:183], v[58:61]
	v_mfma_f32_16x16x32_bf16 v[50:53], v[148:151], v[188:191], v[50:53]
	v_mfma_f32_16x16x32_bf16 v[42:45], v[156:159], v[188:191], v[42:45]
	v_mfma_f32_16x16x32_bf16 v[34:37], v[148:151], v[196:199], v[34:37]
	v_mfma_f32_16x16x32_bf16 v[26:29], v[156:159], v[196:199], v[26:29]
	v_mfma_f32_16x16x32_bf16 v[18:21], v[148:151], v[204:207], v[18:21]
	v_mfma_f32_16x16x32_bf16 v[10:13], v[156:159], v[204:207], v[10:13]
	v_mfma_f32_16x16x32_bf16 v[62:65], v[152:155], v[184:187], v[62:65]
	v_mfma_f32_16x16x32_bf16 v[58:61], v[160:163], v[184:187], v[58:61]
	v_mfma_f32_16x16x32_bf16 v[50:53], v[152:155], v[192:195], v[50:53]
	v_mfma_f32_16x16x32_bf16 v[42:45], v[160:163], v[192:195], v[42:45]
	v_mfma_f32_16x16x32_bf16 v[34:37], v[152:155], v[200:203], v[34:37]
	v_mfma_f32_16x16x32_bf16 v[26:29], v[160:163], v[200:203], v[26:29]
	v_mfma_f32_16x16x32_bf16 v[18:21], v[152:155], v[208:211], v[18:21]
	v_mfma_f32_16x16x32_bf16 v[10:13], v[160:163], v[208:211], v[10:13]
	s_setprio 0
	s_setprio 1
	v_mfma_f32_16x16x32_bf16 v[54:57], v[164:167], v[180:183], v[54:57]
	v_mfma_f32_16x16x32_bf16 v[46:49], v[172:175], v[180:183], v[46:49]
	v_mfma_f32_16x16x32_bf16 v[38:41], v[164:167], v[188:191], v[38:41]
	v_mfma_f32_16x16x32_bf16 v[30:33], v[172:175], v[188:191], v[30:33]
	v_mfma_f32_16x16x32_bf16 v[22:25], v[164:167], v[196:199], v[22:25]
	v_mfma_f32_16x16x32_bf16 v[14:17], v[172:175], v[196:199], v[14:17]
	v_mfma_f32_16x16x32_bf16 v[6:9], v[164:167], v[204:207], v[6:9]
	v_mfma_f32_16x16x32_bf16 v[2:5], v[172:175], v[204:207], v[2:5]
	v_mfma_f32_16x16x32_bf16 v[54:57], v[168:171], v[184:187], v[54:57]
	v_mfma_f32_16x16x32_bf16 v[46:49], v[176:179], v[184:187], v[46:49]
	v_mfma_f32_16x16x32_bf16 v[38:41], v[168:171], v[192:195], v[38:41]
	v_mfma_f32_16x16x32_bf16 v[30:33], v[176:179], v[192:195], v[30:33]
	v_mfma_f32_16x16x32_bf16 v[22:25], v[168:171], v[200:203], v[22:25]
	v_mfma_f32_16x16x32_bf16 v[14:17], v[176:179], v[200:203], v[14:17]
	v_mfma_f32_16x16x32_bf16 v[6:9], v[168:171], v[208:211], v[6:9]
	v_mfma_f32_16x16x32_bf16 v[2:5], v[176:179], v[208:211], v[2:5]
	s_setprio 0
	s_barrier
	s_mov_b32 m0, s3
	s_nop 0
	global_load_lds_dwordx4 v[218:219], off
	s_mov_b32 m0, s22
	s_nop 0
	global_load_lds_dwordx4 v[220:221], off
	ds_read_b128 v[148:151], v146
	ds_read_b128 v[152:155], v146 offset:1024
	ds_read_b128 v[156:159], v146 offset:2048
	ds_read_b128 v[160:163], v146 offset:3072
	ds_read_b128 v[164:167], v147
	ds_read_b128 v[168:171], v147 offset:1024
	ds_read_b128 v[172:175], v147 offset:2048
	ds_read_b128 v[176:179], v147 offset:3072
	s_add_u32 s18, s18, 0x100000
	s_addc_u32 s19, s19, 0
	s_mov_b32 m0, s23
	v_lshl_add_u64 v[222:223], s[18:19], 0, v[130:131]
	ds_read_b128 v[180:183], v145 offset:32768
	ds_read_b128 v[184:187], v145 offset:33792
	ds_read_b128 v[188:191], v145 offset:34816
	ds_read_b128 v[192:195], v145 offset:35840
	ds_read_b128 v[196:199], v145 offset:36864
	ds_read_b128 v[200:203], v145 offset:37888
	ds_read_b128 v[204:207], v145 offset:38912
	ds_read_b128 v[208:211], v145 offset:39936
	global_load_lds_dwordx4 v[222:223], off
	v_lshl_add_u64 v[222:223], s[18:19], 0, v[134:135]
	s_mov_b32 m0, s24
	s_nop 0
	global_load_lds_dwordx4 v[222:223], off
	s_waitcnt vmcnt(8)
	s_waitcnt lgkmcnt(0)
	s_barrier
	s_setprio 1
	s_waitcnt lgkmcnt(0)
	v_mfma_f32_16x16x32_bf16 v[126:129], v[148:151], v[180:183], v[126:129]
	v_mfma_f32_16x16x32_bf16 v[122:125], v[156:159], v[180:183], v[122:125]
	v_mfma_f32_16x16x32_bf16 v[114:117], v[148:151], v[188:191], v[114:117]
	v_mfma_f32_16x16x32_bf16 v[106:109], v[156:159], v[188:191], v[106:109]
	v_mfma_f32_16x16x32_bf16 v[98:101], v[148:151], v[196:199], v[98:101]
	v_mfma_f32_16x16x32_bf16 v[90:93], v[156:159], v[196:199], v[90:93]
	v_mfma_f32_16x16x32_bf16 v[82:85], v[148:151], v[204:207], v[82:85]
	v_mfma_f32_16x16x32_bf16 v[74:77], v[156:159], v[204:207], v[74:77]
	v_mfma_f32_16x16x32_bf16 v[126:129], v[152:155], v[184:187], v[126:129]
	v_mfma_f32_16x16x32_bf16 v[122:125], v[160:163], v[184:187], v[122:125]
	v_mfma_f32_16x16x32_bf16 v[114:117], v[152:155], v[192:195], v[114:117]
	v_mfma_f32_16x16x32_bf16 v[106:109], v[160:163], v[192:195], v[106:109]
	v_mfma_f32_16x16x32_bf16 v[98:101], v[152:155], v[200:203], v[98:101]
	v_mfma_f32_16x16x32_bf16 v[90:93], v[160:163], v[200:203], v[90:93]
	v_mfma_f32_16x16x32_bf16 v[82:85], v[152:155], v[208:211], v[82:85]
	v_mfma_f32_16x16x32_bf16 v[74:77], v[160:163], v[208:211], v[74:77]
	s_setprio 0
	s_setprio 1
	v_mfma_f32_16x16x32_bf16 v[118:121], v[164:167], v[180:183], v[118:121]
	v_mfma_f32_16x16x32_bf16 v[110:113], v[172:175], v[180:183], v[110:113]
	v_mfma_f32_16x16x32_bf16 v[102:105], v[164:167], v[188:191], v[102:105]
	v_mfma_f32_16x16x32_bf16 v[94:97], v[172:175], v[188:191], v[94:97]
	v_mfma_f32_16x16x32_bf16 v[86:89], v[164:167], v[196:199], v[86:89]
	v_mfma_f32_16x16x32_bf16 v[78:81], v[172:175], v[196:199], v[78:81]
	v_mfma_f32_16x16x32_bf16 v[70:73], v[164:167], v[204:207], v[70:73]
	v_mfma_f32_16x16x32_bf16 v[66:69], v[172:175], v[204:207], v[66:69]
	v_mfma_f32_16x16x32_bf16 v[118:121], v[168:171], v[184:187], v[118:121]
	v_mfma_f32_16x16x32_bf16 v[110:113], v[176:179], v[184:187], v[110:113]
	v_mfma_f32_16x16x32_bf16 v[102:105], v[168:171], v[192:195], v[102:105]
	v_mfma_f32_16x16x32_bf16 v[94:97], v[176:179], v[192:195], v[94:97]
	v_mfma_f32_16x16x32_bf16 v[86:89], v[168:171], v[200:203], v[86:89]
	v_mfma_f32_16x16x32_bf16 v[78:81], v[176:179], v[200:203], v[78:81]
	v_mfma_f32_16x16x32_bf16 v[70:73], v[168:171], v[208:211], v[70:73]
	v_mfma_f32_16x16x32_bf16 v[66:69], v[176:179], v[208:211], v[66:69]
	s_setprio 0
	s_barrier
; #define PG8_STAGE(bufoff, gbase, voff) do { _Pragma("unroll") for (int _i = 0; _i < 2; ++_i) \
;         __builtin_amdgcn_global_load_lds((const unsigned*)((const char*)(gbase) + (voff)[_i]), (PG8_LAS unsigned*)(lds + (bufoff) + ldsw + _i * 8192), 16, 0, 0); } while (0)
; #define PG8_LDA(dst, b, h) do { _Pragma("unroll") for (int m = 0; m < 4; ++m) _Pragma("unroll") for (int k = 0; k < 2; ++k) dst[m][k] = *(const PG8_LAS bf16x8*)(lds + PG8_SA(b, h) + aoff + m * 2048 + k * 1024); } while (0)
; #define PG8_MMA(ai, bj, At, Bt) do { __builtin_amdgcn_s_setprio(1); _Pragma("unroll") for (int m = 0; m < 4; ++m) _Pragma("unroll") for (int n = 0; n < 2; ++n) _Pragma("unroll") for (int k = 0; k < 2; ++k) \
;         acc[ai][bj][m][n] = __builtin_amdgcn_mfma_f32_16x16x32_bf16(Bt[n][k], At[m][k], acc[ai][bj][m][n], 0, 0, 0); __builtin_amdgcn_s_setprio(0); } while (0)
; #define PG8_WAIT_V(n) asm volatile("s_waitcnt vmcnt(" #n ")" ::: "memory")
; #define PG8_WAIT_L(n) asm volatile("s_waitcnt lgkmcnt(" #n ")" ::: "memory")
; #define PG8_BAR __builtin_amdgcn_s_barrier()
; #define PG8_SCHED __builtin_amdgcn_sched_barrier(0)
; template <class Epi, class Sched, bool ALIGN_EPI = false, bool SP2 = false>
; __device__ __forceinline__ void gemm_phase(PG8_LAS unsigned char* lds, const Gemm g, const Sched& S, const Epi& E) {
;     ...
;             PG8_LDA(At, 1, 1); PG8_STAGE(PG8_SB(1, 0), b3, voffB); PG8_STAGE(PG8_SB(1, 1), b3 + hstepB, voffB); PG8_STAGE(PG8_SA(1, 0), a3, voffA);
;             PG8_WAIT_V(8); PG8_WAIT_L(0); PG8_BAR; PG8_MMA(1, 0, At, B0); PG8_MMA(1, 1, At, B1); PG8_BAR; PG8_SCHED;
	s_mov_b32 m0, s38
	v_lshl_add_u64 v[212:213], v[212:213], 0, s[10:11]
	s_add_u32 s16, s16, 0x100080
	ds_read_b128 v[180:183], v145 offset:49152
	ds_read_b128 v[184:187], v145 offset:50176
	ds_read_b128 v[188:191], v145 offset:51200
	ds_read_b128 v[192:195], v145 offset:52224
	ds_read_b128 v[196:199], v145 offset:53248
	ds_read_b128 v[200:203], v145 offset:54272
	ds_read_b128 v[204:207], v145 offset:55296
	ds_read_b128 v[208:211], v145 offset:56320
	global_load_lds_dwordx4 v[212:213], off
	v_lshl_add_u64 v[212:213], v[214:215], 0, s[10:11]
	s_mov_b32 m0, s39
	s_addc_u32 s17, s17, 0
	global_load_lds_dwordx4 v[212:213], off
	v_lshl_add_u64 v[212:213], s[16:17], 0, v[132:133]
	s_mov_b32 m0, s40
	s_nop 0
	global_load_lds_dwordx4 v[212:213], off
	v_lshl_add_u64 v[212:213], s[16:17], 0, v[136:137]
	s_mov_b32 m0, s41
	s_nop 0
	global_load_lds_dwordx4 v[212:213], off
	s_waitcnt vmcnt(6)
	s_waitcnt lgkmcnt(0)
	s_barrier
	s_setprio 1
	s_waitcnt lgkmcnt(0)
	v_mfma_f32_16x16x32_bf16 v[62:65], v[148:151], v[180:183], v[62:65]
	v_mfma_f32_16x16x32_bf16 v[58:61], v[156:159], v[180:183], v[58:61]
	v_mfma_f32_16x16x32_bf16 v[50:53], v[148:151], v[188:191], v[50:53]
	v_mfma_f32_16x16x32_bf16 v[42:45], v[156:159], v[188:191], v[42:45]
	v_mfma_f32_16x16x32_bf16 v[34:37], v[148:151], v[196:199], v[34:37]
	v_mfma_f32_16x16x32_bf16 v[26:29], v[156:159], v[196:199], v[26:29]
	v_mfma_f32_16x16x32_bf16 v[18:21], v[148:151], v[204:207], v[18:21]
	v_mfma_f32_16x16x32_bf16 v[10:13], v[156:159], v[204:207], v[10:13]
	v_mfma_f32_16x16x32_bf16 v[62:65], v[152:155], v[184:187], v[62:65]
	v_mfma_f32_16x16x32_bf16 v[58:61], v[160:163], v[184:187], v[58:61]
	v_mfma_f32_16x16x32_bf16 v[50:53], v[152:155], v[192:195], v[50:53]
	v_mfma_f32_16x16x32_bf16 v[42:45], v[160:163], v[192:195], v[42:45]
	v_mfma_f32_16x16x32_bf16 v[34:37], v[152:155], v[200:203], v[34:37]
	v_mfma_f32_16x16x32_bf16 v[26:29], v[160:163], v[200:203], v[26:29]
	v_mfma_f32_16x16x32_bf16 v[18:21], v[152:155], v[208:211], v[18:21]
	v_mfma_f32_16x16x32_bf16 v[10:13], v[160:163], v[208:211], v[10:13]
	s_setprio 0
	s_setprio 1
	v_mfma_f32_16x16x32_bf16 v[54:57], v[164:167], v[180:183], v[54:57]
	v_mfma_f32_16x16x32_bf16 v[46:49], v[172:175], v[180:183], v[46:49]
	v_mfma_f32_16x16x32_bf16 v[38:41], v[164:167], v[188:191], v[38:41]
	v_mfma_f32_16x16x32_bf16 v[30:33], v[172:175], v[188:191], v[30:33]
	v_mfma_f32_16x16x32_bf16 v[22:25], v[164:167], v[196:199], v[22:25]
	v_mfma_f32_16x16x32_bf16 v[14:17], v[172:175], v[196:199], v[14:17]
	v_mfma_f32_16x16x32_bf16 v[6:9], v[164:167], v[204:207], v[6:9]
	v_mfma_f32_16x16x32_bf16 v[2:5], v[172:175], v[204:207], v[2:5]
	v_mfma_f32_16x16x32_bf16 v[54:57], v[168:171], v[184:187], v[54:57]
	v_mfma_f32_16x16x32_bf16 v[46:49], v[176:179], v[184:187], v[46:49]
	v_mfma_f32_16x16x32_bf16 v[38:41], v[168:171], v[192:195], v[38:41]
	v_mfma_f32_16x16x32_bf16 v[30:33], v[176:179], v[192:195], v[30:33]
	v_mfma_f32_16x16x32_bf16 v[22:25], v[168:171], v[200:203], v[22:25]
	v_mfma_f32_16x16x32_bf16 v[14:17], v[176:179], v[200:203], v[14:17]
	v_mfma_f32_16x16x32_bf16 v[6:9], v[168:171], v[208:211], v[6:9]
	v_mfma_f32_16x16x32_bf16 v[2:5], v[176:179], v[208:211], v[2:5]
	s_setprio 0
	s_barrier
	v_lshl_add_u64 v[212:213], v[218:219], 0, s[10:11]
	s_mov_b32 m0, s26
	s_nop 0
	global_load_lds_dwordx4 v[212:213], off
	v_lshl_add_u64 v[212:213], v[220:221], 0, s[10:11]
	s_mov_b32 m0, s27
	s_nop 0
	global_load_lds_dwordx4 v[212:213], off
	s_add_i32 s30, s30, 2
	s_add_u32 s14, s14, 0x100
	s_addc_u32 s15, s15, 0
	s_cmp_gt_u32 s30, 61
	s_cbranch_scc0 .LBB0_1880
	s_cmpk_lt_u32 s20, 0x100
	s_cbranch_scc0 .LBB0_1883
	s_barrier
